# residual epilogue of the N=1024 GEMMs: one memory round trip (first 8 H loads prefetched at tile start into unused v220-v251, remaining 24 issued together, counted vmcnt waits)
# speedup vs baseline: 1.0539x; 1.0005x over previous
;     DI bool next(int i, Unit& u) const {
;         const long L = (long)i * G + c; if (L >= nwg) return false;
;         int wgid = (int)L; { const int q = nwg / NXCD, r = nwg % NXCD, xcd = wgid % NXCD, off = wgid / NXCD; wgid = (xcd < r ? xcd * (q + 1) : r * (q + 1) + (xcd - r) * q) + off; }
;         const int nig = WGM * nN, gid = wgid / nig, fm = gid * WGM, gsz = (nM - fm) < WGM ? (nM - fm) : WGM;
;         u.pm = fm + ((wgid % nig) % gsz); u.pn = (wgid % nig) / gsz; return true;
;     }
;     DI void operator()(const AccT& acc, const Unit& u, int wr, int wc, int fr, int fq) const {
; #pragma unroll
;         for (int ai = 0; ai < 2; ++ai) {
;             f32x4 h[4][2][2];
;             float* base = H + ((size_t)u.pm * 256 + ai * 128 + wr * 64 + fr) * 1024 + u.pn * 256 + wc * 32 + 4 * fq;
; #pragma unroll
;             for (int m = 0; m < 4; ++m)
; #pragma unroll
;                 for (int bj = 0; bj < 2; ++bj)
; #pragma unroll
;                     for (int n = 0; n < 2; ++n) h[m][bj][n] = *(const f32x4*)(base + (size_t)m * 16 * 1024 + bj * 128 + n * 16);
.LBB0_166:
	s_mov_b32 s98, s16
	s_ashr_i32 s99, s16, 31
	s_lshl_b64 s[98:99], s[98:99], 20
	s_lshl_b32 s100, s65, 8
	s_ashr_i32 s101, s100, 31
	v_lshl_add_u64 v[252:253], v[134:135], 0, s[98:99]
	v_lshl_add_u64 v[252:253], s[100:101], 2, v[252:253]
	v_lshl_add_u64 v[252:253], v[252:253], 0, s[10:11]
	v_lshl_add_u64 v[252:253], v[252:253], 0, v[132:133]
	global_load_dwordx4 v[220:223], v[252:253], off
	global_load_dwordx4 v[224:227], v[252:253], off offset:64
	global_load_dwordx4 v[228:231], v[252:253], off offset:512
	global_load_dwordx4 v[232:235], v[252:253], off offset:576
	s_mov_b32 s100, 0x10000
	s_mov_b32 s101, 0
	v_lshl_add_u64 v[252:253], v[252:253], 0, s[100:101]
	global_load_dwordx4 v[236:239], v[252:253], off
	global_load_dwordx4 v[240:243], v[252:253], off offset:64
	global_load_dwordx4 v[244:247], v[252:253], off offset:512
	global_load_dwordx4 v[248:251], v[252:253], off offset:576
	s_mov_b32 s100, 0xffff0000
	s_mov_b32 s101, -1
	v_lshl_add_u64 v[252:253], v[252:253], 0, s[100:101]
	s_add_i32 s62, s62, 1
	s_mul_i32 s4, s62, s45
	s_mul_hi_u32 s5, s62, s44
	s_add_i32 s5, s5, s4
	s_mul_i32 s4, s62, s44
	s_add_u32 s8, s4, s2
	s_addc_u32 s9, s5, s3
	v_cmp_gt_i64_e64 s[4:5], s[8:9], v[142:143]
	v_cmp_lt_i64_e64 s[6:7], s[8:9], v[140:141]
	s_and_b64 vcc, exec, s[4:5]
	s_cbranch_vccnz .LBB0_172
	s_ashr_i32 s9, s8, 31
	s_lshr_b32 s9, s9, 29
	s_add_i32 s17, s8, s9
	s_and_b32 s9, s17, -8
	s_sub_i32 s28, s8, s9
	s_cmp_gt_i32 s28, 3
	s_mov_b64 s[8:9], -1
	s_cbranch_scc0 .LBB0_169
	s_mul_i32 s8, s28, 0xa1
	s_add_i32 s29, s8, 4
	s_mov_b64 s[8:9], 0

; #define PG8_STAGE(bufoff, gbase, voff) do { _Pragma("unroll") for (int _i = 0; _i < 2; ++_i) \
;         __builtin_amdgcn_global_load_lds((const unsigned*)((const char*)(gbase) + (voff)[_i]), (LAS unsigned*)(lds + (bufoff) + ldsw + _i * 8192), 16, 0, 0); } while (0)
; #define PG8_LDA(dst, b, h) do { _Pragma("unroll") for (int m = 0; m < 4; ++m) _Pragma("unroll") for (int k = 0; k < 2; ++k) dst[m][k] = *(const LAS bf16x8*)(lds + PG8_SA(b, h) + aoff + m * 2048 + k * 1024); } while (0)
; #define PG8_LDB(dst, b, h) do { _Pragma("unroll") for (int n = 0; n < 2; ++n) _Pragma("unroll") for (int k = 0; k < 2; ++k) dst[n][k] = *(const LAS bf16x8*)(lds + PG8_SB(b, h) + boff + n * 2048 + k * 1024); } while (0)
; #define PG8_MMA(ai, bj, At, Bt) do { __builtin_amdgcn_s_setprio(1); _Pragma("unroll") for (int m = 0; m < 4; ++m) _Pragma("unroll") for (int n = 0; n < 2; ++n) _Pragma("unroll") for (int k = 0; k < 2; ++k) \
;         acc[ai][bj][m][n] = __builtin_amdgcn_mfma_f32_16x16x32_bf16(Bt[n][k], At[m][k], acc[ai][bj][m][n], 0, 0, 0); __builtin_amdgcn_s_setprio(0); } while (0)
; #define PG8_WAIT_V(n) asm volatile("s_waitcnt vmcnt(" #n ")" ::: "memory")
; #define PG8_WAIT_L(n) asm volatile("s_waitcnt lgkmcnt(" #n ")" ::: "memory")
; #define PG8_BAR __builtin_amdgcn_s_barrier()
; #define PG8_SCHED __builtin_amdgcn_sched_barrier(0)
; template <class Epi>
; DI void gemm_phase(int wv, LAS unsigned char* lds, const Gemm g, const StaticOrder& S, const Epi& E) {
;     ...
;             PG8_LDB(B0, 0, 0); PG8_SCHED; PG8_LDA(At, 0, 0); PG8_STAGE(PG8_SA(1, 1), a1 + hstep, voffA);
;             PG8_WAIT_L(8); PG8_BAR; PG8_WAIT_L(0); PG8_MMA(0, 0, At, B0); PG8_BAR; PG8_SCHED;
;             PG8_LDB(B1, 0, 1); PG8_STAGE(PG8_SB(0, 0), b2, voffB);
;             PG8_BAR; PG8_WAIT_L(0); PG8_MMA(0, 1, At, B1); PG8_BAR;
;             PG8_LDA(At, 0, 1); PG8_STAGE(PG8_SA(0, 0), a2, voffA);
;             PG8_BAR; PG8_WAIT_L(0); PG8_MMA(1, 0, At, B0); PG8_BAR; PG8_SCHED;
;             PG8_STAGE(PG8_SB(0, 1), b2 + hstep, voffB);
;             PG8_WAIT_V(6); PG8_BAR; PG8_MMA(1, 1, At, B1); PG8_BAR;
;             PG8_LDB(B0, 1, 0); PG8_SCHED; PG8_LDA(At, 1, 0); PG8_STAGE(PG8_SA(0, 1), a2 + hstep, voffA);
;             PG8_WAIT_L(8); PG8_BAR; PG8_WAIT_L(0); PG8_MMA(0, 0, At, B0); PG8_BAR; PG8_SCHED;
.LBB0_177:
	ds_read_b128 v[150:153], v147
	ds_read_b128 v[154:157], v147 offset:1024
	ds_read_b128 v[158:161], v147 offset:2048
	ds_read_b128 v[162:165], v147 offset:3072
	s_add_u32 s20, s18, 0x100
	s_addc_u32 s21, s19, 0
	s_cmp_eq_u32 s67, 40
	s_cselect_b32 s31, s7, s21
	s_cselect_b32 s30, s6, s20
	s_cselect_b32 s29, s9, s66
	s_cselect_b32 s28, s8, s17
	v_lshl_add_u64 v[144:145], s[18:19], 0, v[136:137]
	s_add_i32 m0, s41, 0xc000
	ds_read_b128 v[166:169], v148
	ds_read_b128 v[170:173], v148 offset:1024
	ds_read_b128 v[174:177], v148 offset:2048
	ds_read_b128 v[178:181], v148 offset:3072
	ds_read_b128 v[182:185], v148 offset:4096
	ds_read_b128 v[186:189], v148 offset:5120
	ds_read_b128 v[190:193], v148 offset:6144
	ds_read_b128 v[194:197], v148 offset:7168
	global_load_lds_dwordx4 v[144:145], off
	v_lshl_add_u64 v[144:145], s[18:19], 0, v[138:139]
	s_add_i32 m0, s41, 0xe000
	s_nop 0
	global_load_lds_dwordx4 v[144:145], off
	s_waitcnt lgkmcnt(8)
	s_barrier
	s_waitcnt lgkmcnt(0)
	s_setprio 1
	s_waitcnt lgkmcnt(0)
	v_mfma_f32_16x16x32_bf16 v[124:127], v[150:153], v[166:169], v[124:127]
	v_mfma_f32_16x16x32_bf16 v[120:123], v[158:161], v[166:169], v[120:123]
	v_mfma_f32_16x16x32_bf16 v[116:119], v[150:153], v[174:177], v[116:119]
	v_mfma_f32_16x16x32_bf16 v[112:115], v[158:161], v[174:177], v[112:115]
	v_mfma_f32_16x16x32_bf16 v[104:107], v[150:153], v[182:185], v[104:107]
	v_mfma_f32_16x16x32_bf16 v[96:99], v[158:161], v[182:185], v[96:99]
	v_mfma_f32_16x16x32_bf16 v[88:91], v[150:153], v[190:193], v[88:91]
	v_mfma_f32_16x16x32_bf16 v[80:83], v[158:161], v[190:193], v[80:83]
	v_mfma_f32_16x16x32_bf16 v[124:127], v[154:157], v[170:173], v[124:127]
	v_mfma_f32_16x16x32_bf16 v[120:123], v[162:165], v[170:173], v[120:123]
	v_mfma_f32_16x16x32_bf16 v[116:119], v[154:157], v[178:181], v[116:119]
	v_mfma_f32_16x16x32_bf16 v[112:115], v[162:165], v[178:181], v[112:115]
	v_mfma_f32_16x16x32_bf16 v[104:107], v[154:157], v[186:189], v[104:107]
	v_mfma_f32_16x16x32_bf16 v[96:99], v[162:165], v[186:189], v[96:99]
	v_mfma_f32_16x16x32_bf16 v[88:91], v[154:157], v[194:197], v[88:91]
	v_mfma_f32_16x16x32_bf16 v[80:83], v[162:165], v[194:197], v[80:83]
	s_setprio 0
	s_barrier
	s_add_i32 s18, s52, s39
	v_lshl_add_u64 v[144:145], s[28:29], 0, v[128:129]
	s_mov_b32 m0, s18
	ds_read_b128 v[202:205], v149
	ds_read_b128 v[206:209], v149 offset:1024
	ds_read_b128 v[210:213], v149 offset:2048
	ds_read_b128 v[214:217], v149 offset:3072
	global_load_lds_dwordx4 v[144:145], off
	v_lshl_add_u64 v[198:199], s[28:29], 0, v[130:131]
	s_add_i32 m0, s18, 0x2000
	s_nop 0
	global_load_lds_dwordx4 v[198:199], off
	s_barrier
	s_waitcnt lgkmcnt(0)
	s_setprio 1
	s_waitcnt lgkmcnt(0)
	v_mfma_f32_16x16x32_bf16 v[108:111], v[202:205], v[166:169], v[108:111]
	v_mfma_f32_16x16x32_bf16 v[100:103], v[210:213], v[166:169], v[100:103]
	v_mfma_f32_16x16x32_bf16 v[92:95], v[202:205], v[174:177], v[92:95]
	v_mfma_f32_16x16x32_bf16 v[84:87], v[210:213], v[174:177], v[84:87]
	v_mfma_f32_16x16x32_bf16 v[76:79], v[202:205], v[182:185], v[76:79]
	v_mfma_f32_16x16x32_bf16 v[72:75], v[210:213], v[182:185], v[72:75]
	v_mfma_f32_16x16x32_bf16 v[68:71], v[202:205], v[190:193], v[68:71]
	v_mfma_f32_16x16x32_bf16 v[64:67], v[210:213], v[190:193], v[64:67]
	v_mfma_f32_16x16x32_bf16 v[108:111], v[206:209], v[170:173], v[108:111]
	v_mfma_f32_16x16x32_bf16 v[100:103], v[214:217], v[170:173], v[100:103]
	v_mfma_f32_16x16x32_bf16 v[92:95], v[206:209], v[178:181], v[92:95]
	v_mfma_f32_16x16x32_bf16 v[84:87], v[214:217], v[178:181], v[84:87]
	v_mfma_f32_16x16x32_bf16 v[76:79], v[206:209], v[186:189], v[76:79]
	v_mfma_f32_16x16x32_bf16 v[72:75], v[214:217], v[186:189], v[72:75]
	v_mfma_f32_16x16x32_bf16 v[68:71], v[206:209], v[194:197], v[68:71]
	v_mfma_f32_16x16x32_bf16 v[64:67], v[214:217], v[194:197], v[64:67]
	s_setprio 0
	s_mov_b32 m0, s41
	v_lshl_add_u64 v[200:201], s[30:31], 0, v[128:129]
	s_barrier
	ds_read_b128 v[166:169], v148 offset:16384
	ds_read_b128 v[170:173], v148 offset:17408
	ds_read_b128 v[174:177], v148 offset:18432
	ds_read_b128 v[178:181], v148 offset:19456
	ds_read_b128 v[182:185], v148 offset:20480
	ds_read_b128 v[186:189], v148 offset:21504
	ds_read_b128 v[190:193], v148 offset:22528
	ds_read_b128 v[194:197], v148 offset:23552
	global_load_lds_dwordx4 v[200:201], off
	v_lshl_add_u64 v[218:219], s[30:31], 0, v[130:131]
	s_mov_b32 m0, s46
	s_nop 0
	global_load_lds_dwordx4 v[218:219], off
	s_barrier
	s_waitcnt lgkmcnt(0)
	s_setprio 1
	s_waitcnt lgkmcnt(0)
	v_mfma_f32_16x16x32_bf16 v[60:63], v[150:153], v[166:169], v[60:63]
	v_mfma_f32_16x16x32_bf16 v[56:59], v[158:161], v[166:169], v[56:59]
	v_mfma_f32_16x16x32_bf16 v[52:55], v[150:153], v[174:177], v[52:55]
	v_mfma_f32_16x16x32_bf16 v[44:47], v[158:161], v[174:177], v[44:47]
	v_mfma_f32_16x16x32_bf16 v[36:39], v[150:153], v[182:185], v[36:39]
	v_mfma_f32_16x16x32_bf16 v[28:31], v[158:161], v[182:185], v[28:31]
	v_mfma_f32_16x16x32_bf16 v[20:23], v[150:153], v[190:193], v[20:23]
	v_mfma_f32_16x16x32_bf16 v[12:15], v[158:161], v[190:193], v[12:15]
	v_mfma_f32_16x16x32_bf16 v[60:63], v[154:157], v[170:173], v[60:63]
	v_mfma_f32_16x16x32_bf16 v[56:59], v[162:165], v[170:173], v[56:59]
	v_mfma_f32_16x16x32_bf16 v[52:55], v[154:157], v[178:181], v[52:55]
	v_mfma_f32_16x16x32_bf16 v[44:47], v[162:165], v[178:181], v[44:47]
	v_mfma_f32_16x16x32_bf16 v[36:39], v[154:157], v[186:189], v[36:39]
	v_mfma_f32_16x16x32_bf16 v[28:31], v[162:165], v[186:189], v[28:31]
	v_mfma_f32_16x16x32_bf16 v[20:23], v[154:157], v[194:197], v[20:23]
	v_mfma_f32_16x16x32_bf16 v[12:15], v[162:165], v[194:197], v[12:15]
	s_setprio 0
	s_barrier
; #define PG8_STAGE(bufoff, gbase, voff) do { _Pragma("unroll") for (int _i = 0; _i < 2; ++_i) \
;         __builtin_amdgcn_global_load_lds((const unsigned*)((const char*)(gbase) + (voff)[_i]), (LAS unsigned*)(lds + (bufoff) + ldsw + _i * 8192), 16, 0, 0); } while (0)
; #define PG8_LDA(dst, b, h) do { _Pragma("unroll") for (int m = 0; m < 4; ++m) _Pragma("unroll") for (int k = 0; k < 2; ++k) dst[m][k] = *(const LAS bf16x8*)(lds + PG8_SA(b, h) + aoff + m * 2048 + k * 1024); } while (0)
; #define PG8_LDB(dst, b, h) do { _Pragma("unroll") for (int n = 0; n < 2; ++n) _Pragma("unroll") for (int k = 0; k < 2; ++k) dst[n][k] = *(const LAS bf16x8*)(lds + PG8_SB(b, h) + boff + n * 2048 + k * 1024); } while (0)
; #define PG8_MMA(ai, bj, At, Bt) do { __builtin_amdgcn_s_setprio(1); _Pragma("unroll") for (int m = 0; m < 4; ++m) _Pragma("unroll") for (int n = 0; n < 2; ++n) _Pragma("unroll") for (int k = 0; k < 2; ++k) \
;         acc[ai][bj][m][n] = __builtin_amdgcn_mfma_f32_16x16x32_bf16(Bt[n][k], At[m][k], acc[ai][bj][m][n], 0, 0, 0); __builtin_amdgcn_s_setprio(0); } while (0)
; #define PG8_WAIT_V(n) asm volatile("s_waitcnt vmcnt(" #n ")" ::: "memory")
; #define PG8_WAIT_L(n) asm volatile("s_waitcnt lgkmcnt(" #n ")" ::: "memory")
; #define PG8_BAR __builtin_amdgcn_s_barrier()
; #define PG8_SCHED __builtin_amdgcn_sched_barrier(0)
; template <class Epi>
; DI void gemm_phase(int wv, LAS unsigned char* lds, const Gemm g, const StaticOrder& S, const Epi& E) {
;     ...
;             PG8_LDB(B1, 1, 1); PG8_STAGE(PG8_SB(1, 0), b3, voffB);
;             PG8_BAR; PG8_WAIT_L(0); PG8_MMA(0, 1, At, B1); PG8_BAR;
;             PG8_LDA(At, 1, 1); PG8_STAGE(PG8_SA(1, 0), a3, voffA);
;             PG8_BAR; PG8_WAIT_L(0); PG8_MMA(1, 0, At, B0); PG8_BAR; PG8_SCHED;
;             PG8_STAGE(PG8_SB(1, 1), b3 + hstep, voffB);
;             PG8_WAIT_V(6); PG8_BAR; PG8_MMA(1, 1, At, B1); PG8_BAR;
	s_add_u32 s18, s28, 0xb0000
	s_addc_u32 s19, s29, 0
	s_add_i32 s68, s53, s39
	v_lshl_add_u64 v[150:151], s[18:19], 0, v[128:129]
	s_mov_b32 m0, s68
	s_nop 0
	global_load_lds_dwordx4 v[150:151], off
	v_lshl_add_u64 v[150:151], s[18:19], 0, v[130:131]
	s_add_i32 m0, s68, 0x2000
	s_nop 0
	global_load_lds_dwordx4 v[150:151], off
	s_waitcnt vmcnt(6)
	s_barrier
	s_setprio 1
	v_mfma_f32_16x16x32_bf16 v[48:51], v[202:205], v[166:169], v[48:51]
	v_mfma_f32_16x16x32_bf16 v[40:43], v[210:213], v[166:169], v[40:43]
	v_mfma_f32_16x16x32_bf16 v[32:35], v[202:205], v[174:177], v[32:35]
	v_mfma_f32_16x16x32_bf16 v[24:27], v[210:213], v[174:177], v[24:27]
	v_mfma_f32_16x16x32_bf16 v[16:19], v[202:205], v[182:185], v[16:19]
	v_mfma_f32_16x16x32_bf16 v[8:11], v[210:213], v[182:185], v[8:11]
	v_mfma_f32_16x16x32_bf16 v[4:7], v[202:205], v[190:193], v[4:7]
	v_mfma_f32_16x16x32_bf16 v[0:3], v[210:213], v[190:193], v[0:3]
	v_mfma_f32_16x16x32_bf16 v[48:51], v[206:209], v[170:173], v[48:51]
	v_mfma_f32_16x16x32_bf16 v[40:43], v[214:217], v[170:173], v[40:43]
	v_mfma_f32_16x16x32_bf16 v[32:35], v[206:209], v[178:181], v[32:35]
	v_mfma_f32_16x16x32_bf16 v[24:27], v[214:217], v[178:181], v[24:27]
	v_mfma_f32_16x16x32_bf16 v[16:19], v[206:209], v[186:189], v[16:19]
	v_mfma_f32_16x16x32_bf16 v[8:11], v[214:217], v[186:189], v[8:11]
	v_mfma_f32_16x16x32_bf16 v[4:7], v[206:209], v[194:197], v[4:7]
	v_mfma_f32_16x16x32_bf16 v[0:3], v[214:217], v[194:197], v[0:3]
	s_setprio 0
	s_add_i32 s68, 0, 0x18000
	v_add_u32_e32 v162, s68, v146
	s_barrier
	ds_read_b128 v[150:153], v162
	ds_read_b128 v[154:157], v162 offset:1024
	ds_read_b128 v[158:161], v162 offset:2048
	ds_read_b128 v[162:165], v162 offset:3072
	s_add_u32 s18, s30, 0xb0000
	s_addc_u32 s19, s31, 0
	s_mov_b32 m0, s47
	v_lshl_add_u64 v[202:203], s[18:19], 0, v[128:129]
	ds_read_b128 v[166:169], v148 offset:32768
	ds_read_b128 v[170:173], v148 offset:33792
	ds_read_b128 v[174:177], v148 offset:34816
	ds_read_b128 v[178:181], v148 offset:35840
	ds_read_b128 v[182:185], v148 offset:36864
	ds_read_b128 v[186:189], v148 offset:37888
	ds_read_b128 v[190:193], v148 offset:38912
	ds_read_b128 v[194:197], v148 offset:39936
	global_load_lds_dwordx4 v[202:203], off
	v_lshl_add_u64 v[202:203], s[18:19], 0, v[130:131]
	s_mov_b32 m0, s48
	s_nop 0
	global_load_lds_dwordx4 v[202:203], off
	s_waitcnt lgkmcnt(8)
	s_barrier
	s_waitcnt lgkmcnt(0)
	s_setprio 1
	s_waitcnt lgkmcnt(0)
	v_mfma_f32_16x16x32_bf16 v[124:127], v[150:153], v[166:169], v[124:127]
	v_mfma_f32_16x16x32_bf16 v[120:123], v[158:161], v[166:169], v[120:123]
	v_mfma_f32_16x16x32_bf16 v[116:119], v[150:153], v[174:177], v[116:119]
	v_mfma_f32_16x16x32_bf16 v[112:115], v[158:161], v[174:177], v[112:115]
	v_mfma_f32_16x16x32_bf16 v[104:107], v[150:153], v[182:185], v[104:107]
	v_mfma_f32_16x16x32_bf16 v[96:99], v[158:161], v[182:185], v[96:99]
	v_mfma_f32_16x16x32_bf16 v[88:91], v[150:153], v[190:193], v[88:91]
	v_mfma_f32_16x16x32_bf16 v[80:83], v[158:161], v[190:193], v[80:83]
	v_mfma_f32_16x16x32_bf16 v[124:127], v[154:157], v[170:173], v[124:127]
	v_mfma_f32_16x16x32_bf16 v[120:123], v[162:165], v[170:173], v[120:123]
	v_mfma_f32_16x16x32_bf16 v[116:119], v[154:157], v[178:181], v[116:119]
	v_mfma_f32_16x16x32_bf16 v[112:115], v[162:165], v[178:181], v[112:115]
	v_mfma_f32_16x16x32_bf16 v[104:107], v[154:157], v[186:189], v[104:107]
	v_mfma_f32_16x16x32_bf16 v[96:99], v[162:165], v[186:189], v[96:99]
	v_mfma_f32_16x16x32_bf16 v[88:91], v[154:157], v[194:197], v[88:91]
	v_mfma_f32_16x16x32_bf16 v[80:83], v[162:165], v[194:197], v[80:83]
	s_setprio 0
	s_barrier
	s_add_i32 s30, 0, 0x1c000
	s_add_i32 s18, s68, s39
	v_add_u32_e32 v214, s30, v146
	v_lshl_add_u64 v[144:145], v[144:145], 0, s[12:13]
	s_mov_b32 m0, s18
	ds_read_b128 v[202:205], v214
	ds_read_b128 v[206:209], v214 offset:1024
	ds_read_b128 v[210:213], v214 offset:2048
	ds_read_b128 v[214:217], v214 offset:3072
	global_load_lds_dwordx4 v[144:145], off
	v_lshl_add_u64 v[144:145], v[198:199], 0, s[12:13]
	s_add_i32 m0, s18, 0x2000
	s_nop 0
	global_load_lds_dwordx4 v[144:145], off
	s_barrier
	s_waitcnt lgkmcnt(0)
	s_setprio 1
	s_waitcnt lgkmcnt(0)
	v_mfma_f32_16x16x32_bf16 v[108:111], v[202:205], v[166:169], v[108:111]
	v_mfma_f32_16x16x32_bf16 v[100:103], v[210:213], v[166:169], v[100:103]
	v_mfma_f32_16x16x32_bf16 v[92:95], v[202:205], v[174:177], v[92:95]
	v_mfma_f32_16x16x32_bf16 v[84:87], v[210:213], v[174:177], v[84:87]
	v_mfma_f32_16x16x32_bf16 v[76:79], v[202:205], v[182:185], v[76:79]
	v_mfma_f32_16x16x32_bf16 v[72:75], v[210:213], v[182:185], v[72:75]
	v_mfma_f32_16x16x32_bf16 v[68:71], v[202:205], v[190:193], v[68:71]
	v_mfma_f32_16x16x32_bf16 v[64:67], v[210:213], v[190:193], v[64:67]
	v_mfma_f32_16x16x32_bf16 v[108:111], v[206:209], v[170:173], v[108:111]
	v_mfma_f32_16x16x32_bf16 v[100:103], v[214:217], v[170:173], v[100:103]
	v_mfma_f32_16x16x32_bf16 v[92:95], v[206:209], v[178:181], v[92:95]
	v_mfma_f32_16x16x32_bf16 v[84:87], v[214:217], v[178:181], v[84:87]
	v_mfma_f32_16x16x32_bf16 v[76:79], v[206:209], v[186:189], v[76:79]
	v_mfma_f32_16x16x32_bf16 v[72:75], v[214:217], v[186:189], v[72:75]
	v_mfma_f32_16x16x32_bf16 v[68:71], v[206:209], v[194:197], v[68:71]
	v_mfma_f32_16x16x32_bf16 v[64:67], v[214:217], v[194:197], v[64:67]
	s_setprio 0
	s_mov_b32 m0, s50
	v_lshl_add_u64 v[144:145], v[200:201], 0, s[12:13]
	s_barrier
	ds_read_b128 v[166:169], v148 offset:49152
	ds_read_b128 v[170:173], v148 offset:50176
	ds_read_b128 v[174:177], v148 offset:51200
	ds_read_b128 v[178:181], v148 offset:52224
	ds_read_b128 v[182:185], v148 offset:53248
	ds_read_b128 v[186:189], v148 offset:54272
	ds_read_b128 v[190:193], v148 offset:55296
	ds_read_b128 v[194:197], v148 offset:56320
	global_load_lds_dwordx4 v[144:145], off
	v_lshl_add_u64 v[144:145], v[218:219], 0, s[12:13]
	s_mov_b32 m0, s51
	s_nop 0
	global_load_lds_dwordx4 v[144:145], off
	s_barrier
;     DI void operator()(const AccT& acc, const Unit& u, int wr, int wc, int fr, int fq) const {
; #pragma unroll
;         for (int ai = 0; ai < 2; ++ai) {
;             f32x4 h[4][2][2];
;             float* base = H + ((size_t)u.pm * 256 + ai * 128 + wr * 64 + fr) * 1024 + u.pn * 256 + wc * 32 + 4 * fq;
; #pragma unroll
;             for (int m = 0; m < 4; ++m)
; #pragma unroll
;                 for (int bj = 0; bj < 2; ++bj)
; #pragma unroll
;                     for (int n = 0; n < 2; ++n) h[m][bj][n] = *(const f32x4*)(base + (size_t)m * 16 * 1024 + bj * 128 + n * 16);
;             __builtin_amdgcn_sched_barrier(0);
; #pragma unroll
;             for (int m = 0; m < 4; ++m)
; #pragma unroll
;                 for (int bj = 0; bj < 2; ++bj)
; #pragma unroll
;                     for (int n = 0; n < 2; ++n) *(f32x4*)(base + (size_t)m * 16 * 1024 + bj * 128 + n * 16) = h[m][bj][n] + acc[ai][bj][m][n] * alpha;
;         }
	s_waitcnt lgkmcnt(0)
	s_setprio 1
	s_waitcnt lgkmcnt(0)
	v_mfma_f32_16x16x32_bf16 v[60:63], v[150:153], v[166:169], v[60:63]
	v_mfma_f32_16x16x32_bf16 v[56:59], v[158:161], v[166:169], v[56:59]
	v_mfma_f32_16x16x32_bf16 v[52:55], v[150:153], v[174:177], v[52:55]
	v_mfma_f32_16x16x32_bf16 v[44:47], v[158:161], v[174:177], v[44:47]
	v_mfma_f32_16x16x32_bf16 v[36:39], v[150:153], v[182:185], v[36:39]
	v_mfma_f32_16x16x32_bf16 v[28:31], v[158:161], v[182:185], v[28:31]
	v_mfma_f32_16x16x32_bf16 v[20:23], v[150:153], v[190:193], v[20:23]
	v_mfma_f32_16x16x32_bf16 v[12:15], v[158:161], v[190:193], v[12:15]
	v_mfma_f32_16x16x32_bf16 v[60:63], v[154:157], v[170:173], v[60:63]
	v_mfma_f32_16x16x32_bf16 v[56:59], v[162:165], v[170:173], v[56:59]
	v_mfma_f32_16x16x32_bf16 v[52:55], v[154:157], v[178:181], v[52:55]
	v_mfma_f32_16x16x32_bf16 v[44:47], v[162:165], v[178:181], v[44:47]
	v_mfma_f32_16x16x32_bf16 v[36:39], v[154:157], v[186:189], v[36:39]
	v_mfma_f32_16x16x32_bf16 v[28:31], v[162:165], v[186:189], v[28:31]
	v_mfma_f32_16x16x32_bf16 v[20:23], v[154:157], v[194:197], v[20:23]
	v_mfma_f32_16x16x32_bf16 v[12:15], v[162:165], v[194:197], v[12:15]
	s_setprio 0
	s_barrier
	s_add_u32 s18, s28, 0xb0080
	s_addc_u32 s19, s29, 0
	s_add_i32 s28, s30, s39
	v_lshl_add_u64 v[144:145], s[18:19], 0, v[128:129]
	s_mov_b32 m0, s28
	s_nop 0
	global_load_lds_dwordx4 v[144:145], off
	v_lshl_add_u64 v[144:145], s[18:19], 0, v[130:131]
	s_add_i32 m0, s28, 0x2000
	s_nop 0
	global_load_lds_dwordx4 v[144:145], off
	s_waitcnt vmcnt(6)
	s_barrier
	s_setprio 1
	v_mfma_f32_16x16x32_bf16 v[48:51], v[202:205], v[166:169], v[48:51]
	v_mfma_f32_16x16x32_bf16 v[40:43], v[210:213], v[166:169], v[40:43]
	v_mfma_f32_16x16x32_bf16 v[32:35], v[202:205], v[174:177], v[32:35]
	v_mfma_f32_16x16x32_bf16 v[24:27], v[210:213], v[174:177], v[24:27]
	v_mfma_f32_16x16x32_bf16 v[16:19], v[202:205], v[182:185], v[16:19]
	v_mfma_f32_16x16x32_bf16 v[8:11], v[210:213], v[182:185], v[8:11]
	v_mfma_f32_16x16x32_bf16 v[4:7], v[202:205], v[190:193], v[4:7]
	v_mfma_f32_16x16x32_bf16 v[0:3], v[210:213], v[190:193], v[0:3]
	v_mfma_f32_16x16x32_bf16 v[48:51], v[206:209], v[170:173], v[48:51]
	v_mfma_f32_16x16x32_bf16 v[40:43], v[214:217], v[170:173], v[40:43]
	v_mfma_f32_16x16x32_bf16 v[32:35], v[206:209], v[178:181], v[32:35]
	v_mfma_f32_16x16x32_bf16 v[24:27], v[214:217], v[178:181], v[24:27]
	v_mfma_f32_16x16x32_bf16 v[16:19], v[206:209], v[186:189], v[16:19]
	v_mfma_f32_16x16x32_bf16 v[8:11], v[214:217], v[186:189], v[8:11]
	v_mfma_f32_16x16x32_bf16 v[4:7], v[206:209], v[194:197], v[4:7]
	v_mfma_f32_16x16x32_bf16 v[0:3], v[214:217], v[194:197], v[0:3]
	s_setprio 0
	s_add_i32 s67, s67, 2
	s_add_u32 s17, s17, 0x100
	s_addc_u32 s66, s66, 0
	s_cmp_gt_u32 s67, 41
	s_mov_b64 s[18:19], s[20:21]
	s_barrier
	s_cbranch_scc0 .LBB0_177
	s_ashr_i32 s17, s16, 31
	s_lshl_b32 s18, s65, 8
	s_lshl_b64 s[16:17], s[16:17], 20
	s_ashr_i32 s19, s18, 31
	s_mov_b32 s100, 0x20000
	s_mov_b32 s101, 0
	v_lshl_add_u64 v[214:215], v[252:253], 0, s[100:101]
	global_load_dwordx4 v[150:153], v[214:215], off
	global_load_dwordx4 v[154:157], v[214:215], off offset:64
	global_load_dwordx4 v[158:161], v[214:215], off offset:512
	global_load_dwordx4 v[162:165], v[214:215], off offset:576
	s_mov_b32 s100, 0x30000
	s_mov_b32 s101, 0
	v_lshl_add_u64 v[216:217], v[252:253], 0, s[100:101]
	global_load_dwordx4 v[166:169], v[216:217], off
	global_load_dwordx4 v[170:173], v[216:217], off offset:64
	global_load_dwordx4 v[174:177], v[216:217], off offset:512
	global_load_dwordx4 v[178:181], v[216:217], off offset:576
	s_mov_b32 s100, 0x80000
	s_mov_b32 s101, 0
	v_lshl_add_u64 v[214:215], v[252:253], 0, s[100:101]
	global_load_dwordx4 v[182:185], v[214:215], off
	global_load_dwordx4 v[186:189], v[214:215], off offset:64
	global_load_dwordx4 v[190:193], v[214:215], off offset:512
	global_load_dwordx4 v[194:197], v[214:215], off offset:576
	s_mov_b32 s100, 0x90000
	s_mov_b32 s101, 0
	v_lshl_add_u64 v[216:217], v[252:253], 0, s[100:101]
	global_load_dwordx4 v[198:201], v[216:217], off
	global_load_dwordx4 v[202:205], v[216:217], off offset:64
	global_load_dwordx4 v[206:209], v[216:217], off offset:512
	global_load_dwordx4 v[210:213], v[216:217], off offset:576
	s_waitcnt vmcnt(16)
	v_pk_fma_f32 v[124:125], v[124:125], 0.5, v[220:221] op_sel_hi:[1,0,1]
	v_pk_fma_f32 v[126:127], v[126:127], 0.5, v[222:223] op_sel_hi:[1,0,1]
	v_pk_fma_f32 v[120:121], v[120:121], 0.5, v[224:225] op_sel_hi:[1,0,1]
	v_pk_fma_f32 v[122:123], v[122:123], 0.5, v[226:227] op_sel_hi:[1,0,1]
	v_pk_fma_f32 v[108:109], v[108:109], 0.5, v[228:229] op_sel_hi:[1,0,1]
	v_pk_fma_f32 v[110:111], v[110:111], 0.5, v[230:231] op_sel_hi:[1,0,1]
	v_pk_fma_f32 v[100:101], v[100:101], 0.5, v[232:233] op_sel_hi:[1,0,1]
	v_pk_fma_f32 v[102:103], v[102:103], 0.5, v[234:235] op_sel_hi:[1,0,1]
	v_pk_fma_f32 v[116:117], v[116:117], 0.5, v[236:237] op_sel_hi:[1,0,1]
	v_pk_fma_f32 v[118:119], v[118:119], 0.5, v[238:239] op_sel_hi:[1,0,1]
	v_pk_fma_f32 v[112:113], v[112:113], 0.5, v[240:241] op_sel_hi:[1,0,1]
	v_pk_fma_f32 v[114:115], v[114:115], 0.5, v[242:243] op_sel_hi:[1,0,1]
	v_pk_fma_f32 v[92:93], v[92:93], 0.5, v[244:245] op_sel_hi:[1,0,1]
	v_pk_fma_f32 v[94:95], v[94:95], 0.5, v[246:247] op_sel_hi:[1,0,1]
	v_pk_fma_f32 v[84:85], v[84:85], 0.5, v[248:249] op_sel_hi:[1,0,1]
	v_pk_fma_f32 v[86:87], v[86:87], 0.5, v[250:251] op_sel_hi:[1,0,1]
	s_mov_b32 s100, 0x0
	s_mov_b32 s101, 0
	v_lshl_add_u64 v[216:217], v[252:253], 0, s[100:101]
	global_store_dwordx4 v[216:217], v[124:127], off
	global_store_dwordx4 v[216:217], v[120:123], off offset:64
	global_store_dwordx4 v[216:217], v[108:111], off offset:512
	global_store_dwordx4 v[216:217], v[100:103], off offset:576
	s_mov_b32 s100, 0x10000
	s_mov_b32 s101, 0
	v_lshl_add_u64 v[218:219], v[252:253], 0, s[100:101]
	global_store_dwordx4 v[218:219], v[116:119], off
	global_store_dwordx4 v[218:219], v[112:115], off offset:64
	global_store_dwordx4 v[218:219], v[92:95], off offset:512
	global_store_dwordx4 v[218:219], v[84:87], off offset:576
	s_mov_b32 s100, 0xa0000
	s_mov_b32 s101, 0
	v_lshl_add_u64 v[214:215], v[252:253], 0, s[100:101]
	global_load_dwordx4 v[220:223], v[214:215], off
	global_load_dwordx4 v[224:227], v[214:215], off offset:64
	global_load_dwordx4 v[228:231], v[214:215], off offset:512
	global_load_dwordx4 v[232:235], v[214:215], off offset:576
	s_mov_b32 s100, 0xb0000
	s_mov_b32 s101, 0
	v_lshl_add_u64 v[216:217], v[252:253], 0, s[100:101]
	global_load_dwordx4 v[236:239], v[216:217], off
	global_load_dwordx4 v[240:243], v[216:217], off offset:64
	global_load_dwordx4 v[244:247], v[216:217], off offset:512
	global_load_dwordx4 v[248:251], v[216:217], off offset:576
	s_waitcnt vmcnt(24)
; #define PG8_WAIT_V(n) asm volatile("s_waitcnt vmcnt(" #n ")" ::: "memory")
; #define PG8_BAR __builtin_amdgcn_s_barrier()
; template <class Epi>
; DI void gemm_phase(int wv, LAS unsigned char* lds, const Gemm g, const StaticOrder& S, const Epi& E) {
;     ...
;         if (!has_next) break;
; #pragma unroll
;         for (int a = 0; a < 2; ++a)
; #pragma unroll
;             for (int b = 0; b < 2; ++b)
; #pragma unroll
;                 for (int m = 0; m < 4; ++m)
; #pragma unroll
;                     for (int n = 0; n < 2; ++n) acc[a][b][m][n] = (f32x4){0.f, 0.f, 0.f, 0.f};
;         cur = nxt; cA = nA; cB = nB; ++ui;
;     }
;     PG8_WAIT_V(0);
;     if (wr == 0) PG8_BAR;
;     PG8_BAR;
;     DI void operator()(const AccT& acc, const Unit& u, int wr, int wc, int fr, int fq) const {
; #pragma unroll
;         for (int ai = 0; ai < 2; ++ai) {
;             f32x4 h[4][2][2];
;             float* base = H + ((size_t)u.pm * 256 + ai * 128 + wr * 64 + fr) * 1024 + u.pn * 256 + wc * 32 + 4 * fq;
; #pragma unroll
;             for (int m = 0; m < 4; ++m)
; #pragma unroll
;                 for (int bj = 0; bj < 2; ++bj)
; #pragma unroll
;                     for (int n = 0; n < 2; ++n) h[m][bj][n] = *(const f32x4*)(base + (size_t)m * 16 * 1024 + bj * 128 + n * 16);
;             __builtin_amdgcn_sched_barrier(0);
; #pragma unroll
;             for (int m = 0; m < 4; ++m)
; #pragma unroll
;                 for (int bj = 0; bj < 2; ++bj)
; #pragma unroll
;                     for (int n = 0; n < 2; ++n) *(f32x4*)(base + (size_t)m * 16 * 1024 + bj * 128 + n * 16) = h[m][bj][n] + acc[ai][bj][m][n] * alpha;
;         }
	v_pk_fma_f32 v[104:105], v[104:105], 0.5, v[150:151] op_sel_hi:[1,0,1]
	v_pk_fma_f32 v[106:107], v[106:107], 0.5, v[152:153] op_sel_hi:[1,0,1]
	v_pk_fma_f32 v[96:97], v[96:97], 0.5, v[154:155] op_sel_hi:[1,0,1]
	v_pk_fma_f32 v[98:99], v[98:99], 0.5, v[156:157] op_sel_hi:[1,0,1]
	v_pk_fma_f32 v[76:77], v[76:77], 0.5, v[158:159] op_sel_hi:[1,0,1]
	v_pk_fma_f32 v[78:79], v[78:79], 0.5, v[160:161] op_sel_hi:[1,0,1]
	v_pk_fma_f32 v[72:73], v[72:73], 0.5, v[162:163] op_sel_hi:[1,0,1]
	v_pk_fma_f32 v[74:75], v[74:75], 0.5, v[164:165] op_sel_hi:[1,0,1]
	v_pk_fma_f32 v[88:89], v[88:89], 0.5, v[166:167] op_sel_hi:[1,0,1]
	v_pk_fma_f32 v[90:91], v[90:91], 0.5, v[168:169] op_sel_hi:[1,0,1]
	v_pk_fma_f32 v[80:81], v[80:81], 0.5, v[170:171] op_sel_hi:[1,0,1]
	v_pk_fma_f32 v[82:83], v[82:83], 0.5, v[172:173] op_sel_hi:[1,0,1]
	v_pk_fma_f32 v[68:69], v[68:69], 0.5, v[174:175] op_sel_hi:[1,0,1]
	v_pk_fma_f32 v[70:71], v[70:71], 0.5, v[176:177] op_sel_hi:[1,0,1]
	v_pk_fma_f32 v[64:65], v[64:65], 0.5, v[178:179] op_sel_hi:[1,0,1]
	v_pk_fma_f32 v[66:67], v[66:67], 0.5, v[180:181] op_sel_hi:[1,0,1]
	s_mov_b32 s100, 0x20000
	s_mov_b32 s101, 0
	v_lshl_add_u64 v[216:217], v[252:253], 0, s[100:101]
	global_store_dwordx4 v[216:217], v[104:107], off
	global_store_dwordx4 v[216:217], v[96:99], off offset:64
	global_store_dwordx4 v[216:217], v[76:79], off offset:512
	global_store_dwordx4 v[216:217], v[72:75], off offset:576
	s_mov_b32 s100, 0x30000
	s_mov_b32 s101, 0
	v_lshl_add_u64 v[218:219], v[252:253], 0, s[100:101]
	global_store_dwordx4 v[218:219], v[88:91], off
	global_store_dwordx4 v[218:219], v[80:83], off offset:64
	global_store_dwordx4 v[218:219], v[68:71], off offset:512
	global_store_dwordx4 v[218:219], v[64:67], off offset:576
	s_waitcnt vmcnt(24)
	v_pk_fma_f32 v[60:61], v[60:61], 0.5, v[182:183] op_sel_hi:[1,0,1]
	v_pk_fma_f32 v[62:63], v[62:63], 0.5, v[184:185] op_sel_hi:[1,0,1]
	v_pk_fma_f32 v[56:57], v[56:57], 0.5, v[186:187] op_sel_hi:[1,0,1]
	v_pk_fma_f32 v[58:59], v[58:59], 0.5, v[188:189] op_sel_hi:[1,0,1]
	v_pk_fma_f32 v[48:49], v[48:49], 0.5, v[190:191] op_sel_hi:[1,0,1]
	v_pk_fma_f32 v[50:51], v[50:51], 0.5, v[192:193] op_sel_hi:[1,0,1]
	v_pk_fma_f32 v[40:41], v[40:41], 0.5, v[194:195] op_sel_hi:[1,0,1]
	v_pk_fma_f32 v[42:43], v[42:43], 0.5, v[196:197] op_sel_hi:[1,0,1]
	v_pk_fma_f32 v[52:53], v[52:53], 0.5, v[198:199] op_sel_hi:[1,0,1]
	v_pk_fma_f32 v[54:55], v[54:55], 0.5, v[200:201] op_sel_hi:[1,0,1]
	v_pk_fma_f32 v[44:45], v[44:45], 0.5, v[202:203] op_sel_hi:[1,0,1]
	v_pk_fma_f32 v[46:47], v[46:47], 0.5, v[204:205] op_sel_hi:[1,0,1]
	v_pk_fma_f32 v[32:33], v[32:33], 0.5, v[206:207] op_sel_hi:[1,0,1]
	v_pk_fma_f32 v[34:35], v[34:35], 0.5, v[208:209] op_sel_hi:[1,0,1]
	v_pk_fma_f32 v[24:25], v[24:25], 0.5, v[210:211] op_sel_hi:[1,0,1]
	v_pk_fma_f32 v[26:27], v[26:27], 0.5, v[212:213] op_sel_hi:[1,0,1]
	s_mov_b32 s100, 0x80000
	s_mov_b32 s101, 0
	v_lshl_add_u64 v[216:217], v[252:253], 0, s[100:101]
	global_store_dwordx4 v[216:217], v[60:63], off
	global_store_dwordx4 v[216:217], v[56:59], off offset:64
	global_store_dwordx4 v[216:217], v[48:51], off offset:512
	global_store_dwordx4 v[216:217], v[40:43], off offset:576
	s_mov_b32 s100, 0x90000
	s_mov_b32 s101, 0
	v_lshl_add_u64 v[218:219], v[252:253], 0, s[100:101]
	global_store_dwordx4 v[218:219], v[52:55], off
	global_store_dwordx4 v[218:219], v[44:47], off offset:64
	global_store_dwordx4 v[218:219], v[32:35], off offset:512
	global_store_dwordx4 v[218:219], v[24:27], off offset:576
	s_waitcnt vmcnt(16)
	v_pk_fma_f32 v[36:37], v[36:37], 0.5, v[220:221] op_sel_hi:[1,0,1]
	v_pk_fma_f32 v[38:39], v[38:39], 0.5, v[222:223] op_sel_hi:[1,0,1]
	v_pk_fma_f32 v[28:29], v[28:29], 0.5, v[224:225] op_sel_hi:[1,0,1]
	v_pk_fma_f32 v[30:31], v[30:31], 0.5, v[226:227] op_sel_hi:[1,0,1]
	v_pk_fma_f32 v[16:17], v[16:17], 0.5, v[228:229] op_sel_hi:[1,0,1]
	v_pk_fma_f32 v[18:19], v[18:19], 0.5, v[230:231] op_sel_hi:[1,0,1]
	v_pk_fma_f32 v[8:9], v[8:9], 0.5, v[232:233] op_sel_hi:[1,0,1]
	v_pk_fma_f32 v[10:11], v[10:11], 0.5, v[234:235] op_sel_hi:[1,0,1]
	v_pk_fma_f32 v[20:21], v[20:21], 0.5, v[236:237] op_sel_hi:[1,0,1]
	v_pk_fma_f32 v[22:23], v[22:23], 0.5, v[238:239] op_sel_hi:[1,0,1]
	v_pk_fma_f32 v[12:13], v[12:13], 0.5, v[240:241] op_sel_hi:[1,0,1]
	v_pk_fma_f32 v[14:15], v[14:15], 0.5, v[242:243] op_sel_hi:[1,0,1]
	v_pk_fma_f32 v[4:5], v[4:5], 0.5, v[244:245] op_sel_hi:[1,0,1]
	v_pk_fma_f32 v[6:7], v[6:7], 0.5, v[246:247] op_sel_hi:[1,0,1]
	v_pk_fma_f32 v[0:1], v[0:1], 0.5, v[248:249] op_sel_hi:[1,0,1]
	v_pk_fma_f32 v[2:3], v[2:3], 0.5, v[250:251] op_sel_hi:[1,0,1]
	s_mov_b32 s100, 0xa0000
	s_mov_b32 s101, 0
	v_lshl_add_u64 v[216:217], v[252:253], 0, s[100:101]
	global_store_dwordx4 v[216:217], v[36:39], off
	global_store_dwordx4 v[216:217], v[28:31], off offset:64
	global_store_dwordx4 v[216:217], v[16:19], off offset:512
	global_store_dwordx4 v[216:217], v[8:11], off offset:576
	s_mov_b32 s100, 0xb0000
	s_mov_b32 s101, 0
	v_lshl_add_u64 v[218:219], v[252:253], 0, s[100:101]
	global_store_dwordx4 v[218:219], v[20:23], off
	global_store_dwordx4 v[218:219], v[12:15], off offset:64
	global_store_dwordx4 v[218:219], v[4:7], off offset:512
	global_store_dwordx4 v[218:219], v[0:3], off offset:576
	s_and_b64 vcc, exec, s[4:5]
	s_mov_b32 s65, s63
	s_mov_b32 s16, s64
	s_mov_b64 s[20:21], s[8:9]
	s_mov_b64 s[18:19], s[6:7]
	s_cbranch_vccz .LBB0_166
	s_waitcnt vmcnt(0)
	s_cmpk_gt_u32 s36, 0xff
	s_cbranch_scc1 .LBB0_181
	s_barrier

;     DI bool next(int i, Unit& u) const {
;         const long L = (long)i * G + c; if (L >= nwg) return false;
;         int wgid = (int)L; { const int q = nwg / NXCD, r = nwg % NXCD, xcd = wgid % NXCD, off = wgid / NXCD; wgid = (xcd < r ? xcd * (q + 1) : r * (q + 1) + (xcd - r) * q) + off; }
;         const int nig = WGM * nN, gid = wgid / nig, fm = gid * WGM, gsz = (nM - fm) < WGM ? (nM - fm) : WGM;
;         u.pm = fm + ((wgid % nig) % gsz); u.pn = (wgid % nig) / gsz; return true;
;     }
;     DI void operator()(const AccT& acc, const Unit& u, int wr, int wc, int fr, int fq) const {
; #pragma unroll
;         for (int ai = 0; ai < 2; ++ai) {
;             f32x4 h[4][2][2];
;             float* base = H + ((size_t)u.pm * 256 + ai * 128 + wr * 64 + fr) * 1024 + u.pn * 256 + wc * 32 + 4 * fq;
; #pragma unroll
;             for (int m = 0; m < 4; ++m)
; #pragma unroll
;                 for (int bj = 0; bj < 2; ++bj)
; #pragma unroll
;                     for (int n = 0; n < 2; ++n) h[m][bj][n] = *(const f32x4*)(base + (size_t)m * 16 * 1024 + bj * 128 + n * 16);
.LBB0_1367:
	s_mov_b32 s98, s60
	s_ashr_i32 s99, s60, 31
	s_lshl_b64 s[98:99], s[98:99], 20
	s_lshl_b32 s100, s78, 8
	s_ashr_i32 s101, s100, 31
	v_lshl_add_u64 v[252:253], v[134:135], 0, s[98:99]
	v_lshl_add_u64 v[252:253], s[100:101], 2, v[252:253]
	v_lshl_add_u64 v[252:253], v[252:253], 0, s[14:15]
	v_lshl_add_u64 v[252:253], v[252:253], 0, v[132:133]
	global_load_dwordx4 v[220:223], v[252:253], off
	global_load_dwordx4 v[224:227], v[252:253], off offset:64
	global_load_dwordx4 v[228:231], v[252:253], off offset:512
	global_load_dwordx4 v[232:235], v[252:253], off offset:576
	s_mov_b32 s100, 0x10000
	s_mov_b32 s101, 0
	v_lshl_add_u64 v[252:253], v[252:253], 0, s[100:101]
	global_load_dwordx4 v[236:239], v[252:253], off
	global_load_dwordx4 v[240:243], v[252:253], off offset:64
	global_load_dwordx4 v[244:247], v[252:253], off offset:512
	global_load_dwordx4 v[248:251], v[252:253], off offset:576
	s_mov_b32 s100, 0xffff0000
	s_mov_b32 s101, -1
	v_lshl_add_u64 v[252:253], v[252:253], 0, s[100:101]
	s_add_i32 s77, s77, 1
	s_mul_i32 s12, s77, s45
	s_mul_hi_u32 s13, s77, s44
	s_add_i32 s13, s13, s12
	s_mul_i32 s12, s77, s44
	s_add_u32 s30, s12, s2
	s_addc_u32 s31, s13, s3
	v_cmp_gt_i64_e64 s[12:13], s[30:31], v[142:143]
	s_and_b64 vcc, exec, s[12:13]
	s_cbranch_vccnz .LBB0_1373
	s_ashr_i32 s20, s30, 31
	s_lshr_b32 s20, s20, 29
	s_add_i32 s28, s30, s20
	s_and_b32 s20, s28, -8
	s_sub_i32 s29, s30, s20
	s_cmp_gt_i32 s29, 3
	s_mov_b64 s[20:21], -1
	s_cbranch_scc0 .LBB0_1370
	s_mul_i32 s20, s29, 0xa1
	s_add_i32 s38, s20, 4
	s_mov_b64 s[20:21], 0

; #define PG8_STAGE(bufoff, gbase, voff) do { _Pragma("unroll") for (int _i = 0; _i < 2; ++_i) \
;         __builtin_amdgcn_global_load_lds((const unsigned*)((const char*)(gbase) + (voff)[_i]), (LAS unsigned*)(lds + (bufoff) + ldsw + _i * 8192), 16, 0, 0); } while (0)
; #define PG8_LDA(dst, b, h) do { _Pragma("unroll") for (int m = 0; m < 4; ++m) _Pragma("unroll") for (int k = 0; k < 2; ++k) dst[m][k] = *(const LAS bf16x8*)(lds + PG8_SA(b, h) + aoff + m * 2048 + k * 1024); } while (0)
; #define PG8_LDB(dst, b, h) do { _Pragma("unroll") for (int n = 0; n < 2; ++n) _Pragma("unroll") for (int k = 0; k < 2; ++k) dst[n][k] = *(const LAS bf16x8*)(lds + PG8_SB(b, h) + boff + n * 2048 + k * 1024); } while (0)
; #define PG8_MMA(ai, bj, At, Bt) do { __builtin_amdgcn_s_setprio(1); _Pragma("unroll") for (int m = 0; m < 4; ++m) _Pragma("unroll") for (int n = 0; n < 2; ++n) _Pragma("unroll") for (int k = 0; k < 2; ++k) \
;         acc[ai][bj][m][n] = __builtin_amdgcn_mfma_f32_16x16x32_bf16(Bt[n][k], At[m][k], acc[ai][bj][m][n], 0, 0, 0); __builtin_amdgcn_s_setprio(0); } while (0)
; #define PG8_WAIT_V(n) asm volatile("s_waitcnt vmcnt(" #n ")" ::: "memory")
; #define PG8_WAIT_L(n) asm volatile("s_waitcnt lgkmcnt(" #n ")" ::: "memory")
; #define PG8_BAR __builtin_amdgcn_s_barrier()
; #define PG8_SCHED __builtin_amdgcn_sched_barrier(0)
; template <class Epi>
; DI void gemm_phase(int wv, LAS unsigned char* lds, const Gemm g, const StaticOrder& S, const Epi& E) {
;     ...
;             PG8_LDB(B0, 0, 0); PG8_SCHED; PG8_LDA(At, 0, 0); PG8_STAGE(PG8_SA(1, 1), a1 + hstep, voffA);
;             PG8_WAIT_L(8); PG8_BAR; PG8_WAIT_L(0); PG8_MMA(0, 0, At, B0); PG8_BAR; PG8_SCHED;
;             PG8_LDB(B1, 0, 1); PG8_STAGE(PG8_SB(0, 0), b2, voffB);
;             PG8_BAR; PG8_WAIT_L(0); PG8_MMA(0, 1, At, B1); PG8_BAR;
;             PG8_LDA(At, 0, 1); PG8_STAGE(PG8_SA(0, 0), a2, voffA);
;             PG8_BAR; PG8_WAIT_L(0); PG8_MMA(1, 0, At, B0); PG8_BAR; PG8_SCHED;
;             PG8_STAGE(PG8_SB(0, 1), b2 + hstep, voffB);
;             PG8_WAIT_V(6); PG8_BAR; PG8_MMA(1, 1, At, B1); PG8_BAR;
;             PG8_LDB(B0, 1, 0); PG8_SCHED; PG8_LDA(At, 1, 0); PG8_STAGE(PG8_SA(0, 1), a2 + hstep, voffA);
;             PG8_WAIT_L(8); PG8_BAR; PG8_WAIT_L(0); PG8_MMA(0, 0, At, B0); PG8_BAR; PG8_SCHED;
.LBB0_1374:
	ds_read_b128 v[150:153], v147
	ds_read_b128 v[154:157], v147 offset:1024
	ds_read_b128 v[158:161], v147 offset:2048
	ds_read_b128 v[162:165], v147 offset:3072
	s_add_u32 s64, s62, 0x100
	s_addc_u32 s65, s63, 0
	s_cmp_eq_u32 s82, 12
	s_cselect_b32 s69, s29, s65
	s_cselect_b32 s68, s61, s64
	s_cselect_b32 s67, s21, s81
	s_cselect_b32 s66, s79, s80
	v_lshl_add_u64 v[144:145], s[62:63], 0, v[136:137]
	s_add_i32 m0, s51, 0xc000
	ds_read_b128 v[166:169], v148
	ds_read_b128 v[170:173], v148 offset:1024
	ds_read_b128 v[174:177], v148 offset:2048
	ds_read_b128 v[178:181], v148 offset:3072
	ds_read_b128 v[182:185], v148 offset:4096
	ds_read_b128 v[186:189], v148 offset:5120
	ds_read_b128 v[190:193], v148 offset:6144
	ds_read_b128 v[194:197], v148 offset:7168
	global_load_lds_dwordx4 v[144:145], off
	v_lshl_add_u64 v[144:145], s[62:63], 0, v[138:139]
	s_add_i32 m0, s51, 0xe000
	s_nop 0
	global_load_lds_dwordx4 v[144:145], off
	s_waitcnt lgkmcnt(8)
	s_barrier
	s_waitcnt lgkmcnt(0)
	s_setprio 1
	s_waitcnt lgkmcnt(0)
	v_mfma_f32_16x16x32_bf16 v[124:127], v[150:153], v[166:169], v[124:127]
	v_mfma_f32_16x16x32_bf16 v[120:123], v[158:161], v[166:169], v[120:123]
	v_mfma_f32_16x16x32_bf16 v[116:119], v[150:153], v[174:177], v[116:119]
	v_mfma_f32_16x16x32_bf16 v[112:115], v[158:161], v[174:177], v[112:115]
	v_mfma_f32_16x16x32_bf16 v[104:107], v[150:153], v[182:185], v[104:107]
	v_mfma_f32_16x16x32_bf16 v[96:99], v[158:161], v[182:185], v[96:99]
	v_mfma_f32_16x16x32_bf16 v[88:91], v[150:153], v[190:193], v[88:91]
	v_mfma_f32_16x16x32_bf16 v[80:83], v[158:161], v[190:193], v[80:83]
	v_mfma_f32_16x16x32_bf16 v[124:127], v[154:157], v[170:173], v[124:127]
	v_mfma_f32_16x16x32_bf16 v[120:123], v[162:165], v[170:173], v[120:123]
	v_mfma_f32_16x16x32_bf16 v[116:119], v[154:157], v[178:181], v[116:119]
	v_mfma_f32_16x16x32_bf16 v[112:115], v[162:165], v[178:181], v[112:115]
	v_mfma_f32_16x16x32_bf16 v[104:107], v[154:157], v[186:189], v[104:107]
	v_mfma_f32_16x16x32_bf16 v[96:99], v[162:165], v[186:189], v[96:99]
	v_mfma_f32_16x16x32_bf16 v[88:91], v[154:157], v[194:197], v[88:91]
	v_mfma_f32_16x16x32_bf16 v[80:83], v[162:165], v[194:197], v[80:83]
	s_setprio 0
	s_barrier
	s_add_i32 s62, s59, s50
	v_lshl_add_u64 v[144:145], s[66:67], 0, v[128:129]
	s_mov_b32 m0, s62
	ds_read_b128 v[198:201], v149
	ds_read_b128 v[202:205], v149 offset:1024
	ds_read_b128 v[206:209], v149 offset:2048
	ds_read_b128 v[210:213], v149 offset:3072
	global_load_lds_dwordx4 v[144:145], off
	v_lshl_add_u64 v[214:215], s[66:67], 0, v[130:131]
	s_add_i32 m0, s62, 0x2000
	s_nop 0
	global_load_lds_dwordx4 v[214:215], off
	s_barrier
	s_waitcnt lgkmcnt(0)
	s_setprio 1
	s_waitcnt lgkmcnt(0)
	v_mfma_f32_16x16x32_bf16 v[108:111], v[198:201], v[166:169], v[108:111]
	v_mfma_f32_16x16x32_bf16 v[100:103], v[206:209], v[166:169], v[100:103]
	v_mfma_f32_16x16x32_bf16 v[92:95], v[198:201], v[174:177], v[92:95]
	v_mfma_f32_16x16x32_bf16 v[84:87], v[206:209], v[174:177], v[84:87]
	v_mfma_f32_16x16x32_bf16 v[76:79], v[198:201], v[182:185], v[76:79]
	v_mfma_f32_16x16x32_bf16 v[72:75], v[206:209], v[182:185], v[72:75]
	v_mfma_f32_16x16x32_bf16 v[68:71], v[198:201], v[190:193], v[68:71]
	v_mfma_f32_16x16x32_bf16 v[64:67], v[206:209], v[190:193], v[64:67]
	v_mfma_f32_16x16x32_bf16 v[108:111], v[202:205], v[170:173], v[108:111]
	v_mfma_f32_16x16x32_bf16 v[100:103], v[210:213], v[170:173], v[100:103]
	v_mfma_f32_16x16x32_bf16 v[92:95], v[202:205], v[178:181], v[92:95]
	v_mfma_f32_16x16x32_bf16 v[84:87], v[210:213], v[178:181], v[84:87]
	v_mfma_f32_16x16x32_bf16 v[76:79], v[202:205], v[186:189], v[76:79]
	v_mfma_f32_16x16x32_bf16 v[72:75], v[210:213], v[186:189], v[72:75]
	v_mfma_f32_16x16x32_bf16 v[68:71], v[202:205], v[194:197], v[68:71]
	v_mfma_f32_16x16x32_bf16 v[64:67], v[210:213], v[194:197], v[64:67]
	s_setprio 0
	s_mov_b32 m0, s51
	v_lshl_add_u64 v[216:217], s[68:69], 0, v[128:129]
	s_barrier
	ds_read_b128 v[166:169], v148 offset:16384
	ds_read_b128 v[170:173], v148 offset:17408
	ds_read_b128 v[174:177], v148 offset:18432
	ds_read_b128 v[178:181], v148 offset:19456
	ds_read_b128 v[182:185], v148 offset:20480
	ds_read_b128 v[186:189], v148 offset:21504
	ds_read_b128 v[190:193], v148 offset:22528
	ds_read_b128 v[194:197], v148 offset:23552
	global_load_lds_dwordx4 v[216:217], off
	v_lshl_add_u64 v[218:219], s[68:69], 0, v[130:131]
	s_mov_b32 m0, s52
	s_nop 0
	global_load_lds_dwordx4 v[218:219], off
	s_barrier
	s_waitcnt lgkmcnt(0)
	s_setprio 1
	s_waitcnt lgkmcnt(0)
	v_mfma_f32_16x16x32_bf16 v[60:63], v[150:153], v[166:169], v[60:63]
	v_mfma_f32_16x16x32_bf16 v[56:59], v[158:161], v[166:169], v[56:59]
	v_mfma_f32_16x16x32_bf16 v[52:55], v[150:153], v[174:177], v[52:55]
	v_mfma_f32_16x16x32_bf16 v[44:47], v[158:161], v[174:177], v[44:47]
	v_mfma_f32_16x16x32_bf16 v[36:39], v[150:153], v[182:185], v[36:39]
	v_mfma_f32_16x16x32_bf16 v[28:31], v[158:161], v[182:185], v[28:31]
	v_mfma_f32_16x16x32_bf16 v[20:23], v[150:153], v[190:193], v[20:23]
	v_mfma_f32_16x16x32_bf16 v[12:15], v[158:161], v[190:193], v[12:15]
	v_mfma_f32_16x16x32_bf16 v[60:63], v[154:157], v[170:173], v[60:63]
	v_mfma_f32_16x16x32_bf16 v[56:59], v[162:165], v[170:173], v[56:59]
	v_mfma_f32_16x16x32_bf16 v[52:55], v[154:157], v[178:181], v[52:55]
	v_mfma_f32_16x16x32_bf16 v[44:47], v[162:165], v[178:181], v[44:47]
	v_mfma_f32_16x16x32_bf16 v[36:39], v[154:157], v[186:189], v[36:39]
	v_mfma_f32_16x16x32_bf16 v[28:31], v[162:165], v[186:189], v[28:31]
	v_mfma_f32_16x16x32_bf16 v[20:23], v[154:157], v[194:197], v[20:23]
	v_mfma_f32_16x16x32_bf16 v[12:15], v[162:165], v[194:197], v[12:15]
	s_setprio 0
	s_barrier
; #define PG8_STAGE(bufoff, gbase, voff) do { _Pragma("unroll") for (int _i = 0; _i < 2; ++_i) \
;         __builtin_amdgcn_global_load_lds((const unsigned*)((const char*)(gbase) + (voff)[_i]), (LAS unsigned*)(lds + (bufoff) + ldsw + _i * 8192), 16, 0, 0); } while (0)
; #define PG8_LDA(dst, b, h) do { _Pragma("unroll") for (int m = 0; m < 4; ++m) _Pragma("unroll") for (int k = 0; k < 2; ++k) dst[m][k] = *(const LAS bf16x8*)(lds + PG8_SA(b, h) + aoff + m * 2048 + k * 1024); } while (0)
; #define PG8_LDB(dst, b, h) do { _Pragma("unroll") for (int n = 0; n < 2; ++n) _Pragma("unroll") for (int k = 0; k < 2; ++k) dst[n][k] = *(const LAS bf16x8*)(lds + PG8_SB(b, h) + boff + n * 2048 + k * 1024); } while (0)
; #define PG8_MMA(ai, bj, At, Bt) do { __builtin_amdgcn_s_setprio(1); _Pragma("unroll") for (int m = 0; m < 4; ++m) _Pragma("unroll") for (int n = 0; n < 2; ++n) _Pragma("unroll") for (int k = 0; k < 2; ++k) \
;         acc[ai][bj][m][n] = __builtin_amdgcn_mfma_f32_16x16x32_bf16(Bt[n][k], At[m][k], acc[ai][bj][m][n], 0, 0, 0); __builtin_amdgcn_s_setprio(0); } while (0)
; #define PG8_WAIT_V(n) asm volatile("s_waitcnt vmcnt(" #n ")" ::: "memory")
; #define PG8_WAIT_L(n) asm volatile("s_waitcnt lgkmcnt(" #n ")" ::: "memory")
; #define PG8_BAR __builtin_amdgcn_s_barrier()
; #define PG8_SCHED __builtin_amdgcn_sched_barrier(0)
; template <class Epi>
; DI void gemm_phase(int wv, LAS unsigned char* lds, const Gemm g, const StaticOrder& S, const Epi& E) {
;     ...
;             PG8_LDB(B1, 1, 1); PG8_STAGE(PG8_SB(1, 0), b3, voffB);
;             PG8_BAR; PG8_WAIT_L(0); PG8_MMA(0, 1, At, B1); PG8_BAR;
;             PG8_LDA(At, 1, 1); PG8_STAGE(PG8_SA(1, 0), a3, voffA);
;             PG8_BAR; PG8_WAIT_L(0); PG8_MMA(1, 0, At, B0); PG8_BAR; PG8_SCHED;
;             PG8_STAGE(PG8_SB(1, 1), b3 + hstep, voffB);
;             PG8_WAIT_V(6); PG8_BAR; PG8_MMA(1, 1, At, B1); PG8_BAR;
	s_add_u32 s62, s66, 0x40000
	s_addc_u32 s63, s67, 0
	s_add_i32 s83, s70, s50
	v_lshl_add_u64 v[150:151], s[62:63], 0, v[128:129]
	s_mov_b32 m0, s83
	s_nop 0
	global_load_lds_dwordx4 v[150:151], off
	v_lshl_add_u64 v[150:151], s[62:63], 0, v[130:131]
	s_add_i32 m0, s83, 0x2000
	s_nop 0
	global_load_lds_dwordx4 v[150:151], off
	s_waitcnt vmcnt(6)
	s_barrier
	s_setprio 1
	v_mfma_f32_16x16x32_bf16 v[48:51], v[198:201], v[166:169], v[48:51]
	v_mfma_f32_16x16x32_bf16 v[40:43], v[206:209], v[166:169], v[40:43]
	v_mfma_f32_16x16x32_bf16 v[32:35], v[198:201], v[174:177], v[32:35]
	v_mfma_f32_16x16x32_bf16 v[24:27], v[206:209], v[174:177], v[24:27]
	v_mfma_f32_16x16x32_bf16 v[16:19], v[198:201], v[182:185], v[16:19]
	v_mfma_f32_16x16x32_bf16 v[8:11], v[206:209], v[182:185], v[8:11]
	v_mfma_f32_16x16x32_bf16 v[4:7], v[198:201], v[190:193], v[4:7]
	v_mfma_f32_16x16x32_bf16 v[0:3], v[206:209], v[190:193], v[0:3]
	v_mfma_f32_16x16x32_bf16 v[48:51], v[202:205], v[170:173], v[48:51]
	v_mfma_f32_16x16x32_bf16 v[40:43], v[210:213], v[170:173], v[40:43]
	v_mfma_f32_16x16x32_bf16 v[32:35], v[202:205], v[178:181], v[32:35]
	v_mfma_f32_16x16x32_bf16 v[24:27], v[210:213], v[178:181], v[24:27]
	v_mfma_f32_16x16x32_bf16 v[16:19], v[202:205], v[186:189], v[16:19]
	v_mfma_f32_16x16x32_bf16 v[8:11], v[210:213], v[186:189], v[8:11]
	v_mfma_f32_16x16x32_bf16 v[4:7], v[202:205], v[194:197], v[4:7]
	v_mfma_f32_16x16x32_bf16 v[0:3], v[210:213], v[194:197], v[0:3]
	s_setprio 0
	s_add_i32 s83, 0, 0x18000
	v_add_u32_e32 v162, s83, v146
	s_barrier
	ds_read_b128 v[150:153], v162
	ds_read_b128 v[154:157], v162 offset:1024
	ds_read_b128 v[158:161], v162 offset:2048
	ds_read_b128 v[162:165], v162 offset:3072
	s_add_u32 s62, s68, 0x40000
	s_addc_u32 s63, s69, 0
	s_mov_b32 m0, s53
	v_lshl_add_u64 v[198:199], s[62:63], 0, v[128:129]
	ds_read_b128 v[166:169], v148 offset:32768
	ds_read_b128 v[170:173], v148 offset:33792
	ds_read_b128 v[174:177], v148 offset:34816
	ds_read_b128 v[178:181], v148 offset:35840
	ds_read_b128 v[182:185], v148 offset:36864
	ds_read_b128 v[186:189], v148 offset:37888
	ds_read_b128 v[190:193], v148 offset:38912
	ds_read_b128 v[194:197], v148 offset:39936
	global_load_lds_dwordx4 v[198:199], off
	v_lshl_add_u64 v[198:199], s[62:63], 0, v[130:131]
	s_mov_b32 m0, s54
	s_nop 0
	global_load_lds_dwordx4 v[198:199], off
	s_waitcnt lgkmcnt(8)
	s_barrier
	s_waitcnt lgkmcnt(0)
	s_setprio 1
	s_waitcnt lgkmcnt(0)
	v_mfma_f32_16x16x32_bf16 v[124:127], v[150:153], v[166:169], v[124:127]
	v_mfma_f32_16x16x32_bf16 v[120:123], v[158:161], v[166:169], v[120:123]
	v_mfma_f32_16x16x32_bf16 v[116:119], v[150:153], v[174:177], v[116:119]
	v_mfma_f32_16x16x32_bf16 v[112:115], v[158:161], v[174:177], v[112:115]
	v_mfma_f32_16x16x32_bf16 v[104:107], v[150:153], v[182:185], v[104:107]
	v_mfma_f32_16x16x32_bf16 v[96:99], v[158:161], v[182:185], v[96:99]
	v_mfma_f32_16x16x32_bf16 v[88:91], v[150:153], v[190:193], v[88:91]
	v_mfma_f32_16x16x32_bf16 v[80:83], v[158:161], v[190:193], v[80:83]
	v_mfma_f32_16x16x32_bf16 v[124:127], v[154:157], v[170:173], v[124:127]
	v_mfma_f32_16x16x32_bf16 v[120:123], v[162:165], v[170:173], v[120:123]
	v_mfma_f32_16x16x32_bf16 v[116:119], v[154:157], v[178:181], v[116:119]
	v_mfma_f32_16x16x32_bf16 v[112:115], v[162:165], v[178:181], v[112:115]
	v_mfma_f32_16x16x32_bf16 v[104:107], v[154:157], v[186:189], v[104:107]
	v_mfma_f32_16x16x32_bf16 v[96:99], v[162:165], v[186:189], v[96:99]
	v_mfma_f32_16x16x32_bf16 v[88:91], v[154:157], v[194:197], v[88:91]
	v_mfma_f32_16x16x32_bf16 v[80:83], v[162:165], v[194:197], v[80:83]
	s_setprio 0
	s_barrier
	s_add_i32 s68, 0, 0x1c000
	s_add_i32 s62, s83, s50
	v_add_u32_e32 v210, s68, v146
	v_lshl_add_u64 v[144:145], v[144:145], 0, s[16:17]
	s_mov_b32 m0, s62
	ds_read_b128 v[198:201], v210
	ds_read_b128 v[202:205], v210 offset:1024
	ds_read_b128 v[206:209], v210 offset:2048
	ds_read_b128 v[210:213], v210 offset:3072
	global_load_lds_dwordx4 v[144:145], off
	v_lshl_add_u64 v[144:145], v[214:215], 0, s[16:17]
	s_add_i32 m0, s62, 0x2000
	s_nop 0
	global_load_lds_dwordx4 v[144:145], off
	s_barrier
	s_waitcnt lgkmcnt(0)
	s_setprio 1
	s_waitcnt lgkmcnt(0)
	v_mfma_f32_16x16x32_bf16 v[108:111], v[198:201], v[166:169], v[108:111]
	v_mfma_f32_16x16x32_bf16 v[100:103], v[206:209], v[166:169], v[100:103]
	v_mfma_f32_16x16x32_bf16 v[92:95], v[198:201], v[174:177], v[92:95]
	v_mfma_f32_16x16x32_bf16 v[84:87], v[206:209], v[174:177], v[84:87]
	v_mfma_f32_16x16x32_bf16 v[76:79], v[198:201], v[182:185], v[76:79]
	v_mfma_f32_16x16x32_bf16 v[72:75], v[206:209], v[182:185], v[72:75]
	v_mfma_f32_16x16x32_bf16 v[68:71], v[198:201], v[190:193], v[68:71]
	v_mfma_f32_16x16x32_bf16 v[64:67], v[206:209], v[190:193], v[64:67]
	v_mfma_f32_16x16x32_bf16 v[108:111], v[202:205], v[170:173], v[108:111]
	v_mfma_f32_16x16x32_bf16 v[100:103], v[210:213], v[170:173], v[100:103]
	v_mfma_f32_16x16x32_bf16 v[92:95], v[202:205], v[178:181], v[92:95]
	v_mfma_f32_16x16x32_bf16 v[84:87], v[210:213], v[178:181], v[84:87]
	v_mfma_f32_16x16x32_bf16 v[76:79], v[202:205], v[186:189], v[76:79]
	v_mfma_f32_16x16x32_bf16 v[72:75], v[210:213], v[186:189], v[72:75]
	v_mfma_f32_16x16x32_bf16 v[68:71], v[202:205], v[194:197], v[68:71]
	v_mfma_f32_16x16x32_bf16 v[64:67], v[210:213], v[194:197], v[64:67]
	s_setprio 0
	s_mov_b32 m0, s55
	v_lshl_add_u64 v[144:145], v[216:217], 0, s[16:17]
	s_barrier
	ds_read_b128 v[166:169], v148 offset:49152
	ds_read_b128 v[170:173], v148 offset:50176
	ds_read_b128 v[174:177], v148 offset:51200
	ds_read_b128 v[178:181], v148 offset:52224
	ds_read_b128 v[182:185], v148 offset:53248
	ds_read_b128 v[186:189], v148 offset:54272
	ds_read_b128 v[190:193], v148 offset:55296
	ds_read_b128 v[194:197], v148 offset:56320
	global_load_lds_dwordx4 v[144:145], off
	v_lshl_add_u64 v[144:145], v[218:219], 0, s[16:17]
	s_mov_b32 m0, s58
	s_nop 0
	global_load_lds_dwordx4 v[144:145], off
	s_barrier
;     DI void operator()(const AccT& acc, const Unit& u, int wr, int wc, int fr, int fq) const {
; #pragma unroll
;         for (int ai = 0; ai < 2; ++ai) {
;             f32x4 h[4][2][2];
;             float* base = H + ((size_t)u.pm * 256 + ai * 128 + wr * 64 + fr) * 1024 + u.pn * 256 + wc * 32 + 4 * fq;
; #pragma unroll
;             for (int m = 0; m < 4; ++m)
; #pragma unroll
;                 for (int bj = 0; bj < 2; ++bj)
; #pragma unroll
;                     for (int n = 0; n < 2; ++n) h[m][bj][n] = *(const f32x4*)(base + (size_t)m * 16 * 1024 + bj * 128 + n * 16);
;             __builtin_amdgcn_sched_barrier(0);
; #pragma unroll
;             for (int m = 0; m < 4; ++m)
; #pragma unroll
;                 for (int bj = 0; bj < 2; ++bj)
; #pragma unroll
;                     for (int n = 0; n < 2; ++n) *(f32x4*)(base + (size_t)m * 16 * 1024 + bj * 128 + n * 16) = h[m][bj][n] + acc[ai][bj][m][n] * alpha;
;         }
	s_waitcnt lgkmcnt(0)
	s_setprio 1
	s_waitcnt lgkmcnt(0)
	v_mfma_f32_16x16x32_bf16 v[60:63], v[150:153], v[166:169], v[60:63]
	v_mfma_f32_16x16x32_bf16 v[56:59], v[158:161], v[166:169], v[56:59]
	v_mfma_f32_16x16x32_bf16 v[52:55], v[150:153], v[174:177], v[52:55]
	v_mfma_f32_16x16x32_bf16 v[44:47], v[158:161], v[174:177], v[44:47]
	v_mfma_f32_16x16x32_bf16 v[36:39], v[150:153], v[182:185], v[36:39]
	v_mfma_f32_16x16x32_bf16 v[28:31], v[158:161], v[182:185], v[28:31]
	v_mfma_f32_16x16x32_bf16 v[20:23], v[150:153], v[190:193], v[20:23]
	v_mfma_f32_16x16x32_bf16 v[12:15], v[158:161], v[190:193], v[12:15]
	v_mfma_f32_16x16x32_bf16 v[60:63], v[154:157], v[170:173], v[60:63]
	v_mfma_f32_16x16x32_bf16 v[56:59], v[162:165], v[170:173], v[56:59]
	v_mfma_f32_16x16x32_bf16 v[52:55], v[154:157], v[178:181], v[52:55]
	v_mfma_f32_16x16x32_bf16 v[44:47], v[162:165], v[178:181], v[44:47]
	v_mfma_f32_16x16x32_bf16 v[36:39], v[154:157], v[186:189], v[36:39]
	v_mfma_f32_16x16x32_bf16 v[28:31], v[162:165], v[186:189], v[28:31]
	v_mfma_f32_16x16x32_bf16 v[20:23], v[154:157], v[194:197], v[20:23]
	v_mfma_f32_16x16x32_bf16 v[12:15], v[162:165], v[194:197], v[12:15]
	s_setprio 0
	s_barrier
	s_add_u32 s62, s66, 0x40080
	s_addc_u32 s63, s67, 0
	s_add_i32 s66, s68, s50
	v_lshl_add_u64 v[144:145], s[62:63], 0, v[128:129]
	s_mov_b32 m0, s66
	s_nop 0
	global_load_lds_dwordx4 v[144:145], off
	v_lshl_add_u64 v[144:145], s[62:63], 0, v[130:131]
	s_add_i32 m0, s66, 0x2000
	s_nop 0
	global_load_lds_dwordx4 v[144:145], off
	s_waitcnt vmcnt(6)
	s_barrier
	s_setprio 1
	v_mfma_f32_16x16x32_bf16 v[48:51], v[198:201], v[166:169], v[48:51]
	v_mfma_f32_16x16x32_bf16 v[40:43], v[206:209], v[166:169], v[40:43]
	v_mfma_f32_16x16x32_bf16 v[32:35], v[198:201], v[174:177], v[32:35]
	v_mfma_f32_16x16x32_bf16 v[24:27], v[206:209], v[174:177], v[24:27]
	v_mfma_f32_16x16x32_bf16 v[16:19], v[198:201], v[182:185], v[16:19]
	v_mfma_f32_16x16x32_bf16 v[8:11], v[206:209], v[182:185], v[8:11]
	v_mfma_f32_16x16x32_bf16 v[4:7], v[198:201], v[190:193], v[4:7]
	v_mfma_f32_16x16x32_bf16 v[0:3], v[206:209], v[190:193], v[0:3]
	v_mfma_f32_16x16x32_bf16 v[48:51], v[202:205], v[170:173], v[48:51]
	v_mfma_f32_16x16x32_bf16 v[40:43], v[210:213], v[170:173], v[40:43]
	v_mfma_f32_16x16x32_bf16 v[32:35], v[202:205], v[178:181], v[32:35]
	v_mfma_f32_16x16x32_bf16 v[24:27], v[210:213], v[178:181], v[24:27]
	v_mfma_f32_16x16x32_bf16 v[16:19], v[202:205], v[186:189], v[16:19]
	v_mfma_f32_16x16x32_bf16 v[8:11], v[210:213], v[186:189], v[8:11]
	v_mfma_f32_16x16x32_bf16 v[4:7], v[202:205], v[194:197], v[4:7]
	v_mfma_f32_16x16x32_bf16 v[0:3], v[210:213], v[194:197], v[0:3]
	s_setprio 0
	s_add_i32 s82, s82, 2
	s_add_u32 s80, s80, 0x100
	s_addc_u32 s81, s81, 0
	s_cmp_gt_u32 s82, 13
	s_mov_b64 s[62:63], s[64:65]
	s_barrier
	s_cbranch_scc0 .LBB0_1374
	s_ashr_i32 s61, s60, 31
	s_lshl_b32 s62, s78, 8
	s_lshl_b64 s[60:61], s[60:61], 20
	s_ashr_i32 s63, s62, 31
	s_mov_b32 s21, 0x10000
	s_mov_b32 s100, 0x20000
	s_mov_b32 s101, 0
	v_lshl_add_u64 v[214:215], v[252:253], 0, s[100:101]
	global_load_dwordx4 v[150:153], v[214:215], off
	global_load_dwordx4 v[154:157], v[214:215], off offset:64
	global_load_dwordx4 v[158:161], v[214:215], off offset:512
	global_load_dwordx4 v[162:165], v[214:215], off offset:576
	s_mov_b32 s100, 0x30000
	s_mov_b32 s101, 0
	v_lshl_add_u64 v[216:217], v[252:253], 0, s[100:101]
	global_load_dwordx4 v[166:169], v[216:217], off
	global_load_dwordx4 v[170:173], v[216:217], off offset:64
	global_load_dwordx4 v[174:177], v[216:217], off offset:512
	global_load_dwordx4 v[178:181], v[216:217], off offset:576
	s_mov_b32 s100, 0x80000
	s_mov_b32 s101, 0
	v_lshl_add_u64 v[214:215], v[252:253], 0, s[100:101]
	global_load_dwordx4 v[182:185], v[214:215], off
	global_load_dwordx4 v[186:189], v[214:215], off offset:64
	global_load_dwordx4 v[190:193], v[214:215], off offset:512
	global_load_dwordx4 v[194:197], v[214:215], off offset:576
	s_mov_b32 s100, 0x90000
	s_mov_b32 s101, 0
	v_lshl_add_u64 v[216:217], v[252:253], 0, s[100:101]
	global_load_dwordx4 v[198:201], v[216:217], off
	global_load_dwordx4 v[202:205], v[216:217], off offset:64
	global_load_dwordx4 v[206:209], v[216:217], off offset:512
	global_load_dwordx4 v[210:213], v[216:217], off offset:576
	s_waitcnt vmcnt(16)
	v_pk_add_f32 v[124:125], v[124:125], v[220:221]
	v_pk_add_f32 v[126:127], v[126:127], v[222:223]
	v_pk_add_f32 v[120:121], v[120:121], v[224:225]
	v_pk_add_f32 v[122:123], v[122:123], v[226:227]
	v_pk_add_f32 v[108:109], v[108:109], v[228:229]
	v_pk_add_f32 v[110:111], v[110:111], v[230:231]
	v_pk_add_f32 v[100:101], v[100:101], v[232:233]
	v_pk_add_f32 v[102:103], v[102:103], v[234:235]
	v_pk_add_f32 v[116:117], v[116:117], v[236:237]
	v_pk_add_f32 v[118:119], v[118:119], v[238:239]
	v_pk_add_f32 v[112:113], v[112:113], v[240:241]
	v_pk_add_f32 v[114:115], v[114:115], v[242:243]
	v_pk_add_f32 v[92:93], v[92:93], v[244:245]
	v_pk_add_f32 v[94:95], v[94:95], v[246:247]
	v_pk_add_f32 v[84:85], v[84:85], v[248:249]
	v_pk_add_f32 v[86:87], v[86:87], v[250:251]
	s_mov_b32 s100, 0x0
	s_mov_b32 s101, 0
	v_lshl_add_u64 v[216:217], v[252:253], 0, s[100:101]
	global_store_dwordx4 v[216:217], v[124:127], off
	global_store_dwordx4 v[216:217], v[120:123], off offset:64
	global_store_dwordx4 v[216:217], v[108:111], off offset:512
	global_store_dwordx4 v[216:217], v[100:103], off offset:576
	s_mov_b32 s100, 0x10000
	s_mov_b32 s101, 0
	v_lshl_add_u64 v[218:219], v[252:253], 0, s[100:101]
	global_store_dwordx4 v[218:219], v[116:119], off
	global_store_dwordx4 v[218:219], v[112:115], off offset:64
	global_store_dwordx4 v[218:219], v[92:95], off offset:512
	global_store_dwordx4 v[218:219], v[84:87], off offset:576
	s_mov_b32 s100, 0xa0000
	s_mov_b32 s101, 0
	v_lshl_add_u64 v[214:215], v[252:253], 0, s[100:101]
	global_load_dwordx4 v[220:223], v[214:215], off
	global_load_dwordx4 v[224:227], v[214:215], off offset:64
	global_load_dwordx4 v[228:231], v[214:215], off offset:512
	global_load_dwordx4 v[232:235], v[214:215], off offset:576
	s_mov_b32 s100, 0xb0000
	s_mov_b32 s101, 0
	v_lshl_add_u64 v[216:217], v[252:253], 0, s[100:101]
	global_load_dwordx4 v[236:239], v[216:217], off
	global_load_dwordx4 v[240:243], v[216:217], off offset:64
	global_load_dwordx4 v[244:247], v[216:217], off offset:512
	global_load_dwordx4 v[248:251], v[216:217], off offset:576
	s_waitcnt vmcnt(24)
; #define PG8_WAIT_V(n) asm volatile("s_waitcnt vmcnt(" #n ")" ::: "memory")
; #define PG8_BAR __builtin_amdgcn_s_barrier()
; template <class Epi>
; DI void gemm_phase(int wv, LAS unsigned char* lds, const Gemm g, const StaticOrder& S, const Epi& E) {
;     ...
;         if (!has_next) break;
; #pragma unroll
;         for (int a = 0; a < 2; ++a)
; #pragma unroll
;             for (int b = 0; b < 2; ++b)
; #pragma unroll
;                 for (int m = 0; m < 4; ++m)
; #pragma unroll
;                     for (int n = 0; n < 2; ++n) acc[a][b][m][n] = (f32x4){0.f, 0.f, 0.f, 0.f};
;         cur = nxt; cA = nA; cB = nB; ++ui;
;     }
;     PG8_WAIT_V(0);
;     if (wr == 0) PG8_BAR;
;     PG8_BAR;
;     DI void operator()(const AccT& acc, const Unit& u, int wr, int wc, int fr, int fq) const {
; #pragma unroll
;         for (int ai = 0; ai < 2; ++ai) {
;             f32x4 h[4][2][2];
;             float* base = H + ((size_t)u.pm * 256 + ai * 128 + wr * 64 + fr) * 1024 + u.pn * 256 + wc * 32 + 4 * fq;
; #pragma unroll
;             for (int m = 0; m < 4; ++m)
; #pragma unroll
;                 for (int bj = 0; bj < 2; ++bj)
; #pragma unroll
;                     for (int n = 0; n < 2; ++n) h[m][bj][n] = *(const f32x4*)(base + (size_t)m * 16 * 1024 + bj * 128 + n * 16);
;             __builtin_amdgcn_sched_barrier(0);
; #pragma unroll
;             for (int m = 0; m < 4; ++m)
; #pragma unroll
;                 for (int bj = 0; bj < 2; ++bj)
; #pragma unroll
;                     for (int n = 0; n < 2; ++n) *(f32x4*)(base + (size_t)m * 16 * 1024 + bj * 128 + n * 16) = h[m][bj][n] + acc[ai][bj][m][n] * alpha;
;         }
	v_pk_add_f32 v[104:105], v[104:105], v[150:151]
	v_pk_add_f32 v[106:107], v[106:107], v[152:153]
	v_pk_add_f32 v[96:97], v[96:97], v[154:155]
	v_pk_add_f32 v[98:99], v[98:99], v[156:157]
	v_pk_add_f32 v[76:77], v[76:77], v[158:159]
	v_pk_add_f32 v[78:79], v[78:79], v[160:161]
	v_pk_add_f32 v[72:73], v[72:73], v[162:163]
	v_pk_add_f32 v[74:75], v[74:75], v[164:165]
	v_pk_add_f32 v[88:89], v[88:89], v[166:167]
	v_pk_add_f32 v[90:91], v[90:91], v[168:169]
	v_pk_add_f32 v[80:81], v[80:81], v[170:171]
	v_pk_add_f32 v[82:83], v[82:83], v[172:173]
	v_pk_add_f32 v[68:69], v[68:69], v[174:175]
	v_pk_add_f32 v[70:71], v[70:71], v[176:177]
	v_pk_add_f32 v[64:65], v[64:65], v[178:179]
	v_pk_add_f32 v[66:67], v[66:67], v[180:181]
	s_mov_b32 s100, 0x20000
	s_mov_b32 s101, 0
	v_lshl_add_u64 v[216:217], v[252:253], 0, s[100:101]
	global_store_dwordx4 v[216:217], v[104:107], off
	global_store_dwordx4 v[216:217], v[96:99], off offset:64
	global_store_dwordx4 v[216:217], v[76:79], off offset:512
	global_store_dwordx4 v[216:217], v[72:75], off offset:576
	s_mov_b32 s100, 0x30000
	s_mov_b32 s101, 0
	v_lshl_add_u64 v[218:219], v[252:253], 0, s[100:101]
	global_store_dwordx4 v[218:219], v[88:91], off
	global_store_dwordx4 v[218:219], v[80:83], off offset:64
	global_store_dwordx4 v[218:219], v[68:71], off offset:512
	global_store_dwordx4 v[218:219], v[64:67], off offset:576
	s_waitcnt vmcnt(24)
	v_pk_add_f32 v[60:61], v[60:61], v[182:183]
	v_pk_add_f32 v[62:63], v[62:63], v[184:185]
	v_pk_add_f32 v[56:57], v[56:57], v[186:187]
	v_pk_add_f32 v[58:59], v[58:59], v[188:189]
	v_pk_add_f32 v[48:49], v[48:49], v[190:191]
	v_pk_add_f32 v[50:51], v[50:51], v[192:193]
	v_pk_add_f32 v[40:41], v[40:41], v[194:195]
	v_pk_add_f32 v[42:43], v[42:43], v[196:197]
	v_pk_add_f32 v[52:53], v[52:53], v[198:199]
	v_pk_add_f32 v[54:55], v[54:55], v[200:201]
	v_pk_add_f32 v[44:45], v[44:45], v[202:203]
	v_pk_add_f32 v[46:47], v[46:47], v[204:205]
	v_pk_add_f32 v[32:33], v[32:33], v[206:207]
	v_pk_add_f32 v[34:35], v[34:35], v[208:209]
	v_pk_add_f32 v[24:25], v[24:25], v[210:211]
	v_pk_add_f32 v[26:27], v[26:27], v[212:213]
	s_mov_b32 s100, 0x80000
	s_mov_b32 s101, 0
	v_lshl_add_u64 v[216:217], v[252:253], 0, s[100:101]
	global_store_dwordx4 v[216:217], v[60:63], off
	global_store_dwordx4 v[216:217], v[56:59], off offset:64
	global_store_dwordx4 v[216:217], v[48:51], off offset:512
	global_store_dwordx4 v[216:217], v[40:43], off offset:576
	s_mov_b32 s100, 0x90000
	s_mov_b32 s101, 0
	v_lshl_add_u64 v[218:219], v[252:253], 0, s[100:101]
	global_store_dwordx4 v[218:219], v[52:55], off
	global_store_dwordx4 v[218:219], v[44:47], off offset:64
	global_store_dwordx4 v[218:219], v[32:35], off offset:512
	global_store_dwordx4 v[218:219], v[24:27], off offset:576
	s_waitcnt vmcnt(16)
	v_pk_add_f32 v[36:37], v[36:37], v[220:221]
	v_pk_add_f32 v[38:39], v[38:39], v[222:223]
	v_pk_add_f32 v[28:29], v[28:29], v[224:225]
	v_pk_add_f32 v[30:31], v[30:31], v[226:227]
	v_pk_add_f32 v[16:17], v[16:17], v[228:229]
	v_pk_add_f32 v[18:19], v[18:19], v[230:231]
	v_pk_add_f32 v[8:9], v[8:9], v[232:233]
	v_pk_add_f32 v[10:11], v[10:11], v[234:235]
	v_pk_add_f32 v[20:21], v[20:21], v[236:237]
	v_pk_add_f32 v[22:23], v[22:23], v[238:239]
	v_pk_add_f32 v[12:13], v[12:13], v[240:241]
	v_pk_add_f32 v[14:15], v[14:15], v[242:243]
	v_pk_add_f32 v[4:5], v[4:5], v[244:245]
	v_pk_add_f32 v[6:7], v[6:7], v[246:247]
	v_pk_add_f32 v[0:1], v[0:1], v[248:249]
	v_pk_add_f32 v[2:3], v[2:3], v[250:251]
	s_mov_b32 s100, 0xa0000
	s_mov_b32 s101, 0
	v_lshl_add_u64 v[216:217], v[252:253], 0, s[100:101]
	global_store_dwordx4 v[216:217], v[36:39], off
	global_store_dwordx4 v[216:217], v[28:31], off offset:64
	global_store_dwordx4 v[216:217], v[16:19], off offset:512
	global_store_dwordx4 v[216:217], v[8:11], off offset:576
	s_mov_b32 s100, 0xb0000
	s_mov_b32 s101, 0
	v_lshl_add_u64 v[218:219], v[252:253], 0, s[100:101]
	global_store_dwordx4 v[218:219], v[20:23], off
	global_store_dwordx4 v[218:219], v[12:15], off offset:64
	global_store_dwordx4 v[218:219], v[4:7], off offset:512
	global_store_dwordx4 v[218:219], v[0:3], off offset:576
	s_and_b64 vcc, exec, s[12:13]
	s_mov_b32 s78, s20
	s_mov_b32 s60, s28
	s_mov_b64 s[64:65], s[38:39]
	s_mov_b64 s[62:63], s[30:31]
	s_cbranch_vccz .LBB0_1367
	s_waitcnt vmcnt(0)
	s_cmpk_gt_u32 s8, 0xff
	s_cbranch_scc1 .LBB0_1378
	s_barrier

;     DI bool next(int i, Unit& u) const {
;         const long L = (long)i * G + c; if (L >= nwg) return false;
;         int wgid = (int)L; { const int q = nwg / NXCD, r = nwg % NXCD, xcd = wgid % NXCD, off = wgid / NXCD; wgid = (xcd < r ? xcd * (q + 1) : r * (q + 1) + (xcd - r) * q) + off; }
;         const int nig = WGM * nN, gid = wgid / nig, fm = gid * WGM, gsz = (nM - fm) < WGM ? (nM - fm) : WGM;
;         u.pm = fm + ((wgid % nig) % gsz); u.pn = (wgid % nig) / gsz; return true;
;     }
;     DI void operator()(const AccT& acc, const Unit& u, int wr, int wc, int fr, int fq) const {
; #pragma unroll
;         for (int ai = 0; ai < 2; ++ai) {
;             f32x4 h[4][2][2];
;             float* base = H + ((size_t)u.pm * 256 + ai * 128 + wr * 64 + fr) * 1024 + u.pn * 256 + wc * 32 + 4 * fq;
; #pragma unroll
;             for (int m = 0; m < 4; ++m)
; #pragma unroll
;                 for (int bj = 0; bj < 2; ++bj)
; #pragma unroll
;                     for (int n = 0; n < 2; ++n) h[m][bj][n] = *(const f32x4*)(base + (size_t)m * 16 * 1024 + bj * 128 + n * 16);
.LBB0_1595:
	s_mov_b32 s98, s30
	s_ashr_i32 s99, s30, 31
	s_lshl_b64 s[98:99], s[98:99], 20
	s_lshl_b32 s100, s73, 8
	s_ashr_i32 s101, s100, 31
	v_lshl_add_u64 v[252:253], v[134:135], 0, s[98:99]
	v_lshl_add_u64 v[252:253], s[100:101], 2, v[252:253]
	v_lshl_add_u64 v[252:253], v[252:253], 0, s[24:25]
	v_lshl_add_u64 v[252:253], v[252:253], 0, v[132:133]
	global_load_dwordx4 v[220:223], v[252:253], off
	global_load_dwordx4 v[224:227], v[252:253], off offset:64
	global_load_dwordx4 v[228:231], v[252:253], off offset:512
	global_load_dwordx4 v[232:235], v[252:253], off offset:576
	s_mov_b32 s100, 0x10000
	s_mov_b32 s101, 0
	v_lshl_add_u64 v[252:253], v[252:253], 0, s[100:101]
	global_load_dwordx4 v[236:239], v[252:253], off
	global_load_dwordx4 v[240:243], v[252:253], off offset:64
	global_load_dwordx4 v[244:247], v[252:253], off offset:512
	global_load_dwordx4 v[248:251], v[252:253], off offset:576
	s_mov_b32 s100, 0xffff0000
	s_mov_b32 s101, -1
	v_lshl_add_u64 v[252:253], v[252:253], 0, s[100:101]
	s_add_i32 s70, s70, 1
	s_mul_i32 s16, s70, s45
	s_mul_hi_u32 s17, s70, s44
	s_add_i32 s17, s17, s16
	s_mul_i32 s16, s70, s44
	s_add_u32 s20, s16, s2
	s_addc_u32 s21, s17, s3
	v_cmp_gt_i64_e64 s[16:17], s[20:21], v[142:143]
	v_cmp_lt_i64_e64 s[18:19], s[20:21], v[140:141]
	s_and_b64 vcc, exec, s[16:17]
	s_cbranch_vccnz .LBB0_1601
	s_ashr_i32 s21, s20, 31
	s_lshr_b32 s21, s21, 29
	s_add_i32 s31, s20, s21
	s_and_b32 s21, s31, -8
	s_sub_i32 s56, s20, s21
	s_cmp_gt_i32 s56, 3
	s_mov_b64 s[20:21], -1
	s_cbranch_scc0 .LBB0_1598
	s_mul_i32 s20, s56, 0xa1
	s_add_i32 s57, s20, 4
	s_mov_b64 s[20:21], 0

; #define PG8_STAGE(bufoff, gbase, voff) do { _Pragma("unroll") for (int _i = 0; _i < 2; ++_i) \
;         __builtin_amdgcn_global_load_lds((const unsigned*)((const char*)(gbase) + (voff)[_i]), (LAS unsigned*)(lds + (bufoff) + ldsw + _i * 8192), 16, 0, 0); } while (0)
; #define PG8_LDA(dst, b, h) do { _Pragma("unroll") for (int m = 0; m < 4; ++m) _Pragma("unroll") for (int k = 0; k < 2; ++k) dst[m][k] = *(const LAS bf16x8*)(lds + PG8_SA(b, h) + aoff + m * 2048 + k * 1024); } while (0)
; #define PG8_LDB(dst, b, h) do { _Pragma("unroll") for (int n = 0; n < 2; ++n) _Pragma("unroll") for (int k = 0; k < 2; ++k) dst[n][k] = *(const LAS bf16x8*)(lds + PG8_SB(b, h) + boff + n * 2048 + k * 1024); } while (0)
; #define PG8_MMA(ai, bj, At, Bt) do { __builtin_amdgcn_s_setprio(1); _Pragma("unroll") for (int m = 0; m < 4; ++m) _Pragma("unroll") for (int n = 0; n < 2; ++n) _Pragma("unroll") for (int k = 0; k < 2; ++k) \
;         acc[ai][bj][m][n] = __builtin_amdgcn_mfma_f32_16x16x32_bf16(Bt[n][k], At[m][k], acc[ai][bj][m][n], 0, 0, 0); __builtin_amdgcn_s_setprio(0); } while (0)
; #define PG8_WAIT_V(n) asm volatile("s_waitcnt vmcnt(" #n ")" ::: "memory")
; #define PG8_WAIT_L(n) asm volatile("s_waitcnt lgkmcnt(" #n ")" ::: "memory")
; #define PG8_BAR __builtin_amdgcn_s_barrier()
; #define PG8_SCHED __builtin_amdgcn_sched_barrier(0)
; template <class Epi>
; DI void gemm_phase(int wv, LAS unsigned char* lds, const Gemm g, const StaticOrder& S, const Epi& E) {
;     ...
;             PG8_LDB(B0, 0, 0); PG8_SCHED; PG8_LDA(At, 0, 0); PG8_STAGE(PG8_SA(1, 1), a1 + hstep, voffA);
;             PG8_WAIT_L(8); PG8_BAR; PG8_WAIT_L(0); PG8_MMA(0, 0, At, B0); PG8_BAR; PG8_SCHED;
;             PG8_LDB(B1, 0, 1); PG8_STAGE(PG8_SB(0, 0), b2, voffB);
;             PG8_BAR; PG8_WAIT_L(0); PG8_MMA(0, 1, At, B1); PG8_BAR;
;             PG8_LDA(At, 0, 1); PG8_STAGE(PG8_SA(0, 0), a2, voffA);
;             PG8_BAR; PG8_WAIT_L(0); PG8_MMA(1, 0, At, B0); PG8_BAR; PG8_SCHED;
;             PG8_STAGE(PG8_SB(0, 1), b2 + hstep, voffB);
;             PG8_WAIT_V(6); PG8_BAR; PG8_MMA(1, 1, At, B1); PG8_BAR;
;             PG8_LDB(B0, 1, 0); PG8_SCHED; PG8_LDA(At, 1, 0); PG8_STAGE(PG8_SA(0, 1), a2 + hstep, voffA);
;             PG8_WAIT_L(8); PG8_BAR; PG8_WAIT_L(0); PG8_MMA(0, 0, At, B0); PG8_BAR; PG8_SCHED;
.LBB0_1606:
	ds_read_b128 v[150:153], v147
	ds_read_b128 v[154:157], v147 offset:1024
	ds_read_b128 v[158:161], v147 offset:2048
	ds_read_b128 v[162:165], v147 offset:3072
	s_add_u32 s54, s38, 0x100
	s_addc_u32 s55, s39, 0
	s_cmp_eq_u32 s75, 40
	s_cselect_b32 s59, s19, s55
	s_cselect_b32 s58, s18, s54
	s_cselect_b32 s57, s21, s74
	s_cselect_b32 s56, s20, s31
	v_lshl_add_u64 v[144:145], s[38:39], 0, v[136:137]
	s_add_i32 m0, s41, 0xc000
	ds_read_b128 v[166:169], v148
	ds_read_b128 v[170:173], v148 offset:1024
	ds_read_b128 v[174:177], v148 offset:2048
	ds_read_b128 v[178:181], v148 offset:3072
	ds_read_b128 v[182:185], v148 offset:4096
	ds_read_b128 v[186:189], v148 offset:5120
	ds_read_b128 v[190:193], v148 offset:6144
	ds_read_b128 v[194:197], v148 offset:7168
	global_load_lds_dwordx4 v[144:145], off
	v_lshl_add_u64 v[144:145], s[38:39], 0, v[138:139]
	s_add_i32 m0, s41, 0xe000
	s_nop 0
	global_load_lds_dwordx4 v[144:145], off
	s_waitcnt lgkmcnt(8)
	s_barrier
	s_waitcnt lgkmcnt(0)
	s_setprio 1
	s_waitcnt lgkmcnt(0)
	v_mfma_f32_16x16x32_bf16 v[124:127], v[150:153], v[166:169], v[124:127]
	v_mfma_f32_16x16x32_bf16 v[120:123], v[158:161], v[166:169], v[120:123]
	v_mfma_f32_16x16x32_bf16 v[116:119], v[150:153], v[174:177], v[116:119]
	v_mfma_f32_16x16x32_bf16 v[112:115], v[158:161], v[174:177], v[112:115]
	v_mfma_f32_16x16x32_bf16 v[104:107], v[150:153], v[182:185], v[104:107]
	v_mfma_f32_16x16x32_bf16 v[96:99], v[158:161], v[182:185], v[96:99]
	v_mfma_f32_16x16x32_bf16 v[88:91], v[150:153], v[190:193], v[88:91]
	v_mfma_f32_16x16x32_bf16 v[80:83], v[158:161], v[190:193], v[80:83]
	v_mfma_f32_16x16x32_bf16 v[124:127], v[154:157], v[170:173], v[124:127]
	v_mfma_f32_16x16x32_bf16 v[120:123], v[162:165], v[170:173], v[120:123]
	v_mfma_f32_16x16x32_bf16 v[116:119], v[154:157], v[178:181], v[116:119]
	v_mfma_f32_16x16x32_bf16 v[112:115], v[162:165], v[178:181], v[112:115]
	v_mfma_f32_16x16x32_bf16 v[104:107], v[154:157], v[186:189], v[104:107]
	v_mfma_f32_16x16x32_bf16 v[96:99], v[162:165], v[186:189], v[96:99]
	v_mfma_f32_16x16x32_bf16 v[88:91], v[154:157], v[194:197], v[88:91]
	v_mfma_f32_16x16x32_bf16 v[80:83], v[162:165], v[194:197], v[80:83]
	s_setprio 0
	s_barrier
	s_add_i32 s38, s62, s11
	v_lshl_add_u64 v[144:145], s[56:57], 0, v[128:129]
	s_mov_b32 m0, s38
	ds_read_b128 v[198:201], v149
	ds_read_b128 v[202:205], v149 offset:1024
	ds_read_b128 v[206:209], v149 offset:2048
	ds_read_b128 v[210:213], v149 offset:3072
	global_load_lds_dwordx4 v[144:145], off
	v_lshl_add_u64 v[214:215], s[56:57], 0, v[130:131]
	s_add_i32 m0, s38, 0x2000
	s_nop 0
	global_load_lds_dwordx4 v[214:215], off
	s_barrier
	s_waitcnt lgkmcnt(0)
	s_setprio 1
	s_waitcnt lgkmcnt(0)
	v_mfma_f32_16x16x32_bf16 v[108:111], v[198:201], v[166:169], v[108:111]
	v_mfma_f32_16x16x32_bf16 v[100:103], v[206:209], v[166:169], v[100:103]
	v_mfma_f32_16x16x32_bf16 v[92:95], v[198:201], v[174:177], v[92:95]
	v_mfma_f32_16x16x32_bf16 v[84:87], v[206:209], v[174:177], v[84:87]
	v_mfma_f32_16x16x32_bf16 v[76:79], v[198:201], v[182:185], v[76:79]
	v_mfma_f32_16x16x32_bf16 v[72:75], v[206:209], v[182:185], v[72:75]
	v_mfma_f32_16x16x32_bf16 v[68:71], v[198:201], v[190:193], v[68:71]
	v_mfma_f32_16x16x32_bf16 v[64:67], v[206:209], v[190:193], v[64:67]
	v_mfma_f32_16x16x32_bf16 v[108:111], v[202:205], v[170:173], v[108:111]
	v_mfma_f32_16x16x32_bf16 v[100:103], v[210:213], v[170:173], v[100:103]
	v_mfma_f32_16x16x32_bf16 v[92:95], v[202:205], v[178:181], v[92:95]
	v_mfma_f32_16x16x32_bf16 v[84:87], v[210:213], v[178:181], v[84:87]
	v_mfma_f32_16x16x32_bf16 v[76:79], v[202:205], v[186:189], v[76:79]
	v_mfma_f32_16x16x32_bf16 v[72:75], v[210:213], v[186:189], v[72:75]
	v_mfma_f32_16x16x32_bf16 v[68:71], v[202:205], v[194:197], v[68:71]
	v_mfma_f32_16x16x32_bf16 v[64:67], v[210:213], v[194:197], v[64:67]
	s_setprio 0
	s_mov_b32 m0, s41
	v_lshl_add_u64 v[216:217], s[58:59], 0, v[128:129]
	s_barrier
	ds_read_b128 v[166:169], v148 offset:16384
	ds_read_b128 v[170:173], v148 offset:17408
	ds_read_b128 v[174:177], v148 offset:18432
	ds_read_b128 v[178:181], v148 offset:19456
	ds_read_b128 v[182:185], v148 offset:20480
	ds_read_b128 v[186:189], v148 offset:21504
	ds_read_b128 v[190:193], v148 offset:22528
	ds_read_b128 v[194:197], v148 offset:23552
	global_load_lds_dwordx4 v[216:217], off
	v_lshl_add_u64 v[218:219], s[58:59], 0, v[130:131]
	s_mov_b32 m0, s50
	s_nop 0
	global_load_lds_dwordx4 v[218:219], off
	s_barrier
	s_waitcnt lgkmcnt(0)
	s_setprio 1
	s_waitcnt lgkmcnt(0)
	v_mfma_f32_16x16x32_bf16 v[60:63], v[150:153], v[166:169], v[60:63]
	v_mfma_f32_16x16x32_bf16 v[56:59], v[158:161], v[166:169], v[56:59]
	v_mfma_f32_16x16x32_bf16 v[52:55], v[150:153], v[174:177], v[52:55]
	v_mfma_f32_16x16x32_bf16 v[44:47], v[158:161], v[174:177], v[44:47]
	v_mfma_f32_16x16x32_bf16 v[36:39], v[150:153], v[182:185], v[36:39]
	v_mfma_f32_16x16x32_bf16 v[28:31], v[158:161], v[182:185], v[28:31]
	v_mfma_f32_16x16x32_bf16 v[20:23], v[150:153], v[190:193], v[20:23]
	v_mfma_f32_16x16x32_bf16 v[12:15], v[158:161], v[190:193], v[12:15]
	v_mfma_f32_16x16x32_bf16 v[60:63], v[154:157], v[170:173], v[60:63]
	v_mfma_f32_16x16x32_bf16 v[56:59], v[162:165], v[170:173], v[56:59]
	v_mfma_f32_16x16x32_bf16 v[52:55], v[154:157], v[178:181], v[52:55]
	v_mfma_f32_16x16x32_bf16 v[44:47], v[162:165], v[178:181], v[44:47]
	v_mfma_f32_16x16x32_bf16 v[36:39], v[154:157], v[186:189], v[36:39]
	v_mfma_f32_16x16x32_bf16 v[28:31], v[162:165], v[186:189], v[28:31]
	v_mfma_f32_16x16x32_bf16 v[20:23], v[154:157], v[194:197], v[20:23]
	v_mfma_f32_16x16x32_bf16 v[12:15], v[162:165], v[194:197], v[12:15]
	s_setprio 0
	s_barrier
; #define PG8_STAGE(bufoff, gbase, voff) do { _Pragma("unroll") for (int _i = 0; _i < 2; ++_i) \
;         __builtin_amdgcn_global_load_lds((const unsigned*)((const char*)(gbase) + (voff)[_i]), (LAS unsigned*)(lds + (bufoff) + ldsw + _i * 8192), 16, 0, 0); } while (0)
; #define PG8_LDA(dst, b, h) do { _Pragma("unroll") for (int m = 0; m < 4; ++m) _Pragma("unroll") for (int k = 0; k < 2; ++k) dst[m][k] = *(const LAS bf16x8*)(lds + PG8_SA(b, h) + aoff + m * 2048 + k * 1024); } while (0)
; #define PG8_LDB(dst, b, h) do { _Pragma("unroll") for (int n = 0; n < 2; ++n) _Pragma("unroll") for (int k = 0; k < 2; ++k) dst[n][k] = *(const LAS bf16x8*)(lds + PG8_SB(b, h) + boff + n * 2048 + k * 1024); } while (0)
; #define PG8_MMA(ai, bj, At, Bt) do { __builtin_amdgcn_s_setprio(1); _Pragma("unroll") for (int m = 0; m < 4; ++m) _Pragma("unroll") for (int n = 0; n < 2; ++n) _Pragma("unroll") for (int k = 0; k < 2; ++k) \
;         acc[ai][bj][m][n] = __builtin_amdgcn_mfma_f32_16x16x32_bf16(Bt[n][k], At[m][k], acc[ai][bj][m][n], 0, 0, 0); __builtin_amdgcn_s_setprio(0); } while (0)
; #define PG8_WAIT_V(n) asm volatile("s_waitcnt vmcnt(" #n ")" ::: "memory")
; #define PG8_WAIT_L(n) asm volatile("s_waitcnt lgkmcnt(" #n ")" ::: "memory")
; #define PG8_BAR __builtin_amdgcn_s_barrier()
; #define PG8_SCHED __builtin_amdgcn_sched_barrier(0)
; template <class Epi>
; DI void gemm_phase(int wv, LAS unsigned char* lds, const Gemm g, const StaticOrder& S, const Epi& E) {
;     ...
;             PG8_LDB(B1, 1, 1); PG8_STAGE(PG8_SB(1, 0), b3, voffB);
;             PG8_BAR; PG8_WAIT_L(0); PG8_MMA(0, 1, At, B1); PG8_BAR;
;             PG8_LDA(At, 1, 1); PG8_STAGE(PG8_SA(1, 0), a3, voffA);
;             PG8_BAR; PG8_WAIT_L(0); PG8_MMA(1, 0, At, B0); PG8_BAR; PG8_SCHED;
;             PG8_STAGE(PG8_SB(1, 1), b3 + hstep, voffB);
;             PG8_WAIT_V(6); PG8_BAR; PG8_MMA(1, 1, At, B1); PG8_BAR;
	s_add_u32 s38, s56, 0xb0000
	s_addc_u32 s39, s57, 0
	s_add_i32 s76, s63, s11
	v_lshl_add_u64 v[150:151], s[38:39], 0, v[128:129]
	s_mov_b32 m0, s76
	s_nop 0
	global_load_lds_dwordx4 v[150:151], off
	v_lshl_add_u64 v[150:151], s[38:39], 0, v[130:131]
	s_add_i32 m0, s76, 0x2000
	s_nop 0
	global_load_lds_dwordx4 v[150:151], off
	s_waitcnt vmcnt(6)
	s_barrier
	s_setprio 1
	v_mfma_f32_16x16x32_bf16 v[48:51], v[198:201], v[166:169], v[48:51]
	v_mfma_f32_16x16x32_bf16 v[40:43], v[206:209], v[166:169], v[40:43]
	v_mfma_f32_16x16x32_bf16 v[32:35], v[198:201], v[174:177], v[32:35]
	v_mfma_f32_16x16x32_bf16 v[24:27], v[206:209], v[174:177], v[24:27]
	v_mfma_f32_16x16x32_bf16 v[16:19], v[198:201], v[182:185], v[16:19]
	v_mfma_f32_16x16x32_bf16 v[8:11], v[206:209], v[182:185], v[8:11]
	v_mfma_f32_16x16x32_bf16 v[4:7], v[198:201], v[190:193], v[4:7]
	v_mfma_f32_16x16x32_bf16 v[0:3], v[206:209], v[190:193], v[0:3]
	v_mfma_f32_16x16x32_bf16 v[48:51], v[202:205], v[170:173], v[48:51]
	v_mfma_f32_16x16x32_bf16 v[40:43], v[210:213], v[170:173], v[40:43]
	v_mfma_f32_16x16x32_bf16 v[32:35], v[202:205], v[178:181], v[32:35]
	v_mfma_f32_16x16x32_bf16 v[24:27], v[210:213], v[178:181], v[24:27]
	v_mfma_f32_16x16x32_bf16 v[16:19], v[202:205], v[186:189], v[16:19]
	v_mfma_f32_16x16x32_bf16 v[8:11], v[210:213], v[186:189], v[8:11]
	v_mfma_f32_16x16x32_bf16 v[4:7], v[202:205], v[194:197], v[4:7]
	v_mfma_f32_16x16x32_bf16 v[0:3], v[210:213], v[194:197], v[0:3]
	s_setprio 0
	s_add_i32 s76, 0, 0x18000
	v_add_u32_e32 v162, s76, v146
	s_barrier
	ds_read_b128 v[150:153], v162
	ds_read_b128 v[154:157], v162 offset:1024
	ds_read_b128 v[158:161], v162 offset:2048
	ds_read_b128 v[162:165], v162 offset:3072
	s_add_u32 s38, s58, 0xb0000
	s_addc_u32 s39, s59, 0
	s_mov_b32 m0, s51
	v_lshl_add_u64 v[198:199], s[38:39], 0, v[128:129]
	ds_read_b128 v[166:169], v148 offset:32768
	ds_read_b128 v[170:173], v148 offset:33792
	ds_read_b128 v[174:177], v148 offset:34816
	ds_read_b128 v[178:181], v148 offset:35840
	ds_read_b128 v[182:185], v148 offset:36864
	ds_read_b128 v[186:189], v148 offset:37888
	ds_read_b128 v[190:193], v148 offset:38912
	ds_read_b128 v[194:197], v148 offset:39936
	global_load_lds_dwordx4 v[198:199], off
	v_lshl_add_u64 v[198:199], s[38:39], 0, v[130:131]
	s_mov_b32 m0, s52
	s_nop 0
	global_load_lds_dwordx4 v[198:199], off
	s_waitcnt lgkmcnt(8)
	s_barrier
	s_waitcnt lgkmcnt(0)
	s_setprio 1
	s_waitcnt lgkmcnt(0)
	v_mfma_f32_16x16x32_bf16 v[124:127], v[150:153], v[166:169], v[124:127]
	v_mfma_f32_16x16x32_bf16 v[120:123], v[158:161], v[166:169], v[120:123]
	v_mfma_f32_16x16x32_bf16 v[116:119], v[150:153], v[174:177], v[116:119]
	v_mfma_f32_16x16x32_bf16 v[112:115], v[158:161], v[174:177], v[112:115]
	v_mfma_f32_16x16x32_bf16 v[104:107], v[150:153], v[182:185], v[104:107]
	v_mfma_f32_16x16x32_bf16 v[96:99], v[158:161], v[182:185], v[96:99]
	v_mfma_f32_16x16x32_bf16 v[88:91], v[150:153], v[190:193], v[88:91]
	v_mfma_f32_16x16x32_bf16 v[80:83], v[158:161], v[190:193], v[80:83]
	v_mfma_f32_16x16x32_bf16 v[124:127], v[154:157], v[170:173], v[124:127]
	v_mfma_f32_16x16x32_bf16 v[120:123], v[162:165], v[170:173], v[120:123]
	v_mfma_f32_16x16x32_bf16 v[116:119], v[154:157], v[178:181], v[116:119]
	v_mfma_f32_16x16x32_bf16 v[112:115], v[162:165], v[178:181], v[112:115]
	v_mfma_f32_16x16x32_bf16 v[104:107], v[154:157], v[186:189], v[104:107]
	v_mfma_f32_16x16x32_bf16 v[96:99], v[162:165], v[186:189], v[96:99]
	v_mfma_f32_16x16x32_bf16 v[88:91], v[154:157], v[194:197], v[88:91]
	v_mfma_f32_16x16x32_bf16 v[80:83], v[162:165], v[194:197], v[80:83]
	s_setprio 0
	s_barrier
	s_add_i32 s58, 0, 0x1c000
	s_add_i32 s38, s76, s11
	v_add_u32_e32 v210, s58, v146
	v_lshl_add_u64 v[144:145], v[144:145], 0, s[28:29]
	s_mov_b32 m0, s38
	ds_read_b128 v[198:201], v210
	ds_read_b128 v[202:205], v210 offset:1024
	ds_read_b128 v[206:209], v210 offset:2048
	ds_read_b128 v[210:213], v210 offset:3072
	global_load_lds_dwordx4 v[144:145], off
	v_lshl_add_u64 v[144:145], v[214:215], 0, s[28:29]
	s_add_i32 m0, s38, 0x2000
	s_nop 0
	global_load_lds_dwordx4 v[144:145], off
	s_barrier
	s_waitcnt lgkmcnt(0)
	s_setprio 1
	s_waitcnt lgkmcnt(0)
	v_mfma_f32_16x16x32_bf16 v[108:111], v[198:201], v[166:169], v[108:111]
	v_mfma_f32_16x16x32_bf16 v[100:103], v[206:209], v[166:169], v[100:103]
	v_mfma_f32_16x16x32_bf16 v[92:95], v[198:201], v[174:177], v[92:95]
	v_mfma_f32_16x16x32_bf16 v[84:87], v[206:209], v[174:177], v[84:87]
	v_mfma_f32_16x16x32_bf16 v[76:79], v[198:201], v[182:185], v[76:79]
	v_mfma_f32_16x16x32_bf16 v[72:75], v[206:209], v[182:185], v[72:75]
	v_mfma_f32_16x16x32_bf16 v[68:71], v[198:201], v[190:193], v[68:71]
	v_mfma_f32_16x16x32_bf16 v[64:67], v[206:209], v[190:193], v[64:67]
	v_mfma_f32_16x16x32_bf16 v[108:111], v[202:205], v[170:173], v[108:111]
	v_mfma_f32_16x16x32_bf16 v[100:103], v[210:213], v[170:173], v[100:103]
	v_mfma_f32_16x16x32_bf16 v[92:95], v[202:205], v[178:181], v[92:95]
	v_mfma_f32_16x16x32_bf16 v[84:87], v[210:213], v[178:181], v[84:87]
	v_mfma_f32_16x16x32_bf16 v[76:79], v[202:205], v[186:189], v[76:79]
	v_mfma_f32_16x16x32_bf16 v[72:75], v[210:213], v[186:189], v[72:75]
	v_mfma_f32_16x16x32_bf16 v[68:71], v[202:205], v[194:197], v[68:71]
	v_mfma_f32_16x16x32_bf16 v[64:67], v[210:213], v[194:197], v[64:67]
	s_setprio 0
	s_mov_b32 m0, s60
	v_lshl_add_u64 v[144:145], v[216:217], 0, s[28:29]
	s_barrier
	ds_read_b128 v[166:169], v148 offset:49152
	ds_read_b128 v[170:173], v148 offset:50176
	ds_read_b128 v[174:177], v148 offset:51200
	ds_read_b128 v[178:181], v148 offset:52224
	ds_read_b128 v[182:185], v148 offset:53248
	ds_read_b128 v[186:189], v148 offset:54272
	ds_read_b128 v[190:193], v148 offset:55296
	ds_read_b128 v[194:197], v148 offset:56320
	global_load_lds_dwordx4 v[144:145], off
	v_lshl_add_u64 v[144:145], v[218:219], 0, s[28:29]
	s_mov_b32 m0, s61
	s_nop 0
	global_load_lds_dwordx4 v[144:145], off
	s_barrier
;     DI void operator()(const AccT& acc, const Unit& u, int wr, int wc, int fr, int fq) const {
; #pragma unroll
;         for (int ai = 0; ai < 2; ++ai) {
;             f32x4 h[4][2][2];
;             float* base = H + ((size_t)u.pm * 256 + ai * 128 + wr * 64 + fr) * 1024 + u.pn * 256 + wc * 32 + 4 * fq;
; #pragma unroll
;             for (int m = 0; m < 4; ++m)
; #pragma unroll
;                 for (int bj = 0; bj < 2; ++bj)
; #pragma unroll
;                     for (int n = 0; n < 2; ++n) h[m][bj][n] = *(const f32x4*)(base + (size_t)m * 16 * 1024 + bj * 128 + n * 16);
;             __builtin_amdgcn_sched_barrier(0);
; #pragma unroll
;             for (int m = 0; m < 4; ++m)
; #pragma unroll
;                 for (int bj = 0; bj < 2; ++bj)
; #pragma unroll
;                     for (int n = 0; n < 2; ++n) *(f32x4*)(base + (size_t)m * 16 * 1024 + bj * 128 + n * 16) = h[m][bj][n] + acc[ai][bj][m][n] * alpha;
;         }
	s_waitcnt lgkmcnt(0)
	s_setprio 1
	s_waitcnt lgkmcnt(0)
	v_mfma_f32_16x16x32_bf16 v[60:63], v[150:153], v[166:169], v[60:63]
	v_mfma_f32_16x16x32_bf16 v[56:59], v[158:161], v[166:169], v[56:59]
	v_mfma_f32_16x16x32_bf16 v[52:55], v[150:153], v[174:177], v[52:55]
	v_mfma_f32_16x16x32_bf16 v[44:47], v[158:161], v[174:177], v[44:47]
	v_mfma_f32_16x16x32_bf16 v[36:39], v[150:153], v[182:185], v[36:39]
	v_mfma_f32_16x16x32_bf16 v[28:31], v[158:161], v[182:185], v[28:31]
	v_mfma_f32_16x16x32_bf16 v[20:23], v[150:153], v[190:193], v[20:23]
	v_mfma_f32_16x16x32_bf16 v[12:15], v[158:161], v[190:193], v[12:15]
	v_mfma_f32_16x16x32_bf16 v[60:63], v[154:157], v[170:173], v[60:63]
	v_mfma_f32_16x16x32_bf16 v[56:59], v[162:165], v[170:173], v[56:59]
	v_mfma_f32_16x16x32_bf16 v[52:55], v[154:157], v[178:181], v[52:55]
	v_mfma_f32_16x16x32_bf16 v[44:47], v[162:165], v[178:181], v[44:47]
	v_mfma_f32_16x16x32_bf16 v[36:39], v[154:157], v[186:189], v[36:39]
	v_mfma_f32_16x16x32_bf16 v[28:31], v[162:165], v[186:189], v[28:31]
	v_mfma_f32_16x16x32_bf16 v[20:23], v[154:157], v[194:197], v[20:23]
	v_mfma_f32_16x16x32_bf16 v[12:15], v[162:165], v[194:197], v[12:15]
	s_setprio 0
	s_barrier
	s_add_u32 s38, s56, 0xb0080
	s_addc_u32 s39, s57, 0
	s_add_i32 s56, s58, s11
	v_lshl_add_u64 v[144:145], s[38:39], 0, v[128:129]
	s_mov_b32 m0, s56
	s_nop 0
	global_load_lds_dwordx4 v[144:145], off
	v_lshl_add_u64 v[144:145], s[38:39], 0, v[130:131]
	s_add_i32 m0, s56, 0x2000
	s_nop 0
	global_load_lds_dwordx4 v[144:145], off
	s_waitcnt vmcnt(6)
	s_barrier
	s_setprio 1
	v_mfma_f32_16x16x32_bf16 v[48:51], v[198:201], v[166:169], v[48:51]
	v_mfma_f32_16x16x32_bf16 v[40:43], v[206:209], v[166:169], v[40:43]
	v_mfma_f32_16x16x32_bf16 v[32:35], v[198:201], v[174:177], v[32:35]
	v_mfma_f32_16x16x32_bf16 v[24:27], v[206:209], v[174:177], v[24:27]
	v_mfma_f32_16x16x32_bf16 v[16:19], v[198:201], v[182:185], v[16:19]
	v_mfma_f32_16x16x32_bf16 v[8:11], v[206:209], v[182:185], v[8:11]
	v_mfma_f32_16x16x32_bf16 v[4:7], v[198:201], v[190:193], v[4:7]
	v_mfma_f32_16x16x32_bf16 v[0:3], v[206:209], v[190:193], v[0:3]
	v_mfma_f32_16x16x32_bf16 v[48:51], v[202:205], v[170:173], v[48:51]
	v_mfma_f32_16x16x32_bf16 v[40:43], v[210:213], v[170:173], v[40:43]
	v_mfma_f32_16x16x32_bf16 v[32:35], v[202:205], v[178:181], v[32:35]
	v_mfma_f32_16x16x32_bf16 v[24:27], v[210:213], v[178:181], v[24:27]
	v_mfma_f32_16x16x32_bf16 v[16:19], v[202:205], v[186:189], v[16:19]
	v_mfma_f32_16x16x32_bf16 v[8:11], v[210:213], v[186:189], v[8:11]
	v_mfma_f32_16x16x32_bf16 v[4:7], v[202:205], v[194:197], v[4:7]
	v_mfma_f32_16x16x32_bf16 v[0:3], v[210:213], v[194:197], v[0:3]
	s_setprio 0
	s_add_i32 s75, s75, 2
	s_add_u32 s31, s31, 0x100
	s_addc_u32 s74, s74, 0
	s_cmp_gt_u32 s75, 41
	s_mov_b64 s[38:39], s[54:55]
	s_barrier
	s_cbranch_scc0 .LBB0_1606
	s_ashr_i32 s31, s30, 31
	s_lshl_b32 s38, s73, 8
	s_lshl_b64 s[30:31], s[30:31], 20
	s_ashr_i32 s39, s38, 31
	s_mov_b32 s100, 0x20000
	s_mov_b32 s101, 0
	v_lshl_add_u64 v[214:215], v[252:253], 0, s[100:101]
	global_load_dwordx4 v[150:153], v[214:215], off
	global_load_dwordx4 v[154:157], v[214:215], off offset:64
	global_load_dwordx4 v[158:161], v[214:215], off offset:512
	global_load_dwordx4 v[162:165], v[214:215], off offset:576
	s_mov_b32 s100, 0x30000
	s_mov_b32 s101, 0
	v_lshl_add_u64 v[216:217], v[252:253], 0, s[100:101]
	global_load_dwordx4 v[166:169], v[216:217], off
	global_load_dwordx4 v[170:173], v[216:217], off offset:64
	global_load_dwordx4 v[174:177], v[216:217], off offset:512
	global_load_dwordx4 v[178:181], v[216:217], off offset:576
	s_mov_b32 s100, 0x80000
	s_mov_b32 s101, 0
	v_lshl_add_u64 v[214:215], v[252:253], 0, s[100:101]
	global_load_dwordx4 v[182:185], v[214:215], off
	global_load_dwordx4 v[186:189], v[214:215], off offset:64
	global_load_dwordx4 v[190:193], v[214:215], off offset:512
	global_load_dwordx4 v[194:197], v[214:215], off offset:576
	s_mov_b32 s100, 0x90000
	s_mov_b32 s101, 0
	v_lshl_add_u64 v[216:217], v[252:253], 0, s[100:101]
	global_load_dwordx4 v[198:201], v[216:217], off
	global_load_dwordx4 v[202:205], v[216:217], off offset:64
	global_load_dwordx4 v[206:209], v[216:217], off offset:512
	global_load_dwordx4 v[210:213], v[216:217], off offset:576
	s_waitcnt vmcnt(16)
	v_pk_fma_f32 v[124:125], v[124:125], 0.5, v[220:221] op_sel_hi:[1,0,1]
	v_pk_fma_f32 v[126:127], v[126:127], 0.5, v[222:223] op_sel_hi:[1,0,1]
	v_pk_fma_f32 v[120:121], v[120:121], 0.5, v[224:225] op_sel_hi:[1,0,1]
	v_pk_fma_f32 v[122:123], v[122:123], 0.5, v[226:227] op_sel_hi:[1,0,1]
	v_pk_fma_f32 v[108:109], v[108:109], 0.5, v[228:229] op_sel_hi:[1,0,1]
	v_pk_fma_f32 v[110:111], v[110:111], 0.5, v[230:231] op_sel_hi:[1,0,1]
	v_pk_fma_f32 v[100:101], v[100:101], 0.5, v[232:233] op_sel_hi:[1,0,1]
	v_pk_fma_f32 v[102:103], v[102:103], 0.5, v[234:235] op_sel_hi:[1,0,1]
	v_pk_fma_f32 v[116:117], v[116:117], 0.5, v[236:237] op_sel_hi:[1,0,1]
	v_pk_fma_f32 v[118:119], v[118:119], 0.5, v[238:239] op_sel_hi:[1,0,1]
	v_pk_fma_f32 v[112:113], v[112:113], 0.5, v[240:241] op_sel_hi:[1,0,1]
	v_pk_fma_f32 v[114:115], v[114:115], 0.5, v[242:243] op_sel_hi:[1,0,1]
	v_pk_fma_f32 v[92:93], v[92:93], 0.5, v[244:245] op_sel_hi:[1,0,1]
	v_pk_fma_f32 v[94:95], v[94:95], 0.5, v[246:247] op_sel_hi:[1,0,1]
	v_pk_fma_f32 v[84:85], v[84:85], 0.5, v[248:249] op_sel_hi:[1,0,1]
	v_pk_fma_f32 v[86:87], v[86:87], 0.5, v[250:251] op_sel_hi:[1,0,1]
	s_mov_b32 s100, 0x0
	s_mov_b32 s101, 0
	v_lshl_add_u64 v[216:217], v[252:253], 0, s[100:101]
	global_store_dwordx4 v[216:217], v[124:127], off
	global_store_dwordx4 v[216:217], v[120:123], off offset:64
	global_store_dwordx4 v[216:217], v[108:111], off offset:512
	global_store_dwordx4 v[216:217], v[100:103], off offset:576
	s_mov_b32 s100, 0x10000
	s_mov_b32 s101, 0
	v_lshl_add_u64 v[218:219], v[252:253], 0, s[100:101]
	global_store_dwordx4 v[218:219], v[116:119], off
	global_store_dwordx4 v[218:219], v[112:115], off offset:64
	global_store_dwordx4 v[218:219], v[92:95], off offset:512
	global_store_dwordx4 v[218:219], v[84:87], off offset:576
	s_mov_b32 s100, 0xa0000
	s_mov_b32 s101, 0
	v_lshl_add_u64 v[214:215], v[252:253], 0, s[100:101]
	global_load_dwordx4 v[220:223], v[214:215], off
	global_load_dwordx4 v[224:227], v[214:215], off offset:64
	global_load_dwordx4 v[228:231], v[214:215], off offset:512
	global_load_dwordx4 v[232:235], v[214:215], off offset:576
	s_mov_b32 s100, 0xb0000
	s_mov_b32 s101, 0
	v_lshl_add_u64 v[216:217], v[252:253], 0, s[100:101]
	global_load_dwordx4 v[236:239], v[216:217], off
	global_load_dwordx4 v[240:243], v[216:217], off offset:64
	global_load_dwordx4 v[244:247], v[216:217], off offset:512
	global_load_dwordx4 v[248:251], v[216:217], off offset:576
	s_waitcnt vmcnt(24)
; #define PG8_WAIT_V(n) asm volatile("s_waitcnt vmcnt(" #n ")" ::: "memory")
; #define PG8_BAR __builtin_amdgcn_s_barrier()
; template <class Epi>
; DI void gemm_phase(int wv, LAS unsigned char* lds, const Gemm g, const StaticOrder& S, const Epi& E) {
;     ...
;         if (!has_next) break;
; #pragma unroll
;         for (int a = 0; a < 2; ++a)
; #pragma unroll
;             for (int b = 0; b < 2; ++b)
; #pragma unroll
;                 for (int m = 0; m < 4; ++m)
; #pragma unroll
;                     for (int n = 0; n < 2; ++n) acc[a][b][m][n] = (f32x4){0.f, 0.f, 0.f, 0.f};
;         cur = nxt; cA = nA; cB = nB; ++ui;
;     }
;     PG8_WAIT_V(0);
;     if (wr == 0) PG8_BAR;
;     PG8_BAR;
;     DI void operator()(const AccT& acc, const Unit& u, int wr, int wc, int fr, int fq) const {
; #pragma unroll
;         for (int ai = 0; ai < 2; ++ai) {
;             f32x4 h[4][2][2];
;             float* base = H + ((size_t)u.pm * 256 + ai * 128 + wr * 64 + fr) * 1024 + u.pn * 256 + wc * 32 + 4 * fq;
; #pragma unroll
;             for (int m = 0; m < 4; ++m)
; #pragma unroll
;                 for (int bj = 0; bj < 2; ++bj)
; #pragma unroll
;                     for (int n = 0; n < 2; ++n) h[m][bj][n] = *(const f32x4*)(base + (size_t)m * 16 * 1024 + bj * 128 + n * 16);
;             __builtin_amdgcn_sched_barrier(0);
; #pragma unroll
;             for (int m = 0; m < 4; ++m)
; #pragma unroll
;                 for (int bj = 0; bj < 2; ++bj)
; #pragma unroll
;                     for (int n = 0; n < 2; ++n) *(f32x4*)(base + (size_t)m * 16 * 1024 + bj * 128 + n * 16) = h[m][bj][n] + acc[ai][bj][m][n] * alpha;
;         }
	v_pk_fma_f32 v[104:105], v[104:105], 0.5, v[150:151] op_sel_hi:[1,0,1]
	v_pk_fma_f32 v[106:107], v[106:107], 0.5, v[152:153] op_sel_hi:[1,0,1]
	v_pk_fma_f32 v[96:97], v[96:97], 0.5, v[154:155] op_sel_hi:[1,0,1]
	v_pk_fma_f32 v[98:99], v[98:99], 0.5, v[156:157] op_sel_hi:[1,0,1]
	v_pk_fma_f32 v[76:77], v[76:77], 0.5, v[158:159] op_sel_hi:[1,0,1]
	v_pk_fma_f32 v[78:79], v[78:79], 0.5, v[160:161] op_sel_hi:[1,0,1]
	v_pk_fma_f32 v[72:73], v[72:73], 0.5, v[162:163] op_sel_hi:[1,0,1]
	v_pk_fma_f32 v[74:75], v[74:75], 0.5, v[164:165] op_sel_hi:[1,0,1]
	v_pk_fma_f32 v[88:89], v[88:89], 0.5, v[166:167] op_sel_hi:[1,0,1]
	v_pk_fma_f32 v[90:91], v[90:91], 0.5, v[168:169] op_sel_hi:[1,0,1]
	v_pk_fma_f32 v[80:81], v[80:81], 0.5, v[170:171] op_sel_hi:[1,0,1]
	v_pk_fma_f32 v[82:83], v[82:83], 0.5, v[172:173] op_sel_hi:[1,0,1]
	v_pk_fma_f32 v[68:69], v[68:69], 0.5, v[174:175] op_sel_hi:[1,0,1]
	v_pk_fma_f32 v[70:71], v[70:71], 0.5, v[176:177] op_sel_hi:[1,0,1]
	v_pk_fma_f32 v[64:65], v[64:65], 0.5, v[178:179] op_sel_hi:[1,0,1]
	v_pk_fma_f32 v[66:67], v[66:67], 0.5, v[180:181] op_sel_hi:[1,0,1]
	s_mov_b32 s100, 0x20000
	s_mov_b32 s101, 0
	v_lshl_add_u64 v[216:217], v[252:253], 0, s[100:101]
	global_store_dwordx4 v[216:217], v[104:107], off
	global_store_dwordx4 v[216:217], v[96:99], off offset:64
	global_store_dwordx4 v[216:217], v[76:79], off offset:512
	global_store_dwordx4 v[216:217], v[72:75], off offset:576
	s_mov_b32 s100, 0x30000
	s_mov_b32 s101, 0
	v_lshl_add_u64 v[218:219], v[252:253], 0, s[100:101]
	global_store_dwordx4 v[218:219], v[88:91], off
	global_store_dwordx4 v[218:219], v[80:83], off offset:64
	global_store_dwordx4 v[218:219], v[68:71], off offset:512
	global_store_dwordx4 v[218:219], v[64:67], off offset:576
	s_waitcnt vmcnt(24)
	v_pk_fma_f32 v[60:61], v[60:61], 0.5, v[182:183] op_sel_hi:[1,0,1]
	v_pk_fma_f32 v[62:63], v[62:63], 0.5, v[184:185] op_sel_hi:[1,0,1]
	v_pk_fma_f32 v[56:57], v[56:57], 0.5, v[186:187] op_sel_hi:[1,0,1]
	v_pk_fma_f32 v[58:59], v[58:59], 0.5, v[188:189] op_sel_hi:[1,0,1]
	v_pk_fma_f32 v[48:49], v[48:49], 0.5, v[190:191] op_sel_hi:[1,0,1]
	v_pk_fma_f32 v[50:51], v[50:51], 0.5, v[192:193] op_sel_hi:[1,0,1]
	v_pk_fma_f32 v[40:41], v[40:41], 0.5, v[194:195] op_sel_hi:[1,0,1]
	v_pk_fma_f32 v[42:43], v[42:43], 0.5, v[196:197] op_sel_hi:[1,0,1]
	v_pk_fma_f32 v[52:53], v[52:53], 0.5, v[198:199] op_sel_hi:[1,0,1]
	v_pk_fma_f32 v[54:55], v[54:55], 0.5, v[200:201] op_sel_hi:[1,0,1]
	v_pk_fma_f32 v[44:45], v[44:45], 0.5, v[202:203] op_sel_hi:[1,0,1]
	v_pk_fma_f32 v[46:47], v[46:47], 0.5, v[204:205] op_sel_hi:[1,0,1]
	v_pk_fma_f32 v[32:33], v[32:33], 0.5, v[206:207] op_sel_hi:[1,0,1]
	v_pk_fma_f32 v[34:35], v[34:35], 0.5, v[208:209] op_sel_hi:[1,0,1]
	v_pk_fma_f32 v[24:25], v[24:25], 0.5, v[210:211] op_sel_hi:[1,0,1]
	v_pk_fma_f32 v[26:27], v[26:27], 0.5, v[212:213] op_sel_hi:[1,0,1]
	s_mov_b32 s100, 0x80000
	s_mov_b32 s101, 0
	v_lshl_add_u64 v[216:217], v[252:253], 0, s[100:101]
	global_store_dwordx4 v[216:217], v[60:63], off
	global_store_dwordx4 v[216:217], v[56:59], off offset:64
	global_store_dwordx4 v[216:217], v[48:51], off offset:512
	global_store_dwordx4 v[216:217], v[40:43], off offset:576
	s_mov_b32 s100, 0x90000
	s_mov_b32 s101, 0
	v_lshl_add_u64 v[218:219], v[252:253], 0, s[100:101]
	global_store_dwordx4 v[218:219], v[52:55], off
	global_store_dwordx4 v[218:219], v[44:47], off offset:64
	global_store_dwordx4 v[218:219], v[32:35], off offset:512
	global_store_dwordx4 v[218:219], v[24:27], off offset:576
	s_waitcnt vmcnt(16)
	v_pk_fma_f32 v[36:37], v[36:37], 0.5, v[220:221] op_sel_hi:[1,0,1]
	v_pk_fma_f32 v[38:39], v[38:39], 0.5, v[222:223] op_sel_hi:[1,0,1]
	v_pk_fma_f32 v[28:29], v[28:29], 0.5, v[224:225] op_sel_hi:[1,0,1]
	v_pk_fma_f32 v[30:31], v[30:31], 0.5, v[226:227] op_sel_hi:[1,0,1]
	v_pk_fma_f32 v[16:17], v[16:17], 0.5, v[228:229] op_sel_hi:[1,0,1]
	v_pk_fma_f32 v[18:19], v[18:19], 0.5, v[230:231] op_sel_hi:[1,0,1]
	v_pk_fma_f32 v[8:9], v[8:9], 0.5, v[232:233] op_sel_hi:[1,0,1]
	v_pk_fma_f32 v[10:11], v[10:11], 0.5, v[234:235] op_sel_hi:[1,0,1]
	v_pk_fma_f32 v[20:21], v[20:21], 0.5, v[236:237] op_sel_hi:[1,0,1]
	v_pk_fma_f32 v[22:23], v[22:23], 0.5, v[238:239] op_sel_hi:[1,0,1]
	v_pk_fma_f32 v[12:13], v[12:13], 0.5, v[240:241] op_sel_hi:[1,0,1]
	v_pk_fma_f32 v[14:15], v[14:15], 0.5, v[242:243] op_sel_hi:[1,0,1]
	v_pk_fma_f32 v[4:5], v[4:5], 0.5, v[244:245] op_sel_hi:[1,0,1]
	v_pk_fma_f32 v[6:7], v[6:7], 0.5, v[246:247] op_sel_hi:[1,0,1]
	v_pk_fma_f32 v[0:1], v[0:1], 0.5, v[248:249] op_sel_hi:[1,0,1]
	v_pk_fma_f32 v[2:3], v[2:3], 0.5, v[250:251] op_sel_hi:[1,0,1]
	s_mov_b32 s100, 0xa0000
	s_mov_b32 s101, 0
	v_lshl_add_u64 v[216:217], v[252:253], 0, s[100:101]
	global_store_dwordx4 v[216:217], v[36:39], off
	global_store_dwordx4 v[216:217], v[28:31], off offset:64
	global_store_dwordx4 v[216:217], v[16:19], off offset:512
	global_store_dwordx4 v[216:217], v[8:11], off offset:576
	s_mov_b32 s100, 0xb0000
	s_mov_b32 s101, 0
	v_lshl_add_u64 v[218:219], v[252:253], 0, s[100:101]
	global_store_dwordx4 v[218:219], v[20:23], off
	global_store_dwordx4 v[218:219], v[12:15], off offset:64
	global_store_dwordx4 v[218:219], v[4:7], off offset:512
	global_store_dwordx4 v[218:219], v[0:3], off offset:576
	s_and_b64 vcc, exec, s[16:17]
	s_mov_b32 s73, s71
	s_mov_b32 s30, s72
	s_mov_b64 s[54:55], s[20:21]
	s_mov_b64 s[38:39], s[18:19]
	s_cbranch_vccz .LBB0_1595
	s_waitcnt vmcnt(0)
	s_cmpk_gt_u32 s8, 0xff
	s_cbranch_scc1 .LBB0_1610
	s_barrier

;     DI bool next(int i, Unit& u) const {
;         const long L = (long)i * G + c; if (L >= nwg) return false;
;         int wgid = (int)L; { const int q = nwg / NXCD, r = nwg % NXCD, xcd = wgid % NXCD, off = wgid / NXCD; wgid = (xcd < r ? xcd * (q + 1) : r * (q + 1) + (xcd - r) * q) + off; }
;         const int nig = WGM * nN, gid = wgid / nig, fm = gid * WGM, gsz = (nM - fm) < WGM ? (nM - fm) : WGM;
;         u.pm = fm + ((wgid % nig) % gsz); u.pn = (wgid % nig) / gsz; return true;
;     }
;     DI void operator()(const AccT& acc, const Unit& u, int wr, int wc, int fr, int fq) const {
; #pragma unroll
;         for (int ai = 0; ai < 2; ++ai) {
;             f32x4 h[4][2][2];
;             float* base = H + ((size_t)u.pm * 256 + ai * 128 + wr * 64 + fr) * 1024 + u.pn * 256 + wc * 32 + 4 * fq;
; #pragma unroll
;             for (int m = 0; m < 4; ++m)
; #pragma unroll
;                 for (int bj = 0; bj < 2; ++bj)
; #pragma unroll
;                     for (int n = 0; n < 2; ++n) h[m][bj][n] = *(const f32x4*)(base + (size_t)m * 16 * 1024 + bj * 128 + n * 16);
.LBB0_1943:
	s_mov_b32 s98, s30
	s_ashr_i32 s99, s30, 31
	s_lshl_b64 s[98:99], s[98:99], 20
	s_lshl_b32 s100, s75, 8
	s_ashr_i32 s101, s100, 31
	v_lshl_add_u64 v[252:253], v[134:135], 0, s[98:99]
	v_lshl_add_u64 v[252:253], s[100:101], 2, v[252:253]
	v_lshl_add_u64 v[252:253], v[252:253], 0, s[24:25]
	v_lshl_add_u64 v[252:253], v[252:253], 0, v[132:133]
	global_load_dwordx4 v[220:223], v[252:253], off
	global_load_dwordx4 v[224:227], v[252:253], off offset:64
	global_load_dwordx4 v[228:231], v[252:253], off offset:512
	global_load_dwordx4 v[232:235], v[252:253], off offset:576
	s_mov_b32 s100, 0x10000
	s_mov_b32 s101, 0
	v_lshl_add_u64 v[252:253], v[252:253], 0, s[100:101]
	global_load_dwordx4 v[236:239], v[252:253], off
	global_load_dwordx4 v[240:243], v[252:253], off offset:64
	global_load_dwordx4 v[244:247], v[252:253], off offset:512
	global_load_dwordx4 v[248:251], v[252:253], off offset:576
	s_mov_b32 s100, 0xffff0000
	s_mov_b32 s101, -1
	v_lshl_add_u64 v[252:253], v[252:253], 0, s[100:101]
	s_add_i32 s72, s72, 1
	s_mul_i32 s14, s72, s45
	s_mul_hi_u32 s15, s72, s44
	s_add_i32 s15, s15, s14
	s_mul_i32 s14, s72, s44
	s_add_u32 s18, s14, s2
	s_addc_u32 s19, s15, s3
	v_cmp_gt_i64_e64 s[14:15], s[18:19], v[142:143]
	v_cmp_lt_i64_e64 s[16:17], s[18:19], v[140:141]
	s_and_b64 vcc, exec, s[14:15]
	s_cbranch_vccnz .LBB0_1949
	s_ashr_i32 s19, s18, 31
	s_lshr_b32 s19, s19, 29
	s_add_i32 s31, s18, s19
	s_and_b32 s19, s31, -8
	s_sub_i32 s56, s18, s19
	s_cmp_gt_i32 s56, 3
	s_mov_b64 s[18:19], -1
	s_cbranch_scc0 .LBB0_1946
	s_mul_i32 s18, s56, 0xa1
	s_add_i32 s57, s18, 4
	s_mov_b64 s[18:19], 0

; #define PG8_STAGE(bufoff, gbase, voff) do { _Pragma("unroll") for (int _i = 0; _i < 2; ++_i) \
;         __builtin_amdgcn_global_load_lds((const unsigned*)((const char*)(gbase) + (voff)[_i]), (LAS unsigned*)(lds + (bufoff) + ldsw + _i * 8192), 16, 0, 0); } while (0)
; #define PG8_LDA(dst, b, h) do { _Pragma("unroll") for (int m = 0; m < 4; ++m) _Pragma("unroll") for (int k = 0; k < 2; ++k) dst[m][k] = *(const LAS bf16x8*)(lds + PG8_SA(b, h) + aoff + m * 2048 + k * 1024); } while (0)
; #define PG8_LDB(dst, b, h) do { _Pragma("unroll") for (int n = 0; n < 2; ++n) _Pragma("unroll") for (int k = 0; k < 2; ++k) dst[n][k] = *(const LAS bf16x8*)(lds + PG8_SB(b, h) + boff + n * 2048 + k * 1024); } while (0)
; #define PG8_MMA(ai, bj, At, Bt) do { __builtin_amdgcn_s_setprio(1); _Pragma("unroll") for (int m = 0; m < 4; ++m) _Pragma("unroll") for (int n = 0; n < 2; ++n) _Pragma("unroll") for (int k = 0; k < 2; ++k) \
;         acc[ai][bj][m][n] = __builtin_amdgcn_mfma_f32_16x16x32_bf16(Bt[n][k], At[m][k], acc[ai][bj][m][n], 0, 0, 0); __builtin_amdgcn_s_setprio(0); } while (0)
; #define PG8_WAIT_V(n) asm volatile("s_waitcnt vmcnt(" #n ")" ::: "memory")
; #define PG8_WAIT_L(n) asm volatile("s_waitcnt lgkmcnt(" #n ")" ::: "memory")
; #define PG8_BAR __builtin_amdgcn_s_barrier()
; #define PG8_SCHED __builtin_amdgcn_sched_barrier(0)
; template <class Epi>
; DI void gemm_phase(int wv, LAS unsigned char* lds, const Gemm g, const StaticOrder& S, const Epi& E) {
;     ...
;             PG8_LDB(B0, 0, 0); PG8_SCHED; PG8_LDA(At, 0, 0); PG8_STAGE(PG8_SA(1, 1), a1 + hstep, voffA);
;             PG8_WAIT_L(8); PG8_BAR; PG8_WAIT_L(0); PG8_MMA(0, 0, At, B0); PG8_BAR; PG8_SCHED;
;             PG8_LDB(B1, 0, 1); PG8_STAGE(PG8_SB(0, 0), b2, voffB);
;             PG8_BAR; PG8_WAIT_L(0); PG8_MMA(0, 1, At, B1); PG8_BAR;
;             PG8_LDA(At, 0, 1); PG8_STAGE(PG8_SA(0, 0), a2, voffA);
;             PG8_BAR; PG8_WAIT_L(0); PG8_MMA(1, 0, At, B0); PG8_BAR; PG8_SCHED;
;             PG8_STAGE(PG8_SB(0, 1), b2 + hstep, voffB);
;             PG8_WAIT_V(6); PG8_BAR; PG8_MMA(1, 1, At, B1); PG8_BAR;
;             PG8_LDB(B0, 1, 0); PG8_SCHED; PG8_LDA(At, 1, 0); PG8_STAGE(PG8_SA(0, 1), a2 + hstep, voffA);
;             PG8_WAIT_L(8); PG8_BAR; PG8_WAIT_L(0); PG8_MMA(0, 0, At, B0); PG8_BAR; PG8_SCHED;
.LBB0_1954:
	ds_read_b128 v[150:153], v147
	ds_read_b128 v[154:157], v147 offset:1024
	ds_read_b128 v[158:161], v147 offset:2048
	ds_read_b128 v[162:165], v147 offset:3072
	s_add_u32 s54, s52, 0x100
	s_addc_u32 s55, s53, 0
	s_cmp_eq_u32 s77, 40
	s_cselect_b32 s59, s17, s55
	s_cselect_b32 s58, s16, s54
	s_cselect_b32 s57, s19, s76
	s_cselect_b32 s56, s18, s31
	v_lshl_add_u64 v[144:145], s[52:53], 0, v[136:137]
	s_add_i32 m0, s41, 0xc000
	ds_read_b128 v[166:169], v148
	ds_read_b128 v[170:173], v148 offset:1024
	ds_read_b128 v[174:177], v148 offset:2048
	ds_read_b128 v[178:181], v148 offset:3072
	ds_read_b128 v[182:185], v148 offset:4096
	ds_read_b128 v[186:189], v148 offset:5120
	ds_read_b128 v[190:193], v148 offset:6144
	ds_read_b128 v[194:197], v148 offset:7168
	global_load_lds_dwordx4 v[144:145], off
	v_lshl_add_u64 v[144:145], s[52:53], 0, v[138:139]
	s_add_i32 m0, s41, 0xe000
	s_nop 0
	global_load_lds_dwordx4 v[144:145], off
	s_waitcnt lgkmcnt(8)
	s_barrier
	s_waitcnt lgkmcnt(0)
	s_setprio 1
	s_waitcnt lgkmcnt(0)
	v_mfma_f32_16x16x32_bf16 v[124:127], v[150:153], v[166:169], v[124:127]
	v_mfma_f32_16x16x32_bf16 v[120:123], v[158:161], v[166:169], v[120:123]
	v_mfma_f32_16x16x32_bf16 v[116:119], v[150:153], v[174:177], v[116:119]
	v_mfma_f32_16x16x32_bf16 v[112:115], v[158:161], v[174:177], v[112:115]
	v_mfma_f32_16x16x32_bf16 v[104:107], v[150:153], v[182:185], v[104:107]
	v_mfma_f32_16x16x32_bf16 v[96:99], v[158:161], v[182:185], v[96:99]
	v_mfma_f32_16x16x32_bf16 v[88:91], v[150:153], v[190:193], v[88:91]
	v_mfma_f32_16x16x32_bf16 v[80:83], v[158:161], v[190:193], v[80:83]
	v_mfma_f32_16x16x32_bf16 v[124:127], v[154:157], v[170:173], v[124:127]
	v_mfma_f32_16x16x32_bf16 v[120:123], v[162:165], v[170:173], v[120:123]
	v_mfma_f32_16x16x32_bf16 v[116:119], v[154:157], v[178:181], v[116:119]
	v_mfma_f32_16x16x32_bf16 v[112:115], v[162:165], v[178:181], v[112:115]
	v_mfma_f32_16x16x32_bf16 v[104:107], v[154:157], v[186:189], v[104:107]
	v_mfma_f32_16x16x32_bf16 v[96:99], v[162:165], v[186:189], v[96:99]
	v_mfma_f32_16x16x32_bf16 v[88:91], v[154:157], v[194:197], v[88:91]
	v_mfma_f32_16x16x32_bf16 v[80:83], v[162:165], v[194:197], v[80:83]
	s_setprio 0
	s_barrier
	s_add_i32 s52, s64, s11
	v_lshl_add_u64 v[144:145], s[56:57], 0, v[128:129]
	s_mov_b32 m0, s52
	ds_read_b128 v[198:201], v149
	ds_read_b128 v[202:205], v149 offset:1024
	ds_read_b128 v[206:209], v149 offset:2048
	ds_read_b128 v[210:213], v149 offset:3072
	global_load_lds_dwordx4 v[144:145], off
	v_lshl_add_u64 v[214:215], s[56:57], 0, v[130:131]
	s_add_i32 m0, s52, 0x2000
	s_nop 0
	global_load_lds_dwordx4 v[214:215], off
	s_barrier
	s_waitcnt lgkmcnt(0)
	s_setprio 1
	s_waitcnt lgkmcnt(0)
	v_mfma_f32_16x16x32_bf16 v[108:111], v[198:201], v[166:169], v[108:111]
	v_mfma_f32_16x16x32_bf16 v[100:103], v[206:209], v[166:169], v[100:103]
	v_mfma_f32_16x16x32_bf16 v[92:95], v[198:201], v[174:177], v[92:95]
	v_mfma_f32_16x16x32_bf16 v[84:87], v[206:209], v[174:177], v[84:87]
	v_mfma_f32_16x16x32_bf16 v[76:79], v[198:201], v[182:185], v[76:79]
	v_mfma_f32_16x16x32_bf16 v[72:75], v[206:209], v[182:185], v[72:75]
	v_mfma_f32_16x16x32_bf16 v[68:71], v[198:201], v[190:193], v[68:71]
	v_mfma_f32_16x16x32_bf16 v[64:67], v[206:209], v[190:193], v[64:67]
	v_mfma_f32_16x16x32_bf16 v[108:111], v[202:205], v[170:173], v[108:111]
	v_mfma_f32_16x16x32_bf16 v[100:103], v[210:213], v[170:173], v[100:103]
	v_mfma_f32_16x16x32_bf16 v[92:95], v[202:205], v[178:181], v[92:95]
	v_mfma_f32_16x16x32_bf16 v[84:87], v[210:213], v[178:181], v[84:87]
	v_mfma_f32_16x16x32_bf16 v[76:79], v[202:205], v[186:189], v[76:79]
	v_mfma_f32_16x16x32_bf16 v[72:75], v[210:213], v[186:189], v[72:75]
	v_mfma_f32_16x16x32_bf16 v[68:71], v[202:205], v[194:197], v[68:71]
	v_mfma_f32_16x16x32_bf16 v[64:67], v[210:213], v[194:197], v[64:67]
	s_setprio 0
	s_mov_b32 m0, s41
	v_lshl_add_u64 v[216:217], s[58:59], 0, v[128:129]
	s_barrier
	ds_read_b128 v[166:169], v148 offset:16384
	ds_read_b128 v[170:173], v148 offset:17408
	ds_read_b128 v[174:177], v148 offset:18432
	ds_read_b128 v[178:181], v148 offset:19456
	ds_read_b128 v[182:185], v148 offset:20480
	ds_read_b128 v[186:189], v148 offset:21504
	ds_read_b128 v[190:193], v148 offset:22528
	ds_read_b128 v[194:197], v148 offset:23552
	global_load_lds_dwordx4 v[216:217], off
	v_lshl_add_u64 v[218:219], s[58:59], 0, v[130:131]
	s_mov_b32 m0, s50
	s_nop 0
	global_load_lds_dwordx4 v[218:219], off
	s_barrier
	s_waitcnt lgkmcnt(0)
	s_setprio 1
	s_waitcnt lgkmcnt(0)
	v_mfma_f32_16x16x32_bf16 v[60:63], v[150:153], v[166:169], v[60:63]
	v_mfma_f32_16x16x32_bf16 v[56:59], v[158:161], v[166:169], v[56:59]
	v_mfma_f32_16x16x32_bf16 v[52:55], v[150:153], v[174:177], v[52:55]
	v_mfma_f32_16x16x32_bf16 v[44:47], v[158:161], v[174:177], v[44:47]
	v_mfma_f32_16x16x32_bf16 v[36:39], v[150:153], v[182:185], v[36:39]
	v_mfma_f32_16x16x32_bf16 v[28:31], v[158:161], v[182:185], v[28:31]
	v_mfma_f32_16x16x32_bf16 v[20:23], v[150:153], v[190:193], v[20:23]
	v_mfma_f32_16x16x32_bf16 v[12:15], v[158:161], v[190:193], v[12:15]
	v_mfma_f32_16x16x32_bf16 v[60:63], v[154:157], v[170:173], v[60:63]
	v_mfma_f32_16x16x32_bf16 v[56:59], v[162:165], v[170:173], v[56:59]
	v_mfma_f32_16x16x32_bf16 v[52:55], v[154:157], v[178:181], v[52:55]
	v_mfma_f32_16x16x32_bf16 v[44:47], v[162:165], v[178:181], v[44:47]
	v_mfma_f32_16x16x32_bf16 v[36:39], v[154:157], v[186:189], v[36:39]
	v_mfma_f32_16x16x32_bf16 v[28:31], v[162:165], v[186:189], v[28:31]
	v_mfma_f32_16x16x32_bf16 v[20:23], v[154:157], v[194:197], v[20:23]
	v_mfma_f32_16x16x32_bf16 v[12:15], v[162:165], v[194:197], v[12:15]
	s_setprio 0
	s_barrier
; #define PG8_STAGE(bufoff, gbase, voff) do { _Pragma("unroll") for (int _i = 0; _i < 2; ++_i) \
;         __builtin_amdgcn_global_load_lds((const unsigned*)((const char*)(gbase) + (voff)[_i]), (LAS unsigned*)(lds + (bufoff) + ldsw + _i * 8192), 16, 0, 0); } while (0)
; #define PG8_LDA(dst, b, h) do { _Pragma("unroll") for (int m = 0; m < 4; ++m) _Pragma("unroll") for (int k = 0; k < 2; ++k) dst[m][k] = *(const LAS bf16x8*)(lds + PG8_SA(b, h) + aoff + m * 2048 + k * 1024); } while (0)
; #define PG8_LDB(dst, b, h) do { _Pragma("unroll") for (int n = 0; n < 2; ++n) _Pragma("unroll") for (int k = 0; k < 2; ++k) dst[n][k] = *(const LAS bf16x8*)(lds + PG8_SB(b, h) + boff + n * 2048 + k * 1024); } while (0)
; #define PG8_MMA(ai, bj, At, Bt) do { __builtin_amdgcn_s_setprio(1); _Pragma("unroll") for (int m = 0; m < 4; ++m) _Pragma("unroll") for (int n = 0; n < 2; ++n) _Pragma("unroll") for (int k = 0; k < 2; ++k) \
;         acc[ai][bj][m][n] = __builtin_amdgcn_mfma_f32_16x16x32_bf16(Bt[n][k], At[m][k], acc[ai][bj][m][n], 0, 0, 0); __builtin_amdgcn_s_setprio(0); } while (0)
; #define PG8_WAIT_V(n) asm volatile("s_waitcnt vmcnt(" #n ")" ::: "memory")
; #define PG8_WAIT_L(n) asm volatile("s_waitcnt lgkmcnt(" #n ")" ::: "memory")
; #define PG8_BAR __builtin_amdgcn_s_barrier()
; #define PG8_SCHED __builtin_amdgcn_sched_barrier(0)
; template <class Epi>
; DI void gemm_phase(int wv, LAS unsigned char* lds, const Gemm g, const StaticOrder& S, const Epi& E) {
;     ...
;             PG8_STAGE(PG8_SB(0, 1), b2 + hstep, voffB);
;             PG8_WAIT_V(6); PG8_BAR; PG8_MMA(1, 1, At, B1); PG8_BAR;
;             PG8_LDB(B0, 1, 0); PG8_SCHED; PG8_LDA(At, 1, 0); PG8_STAGE(PG8_SA(0, 1), a2 + hstep, voffA);
;             PG8_WAIT_L(8); PG8_BAR; PG8_WAIT_L(0); PG8_MMA(0, 0, At, B0); PG8_BAR; PG8_SCHED;
;             PG8_LDB(B1, 1, 1); PG8_STAGE(PG8_SB(1, 0), b3, voffB);
;             PG8_BAR; PG8_WAIT_L(0); PG8_MMA(0, 1, At, B1); PG8_BAR;
;             PG8_LDA(At, 1, 1); PG8_STAGE(PG8_SA(1, 0), a3, voffA);
;             PG8_BAR; PG8_WAIT_L(0); PG8_MMA(1, 0, At, B0); PG8_BAR; PG8_SCHED;
	s_add_u32 s52, s56, 0xb0000
	s_addc_u32 s53, s57, 0
	s_add_i32 s78, s65, s11
	v_lshl_add_u64 v[150:151], s[52:53], 0, v[128:129]
	s_mov_b32 m0, s78
	s_nop 0
	global_load_lds_dwordx4 v[150:151], off
	v_lshl_add_u64 v[150:151], s[52:53], 0, v[130:131]
	s_add_i32 m0, s78, 0x2000
	s_nop 0
	global_load_lds_dwordx4 v[150:151], off
	s_waitcnt vmcnt(6)
	s_barrier
	s_setprio 1
	v_mfma_f32_16x16x32_bf16 v[48:51], v[198:201], v[166:169], v[48:51]
	v_mfma_f32_16x16x32_bf16 v[40:43], v[206:209], v[166:169], v[40:43]
	v_mfma_f32_16x16x32_bf16 v[32:35], v[198:201], v[174:177], v[32:35]
	v_mfma_f32_16x16x32_bf16 v[24:27], v[206:209], v[174:177], v[24:27]
	v_mfma_f32_16x16x32_bf16 v[16:19], v[198:201], v[182:185], v[16:19]
	v_mfma_f32_16x16x32_bf16 v[8:11], v[206:209], v[182:185], v[8:11]
	v_mfma_f32_16x16x32_bf16 v[4:7], v[198:201], v[190:193], v[4:7]
	v_mfma_f32_16x16x32_bf16 v[0:3], v[206:209], v[190:193], v[0:3]
	v_mfma_f32_16x16x32_bf16 v[48:51], v[202:205], v[170:173], v[48:51]
	v_mfma_f32_16x16x32_bf16 v[40:43], v[210:213], v[170:173], v[40:43]
	v_mfma_f32_16x16x32_bf16 v[32:35], v[202:205], v[178:181], v[32:35]
	v_mfma_f32_16x16x32_bf16 v[24:27], v[210:213], v[178:181], v[24:27]
	v_mfma_f32_16x16x32_bf16 v[16:19], v[202:205], v[186:189], v[16:19]
	v_mfma_f32_16x16x32_bf16 v[8:11], v[210:213], v[186:189], v[8:11]
	v_mfma_f32_16x16x32_bf16 v[4:7], v[202:205], v[194:197], v[4:7]
	v_mfma_f32_16x16x32_bf16 v[0:3], v[210:213], v[194:197], v[0:3]
	s_setprio 0
	s_add_i32 s78, 0, 0x18000
	v_add_u32_e32 v162, s78, v146
	s_barrier
	ds_read_b128 v[150:153], v162
	ds_read_b128 v[154:157], v162 offset:1024
	ds_read_b128 v[158:161], v162 offset:2048
	ds_read_b128 v[162:165], v162 offset:3072
	s_add_u32 s52, s58, 0xb0000
	s_addc_u32 s53, s59, 0
	s_mov_b32 m0, s51
	v_lshl_add_u64 v[198:199], s[52:53], 0, v[128:129]
	ds_read_b128 v[166:169], v148 offset:32768
	ds_read_b128 v[170:173], v148 offset:33792
	ds_read_b128 v[174:177], v148 offset:34816
	ds_read_b128 v[178:181], v148 offset:35840
	ds_read_b128 v[182:185], v148 offset:36864
	ds_read_b128 v[186:189], v148 offset:37888
	ds_read_b128 v[190:193], v148 offset:38912
	ds_read_b128 v[194:197], v148 offset:39936
	global_load_lds_dwordx4 v[198:199], off
	v_lshl_add_u64 v[198:199], s[52:53], 0, v[130:131]
	s_mov_b32 m0, s60
	s_nop 0
	global_load_lds_dwordx4 v[198:199], off
	s_waitcnt lgkmcnt(8)
	s_barrier
	s_waitcnt lgkmcnt(0)
	s_setprio 1
	s_waitcnt lgkmcnt(0)
	v_mfma_f32_16x16x32_bf16 v[124:127], v[150:153], v[166:169], v[124:127]
	v_mfma_f32_16x16x32_bf16 v[120:123], v[158:161], v[166:169], v[120:123]
	v_mfma_f32_16x16x32_bf16 v[116:119], v[150:153], v[174:177], v[116:119]
	v_mfma_f32_16x16x32_bf16 v[112:115], v[158:161], v[174:177], v[112:115]
	v_mfma_f32_16x16x32_bf16 v[104:107], v[150:153], v[182:185], v[104:107]
	v_mfma_f32_16x16x32_bf16 v[96:99], v[158:161], v[182:185], v[96:99]
	v_mfma_f32_16x16x32_bf16 v[88:91], v[150:153], v[190:193], v[88:91]
	v_mfma_f32_16x16x32_bf16 v[80:83], v[158:161], v[190:193], v[80:83]
	v_mfma_f32_16x16x32_bf16 v[124:127], v[154:157], v[170:173], v[124:127]
	v_mfma_f32_16x16x32_bf16 v[120:123], v[162:165], v[170:173], v[120:123]
	v_mfma_f32_16x16x32_bf16 v[116:119], v[154:157], v[178:181], v[116:119]
	v_mfma_f32_16x16x32_bf16 v[112:115], v[162:165], v[178:181], v[112:115]
	v_mfma_f32_16x16x32_bf16 v[104:107], v[154:157], v[186:189], v[104:107]
	v_mfma_f32_16x16x32_bf16 v[96:99], v[162:165], v[186:189], v[96:99]
	v_mfma_f32_16x16x32_bf16 v[88:91], v[154:157], v[194:197], v[88:91]
	v_mfma_f32_16x16x32_bf16 v[80:83], v[162:165], v[194:197], v[80:83]
	s_setprio 0
	s_barrier
	s_add_i32 s58, 0, 0x1c000
	s_add_i32 s52, s78, s11
	v_add_u32_e32 v210, s58, v146
	v_lshl_add_u64 v[144:145], v[144:145], 0, s[26:27]
	s_mov_b32 m0, s52
	ds_read_b128 v[198:201], v210
	ds_read_b128 v[202:205], v210 offset:1024
	ds_read_b128 v[206:209], v210 offset:2048
	ds_read_b128 v[210:213], v210 offset:3072
	global_load_lds_dwordx4 v[144:145], off
	v_lshl_add_u64 v[144:145], v[214:215], 0, s[26:27]
	s_add_i32 m0, s52, 0x2000
	s_nop 0
	global_load_lds_dwordx4 v[144:145], off
	s_barrier
	s_waitcnt lgkmcnt(0)
	s_setprio 1
	s_waitcnt lgkmcnt(0)
	v_mfma_f32_16x16x32_bf16 v[108:111], v[198:201], v[166:169], v[108:111]
	v_mfma_f32_16x16x32_bf16 v[100:103], v[206:209], v[166:169], v[100:103]
	v_mfma_f32_16x16x32_bf16 v[92:95], v[198:201], v[174:177], v[92:95]
	v_mfma_f32_16x16x32_bf16 v[84:87], v[206:209], v[174:177], v[84:87]
	v_mfma_f32_16x16x32_bf16 v[76:79], v[198:201], v[182:185], v[76:79]
	v_mfma_f32_16x16x32_bf16 v[72:75], v[206:209], v[182:185], v[72:75]
	v_mfma_f32_16x16x32_bf16 v[68:71], v[198:201], v[190:193], v[68:71]
	v_mfma_f32_16x16x32_bf16 v[64:67], v[206:209], v[190:193], v[64:67]
	v_mfma_f32_16x16x32_bf16 v[108:111], v[202:205], v[170:173], v[108:111]
	v_mfma_f32_16x16x32_bf16 v[100:103], v[210:213], v[170:173], v[100:103]
	v_mfma_f32_16x16x32_bf16 v[92:95], v[202:205], v[178:181], v[92:95]
	v_mfma_f32_16x16x32_bf16 v[84:87], v[210:213], v[178:181], v[84:87]
	v_mfma_f32_16x16x32_bf16 v[76:79], v[202:205], v[186:189], v[76:79]
	v_mfma_f32_16x16x32_bf16 v[72:75], v[210:213], v[186:189], v[72:75]
	v_mfma_f32_16x16x32_bf16 v[68:71], v[202:205], v[194:197], v[68:71]
	v_mfma_f32_16x16x32_bf16 v[64:67], v[210:213], v[194:197], v[64:67]
	s_setprio 0
	s_mov_b32 m0, s62
	v_lshl_add_u64 v[144:145], v[216:217], 0, s[26:27]
	s_barrier
	ds_read_b128 v[166:169], v148 offset:49152
	ds_read_b128 v[170:173], v148 offset:50176
	ds_read_b128 v[174:177], v148 offset:51200
	ds_read_b128 v[178:181], v148 offset:52224
	ds_read_b128 v[182:185], v148 offset:53248
	ds_read_b128 v[186:189], v148 offset:54272
	ds_read_b128 v[190:193], v148 offset:55296
	ds_read_b128 v[194:197], v148 offset:56320
	global_load_lds_dwordx4 v[144:145], off
	v_lshl_add_u64 v[144:145], v[218:219], 0, s[26:27]
	s_mov_b32 m0, s63
	s_nop 0
	global_load_lds_dwordx4 v[144:145], off
	s_barrier
; #define PG8_STAGE(bufoff, gbase, voff) do { _Pragma("unroll") for (int _i = 0; _i < 2; ++_i) \
;         __builtin_amdgcn_global_load_lds((const unsigned*)((const char*)(gbase) + (voff)[_i]), (LAS unsigned*)(lds + (bufoff) + ldsw + _i * 8192), 16, 0, 0); } while (0)
; #define PG8_MMA(ai, bj, At, Bt) do { __builtin_amdgcn_s_setprio(1); _Pragma("unroll") for (int m = 0; m < 4; ++m) _Pragma("unroll") for (int n = 0; n < 2; ++n) _Pragma("unroll") for (int k = 0; k < 2; ++k) \
;         acc[ai][bj][m][n] = __builtin_amdgcn_mfma_f32_16x16x32_bf16(Bt[n][k], At[m][k], acc[ai][bj][m][n], 0, 0, 0); __builtin_amdgcn_s_setprio(0); } while (0)
; #define PG8_WAIT_V(n) asm volatile("s_waitcnt vmcnt(" #n ")" ::: "memory")
; #define PG8_WAIT_L(n) asm volatile("s_waitcnt lgkmcnt(" #n ")" ::: "memory")
; #define PG8_BAR __builtin_amdgcn_s_barrier()
; #define PG8_SCHED __builtin_amdgcn_sched_barrier(0)
; template <class Epi>
; DI void gemm_phase(int wv, LAS unsigned char* lds, const Gemm g, const StaticOrder& S, const Epi& E) {
;     ...
;             PG8_BAR; PG8_WAIT_L(0); PG8_MMA(1, 0, At, B0); PG8_BAR; PG8_SCHED;
;             PG8_STAGE(PG8_SB(1, 1), b3 + hstep, voffB);
;             PG8_WAIT_V(6); PG8_BAR; PG8_MMA(1, 1, At, B1); PG8_BAR;
;         }
;         E(acc, cur, wr, wc, fr, fq);
;     DI void operator()(const AccT& acc, const Unit& u, int wr, int wc, int fr, int fq) const {
; #pragma unroll
;         for (int ai = 0; ai < 2; ++ai) {
;             f32x4 h[4][2][2];
;             float* base = H + ((size_t)u.pm * 256 + ai * 128 + wr * 64 + fr) * 1024 + u.pn * 256 + wc * 32 + 4 * fq;
; #pragma unroll
;             for (int m = 0; m < 4; ++m)
; #pragma unroll
;                 for (int bj = 0; bj < 2; ++bj)
; #pragma unroll
;                     for (int n = 0; n < 2; ++n) h[m][bj][n] = *(const f32x4*)(base + (size_t)m * 16 * 1024 + bj * 128 + n * 16);
;             __builtin_amdgcn_sched_barrier(0);
; #pragma unroll
;             for (int m = 0; m < 4; ++m)
; #pragma unroll
;                 for (int bj = 0; bj < 2; ++bj)
; #pragma unroll
;                     for (int n = 0; n < 2; ++n) *(f32x4*)(base + (size_t)m * 16 * 1024 + bj * 128 + n * 16) = h[m][bj][n] + acc[ai][bj][m][n] * alpha;
;         }
;     }
	s_waitcnt lgkmcnt(0)
	s_setprio 1
	s_waitcnt lgkmcnt(0)
	v_mfma_f32_16x16x32_bf16 v[60:63], v[150:153], v[166:169], v[60:63]
	v_mfma_f32_16x16x32_bf16 v[56:59], v[158:161], v[166:169], v[56:59]
	v_mfma_f32_16x16x32_bf16 v[52:55], v[150:153], v[174:177], v[52:55]
	v_mfma_f32_16x16x32_bf16 v[44:47], v[158:161], v[174:177], v[44:47]
	v_mfma_f32_16x16x32_bf16 v[36:39], v[150:153], v[182:185], v[36:39]
	v_mfma_f32_16x16x32_bf16 v[28:31], v[158:161], v[182:185], v[28:31]
	v_mfma_f32_16x16x32_bf16 v[20:23], v[150:153], v[190:193], v[20:23]
	v_mfma_f32_16x16x32_bf16 v[12:15], v[158:161], v[190:193], v[12:15]
	v_mfma_f32_16x16x32_bf16 v[60:63], v[154:157], v[170:173], v[60:63]
	v_mfma_f32_16x16x32_bf16 v[56:59], v[162:165], v[170:173], v[56:59]
	v_mfma_f32_16x16x32_bf16 v[52:55], v[154:157], v[178:181], v[52:55]
	v_mfma_f32_16x16x32_bf16 v[44:47], v[162:165], v[178:181], v[44:47]
	v_mfma_f32_16x16x32_bf16 v[36:39], v[154:157], v[186:189], v[36:39]
	v_mfma_f32_16x16x32_bf16 v[28:31], v[162:165], v[186:189], v[28:31]
	v_mfma_f32_16x16x32_bf16 v[20:23], v[154:157], v[194:197], v[20:23]
	v_mfma_f32_16x16x32_bf16 v[12:15], v[162:165], v[194:197], v[12:15]
	s_setprio 0
	s_barrier
	s_add_u32 s52, s56, 0xb0080
	s_addc_u32 s53, s57, 0
	s_add_i32 s56, s58, s11
	v_lshl_add_u64 v[144:145], s[52:53], 0, v[128:129]
	s_mov_b32 m0, s56
	s_nop 0
	global_load_lds_dwordx4 v[144:145], off
	v_lshl_add_u64 v[144:145], s[52:53], 0, v[130:131]
	s_add_i32 m0, s56, 0x2000
	s_nop 0
	global_load_lds_dwordx4 v[144:145], off
	s_waitcnt vmcnt(6)
	s_barrier
	s_setprio 1
	v_mfma_f32_16x16x32_bf16 v[48:51], v[198:201], v[166:169], v[48:51]
	v_mfma_f32_16x16x32_bf16 v[40:43], v[206:209], v[166:169], v[40:43]
	v_mfma_f32_16x16x32_bf16 v[32:35], v[198:201], v[174:177], v[32:35]
	v_mfma_f32_16x16x32_bf16 v[24:27], v[206:209], v[174:177], v[24:27]
	v_mfma_f32_16x16x32_bf16 v[16:19], v[198:201], v[182:185], v[16:19]
	v_mfma_f32_16x16x32_bf16 v[8:11], v[206:209], v[182:185], v[8:11]
	v_mfma_f32_16x16x32_bf16 v[4:7], v[198:201], v[190:193], v[4:7]
	v_mfma_f32_16x16x32_bf16 v[0:3], v[206:209], v[190:193], v[0:3]
	v_mfma_f32_16x16x32_bf16 v[48:51], v[202:205], v[170:173], v[48:51]
	v_mfma_f32_16x16x32_bf16 v[40:43], v[210:213], v[170:173], v[40:43]
	v_mfma_f32_16x16x32_bf16 v[32:35], v[202:205], v[178:181], v[32:35]
	v_mfma_f32_16x16x32_bf16 v[24:27], v[210:213], v[178:181], v[24:27]
	v_mfma_f32_16x16x32_bf16 v[16:19], v[202:205], v[186:189], v[16:19]
	v_mfma_f32_16x16x32_bf16 v[8:11], v[210:213], v[186:189], v[8:11]
	v_mfma_f32_16x16x32_bf16 v[4:7], v[202:205], v[194:197], v[4:7]
	v_mfma_f32_16x16x32_bf16 v[0:3], v[210:213], v[194:197], v[0:3]
	s_setprio 0
	s_add_i32 s77, s77, 2
	s_add_u32 s31, s31, 0x100
	s_addc_u32 s76, s76, 0
	s_cmp_gt_u32 s77, 41
	s_mov_b64 s[52:53], s[54:55]
	s_barrier
	s_cbranch_scc0 .LBB0_1954
	s_ashr_i32 s31, s30, 31
	s_lshl_b32 s52, s75, 8
	s_lshl_b64 s[30:31], s[30:31], 20
	s_ashr_i32 s53, s52, 31
	s_mov_b32 s100, 0x20000
	s_mov_b32 s101, 0
	v_lshl_add_u64 v[214:215], v[252:253], 0, s[100:101]
	global_load_dwordx4 v[150:153], v[214:215], off
	global_load_dwordx4 v[154:157], v[214:215], off offset:64
	global_load_dwordx4 v[158:161], v[214:215], off offset:512
	global_load_dwordx4 v[162:165], v[214:215], off offset:576
	s_mov_b32 s100, 0x30000
	s_mov_b32 s101, 0
	v_lshl_add_u64 v[216:217], v[252:253], 0, s[100:101]
	global_load_dwordx4 v[166:169], v[216:217], off
	global_load_dwordx4 v[170:173], v[216:217], off offset:64
	global_load_dwordx4 v[174:177], v[216:217], off offset:512
	global_load_dwordx4 v[178:181], v[216:217], off offset:576
	s_mov_b32 s100, 0x80000
	s_mov_b32 s101, 0
	v_lshl_add_u64 v[214:215], v[252:253], 0, s[100:101]
	global_load_dwordx4 v[182:185], v[214:215], off
	global_load_dwordx4 v[186:189], v[214:215], off offset:64
	global_load_dwordx4 v[190:193], v[214:215], off offset:512
	global_load_dwordx4 v[194:197], v[214:215], off offset:576
	s_mov_b32 s100, 0x90000
	s_mov_b32 s101, 0
	v_lshl_add_u64 v[216:217], v[252:253], 0, s[100:101]
	global_load_dwordx4 v[198:201], v[216:217], off
	global_load_dwordx4 v[202:205], v[216:217], off offset:64
	global_load_dwordx4 v[206:209], v[216:217], off offset:512
	global_load_dwordx4 v[210:213], v[216:217], off offset:576
	s_waitcnt vmcnt(16)
	v_pk_fma_f32 v[124:125], v[124:125], 0.5, v[220:221] op_sel_hi:[1,0,1]
	v_pk_fma_f32 v[126:127], v[126:127], 0.5, v[222:223] op_sel_hi:[1,0,1]
	v_pk_fma_f32 v[120:121], v[120:121], 0.5, v[224:225] op_sel_hi:[1,0,1]
	v_pk_fma_f32 v[122:123], v[122:123], 0.5, v[226:227] op_sel_hi:[1,0,1]
	v_pk_fma_f32 v[108:109], v[108:109], 0.5, v[228:229] op_sel_hi:[1,0,1]
	v_pk_fma_f32 v[110:111], v[110:111], 0.5, v[230:231] op_sel_hi:[1,0,1]
	v_pk_fma_f32 v[100:101], v[100:101], 0.5, v[232:233] op_sel_hi:[1,0,1]
	v_pk_fma_f32 v[102:103], v[102:103], 0.5, v[234:235] op_sel_hi:[1,0,1]
	v_pk_fma_f32 v[116:117], v[116:117], 0.5, v[236:237] op_sel_hi:[1,0,1]
	v_pk_fma_f32 v[118:119], v[118:119], 0.5, v[238:239] op_sel_hi:[1,0,1]
	v_pk_fma_f32 v[112:113], v[112:113], 0.5, v[240:241] op_sel_hi:[1,0,1]
	v_pk_fma_f32 v[114:115], v[114:115], 0.5, v[242:243] op_sel_hi:[1,0,1]
	v_pk_fma_f32 v[92:93], v[92:93], 0.5, v[244:245] op_sel_hi:[1,0,1]
	v_pk_fma_f32 v[94:95], v[94:95], 0.5, v[246:247] op_sel_hi:[1,0,1]
	v_pk_fma_f32 v[84:85], v[84:85], 0.5, v[248:249] op_sel_hi:[1,0,1]
	v_pk_fma_f32 v[86:87], v[86:87], 0.5, v[250:251] op_sel_hi:[1,0,1]
	s_mov_b32 s100, 0x0
	s_mov_b32 s101, 0
	v_lshl_add_u64 v[216:217], v[252:253], 0, s[100:101]
	global_store_dwordx4 v[216:217], v[124:127], off
	global_store_dwordx4 v[216:217], v[120:123], off offset:64
	global_store_dwordx4 v[216:217], v[108:111], off offset:512
	global_store_dwordx4 v[216:217], v[100:103], off offset:576
	s_mov_b32 s100, 0x10000
	s_mov_b32 s101, 0
	v_lshl_add_u64 v[218:219], v[252:253], 0, s[100:101]
	global_store_dwordx4 v[218:219], v[116:119], off
	global_store_dwordx4 v[218:219], v[112:115], off offset:64
	global_store_dwordx4 v[218:219], v[92:95], off offset:512
	global_store_dwordx4 v[218:219], v[84:87], off offset:576
	s_mov_b32 s100, 0xa0000
	s_mov_b32 s101, 0
	v_lshl_add_u64 v[214:215], v[252:253], 0, s[100:101]
	global_load_dwordx4 v[220:223], v[214:215], off
	global_load_dwordx4 v[224:227], v[214:215], off offset:64
	global_load_dwordx4 v[228:231], v[214:215], off offset:512
	global_load_dwordx4 v[232:235], v[214:215], off offset:576
	s_mov_b32 s100, 0xb0000
	s_mov_b32 s101, 0
	v_lshl_add_u64 v[216:217], v[252:253], 0, s[100:101]
	global_load_dwordx4 v[236:239], v[216:217], off
	global_load_dwordx4 v[240:243], v[216:217], off offset:64
	global_load_dwordx4 v[244:247], v[216:217], off offset:512
	global_load_dwordx4 v[248:251], v[216:217], off offset:576
	s_waitcnt vmcnt(24)
;     DI void operator()(const AccT& acc, const Unit& u, int wr, int wc, int fr, int fq) const {
; #pragma unroll
;         for (int ai = 0; ai < 2; ++ai) {
;             f32x4 h[4][2][2];
;             float* base = H + ((size_t)u.pm * 256 + ai * 128 + wr * 64 + fr) * 1024 + u.pn * 256 + wc * 32 + 4 * fq;
; #pragma unroll
;             for (int m = 0; m < 4; ++m)
; #pragma unroll
;                 for (int bj = 0; bj < 2; ++bj)
; #pragma unroll
;                     for (int n = 0; n < 2; ++n) h[m][bj][n] = *(const f32x4*)(base + (size_t)m * 16 * 1024 + bj * 128 + n * 16);
;             __builtin_amdgcn_sched_barrier(0);
; #pragma unroll
;             for (int m = 0; m < 4; ++m)
; #pragma unroll
;                 for (int bj = 0; bj < 2; ++bj)
; #pragma unroll
;                     for (int n = 0; n < 2; ++n) *(f32x4*)(base + (size_t)m * 16 * 1024 + bj * 128 + n * 16) = h[m][bj][n] + acc[ai][bj][m][n] * alpha;
;         }
;     }
	v_pk_fma_f32 v[104:105], v[104:105], 0.5, v[150:151] op_sel_hi:[1,0,1]
	v_pk_fma_f32 v[106:107], v[106:107], 0.5, v[152:153] op_sel_hi:[1,0,1]
	v_pk_fma_f32 v[96:97], v[96:97], 0.5, v[154:155] op_sel_hi:[1,0,1]
	v_pk_fma_f32 v[98:99], v[98:99], 0.5, v[156:157] op_sel_hi:[1,0,1]
	v_pk_fma_f32 v[76:77], v[76:77], 0.5, v[158:159] op_sel_hi:[1,0,1]
	v_pk_fma_f32 v[78:79], v[78:79], 0.5, v[160:161] op_sel_hi:[1,0,1]
	v_pk_fma_f32 v[72:73], v[72:73], 0.5, v[162:163] op_sel_hi:[1,0,1]
	v_pk_fma_f32 v[74:75], v[74:75], 0.5, v[164:165] op_sel_hi:[1,0,1]
	v_pk_fma_f32 v[88:89], v[88:89], 0.5, v[166:167] op_sel_hi:[1,0,1]
	v_pk_fma_f32 v[90:91], v[90:91], 0.5, v[168:169] op_sel_hi:[1,0,1]
	v_pk_fma_f32 v[80:81], v[80:81], 0.5, v[170:171] op_sel_hi:[1,0,1]
	v_pk_fma_f32 v[82:83], v[82:83], 0.5, v[172:173] op_sel_hi:[1,0,1]
	v_pk_fma_f32 v[68:69], v[68:69], 0.5, v[174:175] op_sel_hi:[1,0,1]
	v_pk_fma_f32 v[70:71], v[70:71], 0.5, v[176:177] op_sel_hi:[1,0,1]
	v_pk_fma_f32 v[64:65], v[64:65], 0.5, v[178:179] op_sel_hi:[1,0,1]
	v_pk_fma_f32 v[66:67], v[66:67], 0.5, v[180:181] op_sel_hi:[1,0,1]
	s_mov_b32 s100, 0x20000
	s_mov_b32 s101, 0
	v_lshl_add_u64 v[216:217], v[252:253], 0, s[100:101]
	global_store_dwordx4 v[216:217], v[104:107], off
	global_store_dwordx4 v[216:217], v[96:99], off offset:64
	global_store_dwordx4 v[216:217], v[76:79], off offset:512
	global_store_dwordx4 v[216:217], v[72:75], off offset:576
	s_mov_b32 s100, 0x30000
	s_mov_b32 s101, 0
	v_lshl_add_u64 v[218:219], v[252:253], 0, s[100:101]
	global_store_dwordx4 v[218:219], v[88:91], off
	global_store_dwordx4 v[218:219], v[80:83], off offset:64
	global_store_dwordx4 v[218:219], v[68:71], off offset:512
	global_store_dwordx4 v[218:219], v[64:67], off offset:576
	s_waitcnt vmcnt(24)
	v_pk_fma_f32 v[60:61], v[60:61], 0.5, v[182:183] op_sel_hi:[1,0,1]
	v_pk_fma_f32 v[62:63], v[62:63], 0.5, v[184:185] op_sel_hi:[1,0,1]
	v_pk_fma_f32 v[56:57], v[56:57], 0.5, v[186:187] op_sel_hi:[1,0,1]
	v_pk_fma_f32 v[58:59], v[58:59], 0.5, v[188:189] op_sel_hi:[1,0,1]
	v_pk_fma_f32 v[48:49], v[48:49], 0.5, v[190:191] op_sel_hi:[1,0,1]
	v_pk_fma_f32 v[50:51], v[50:51], 0.5, v[192:193] op_sel_hi:[1,0,1]
	v_pk_fma_f32 v[40:41], v[40:41], 0.5, v[194:195] op_sel_hi:[1,0,1]
	v_pk_fma_f32 v[42:43], v[42:43], 0.5, v[196:197] op_sel_hi:[1,0,1]
	v_pk_fma_f32 v[52:53], v[52:53], 0.5, v[198:199] op_sel_hi:[1,0,1]
	v_pk_fma_f32 v[54:55], v[54:55], 0.5, v[200:201] op_sel_hi:[1,0,1]
	v_pk_fma_f32 v[44:45], v[44:45], 0.5, v[202:203] op_sel_hi:[1,0,1]
	v_pk_fma_f32 v[46:47], v[46:47], 0.5, v[204:205] op_sel_hi:[1,0,1]
	v_pk_fma_f32 v[32:33], v[32:33], 0.5, v[206:207] op_sel_hi:[1,0,1]
	v_pk_fma_f32 v[34:35], v[34:35], 0.5, v[208:209] op_sel_hi:[1,0,1]
	v_pk_fma_f32 v[24:25], v[24:25], 0.5, v[210:211] op_sel_hi:[1,0,1]
	v_pk_fma_f32 v[26:27], v[26:27], 0.5, v[212:213] op_sel_hi:[1,0,1]
	s_mov_b32 s100, 0x80000
	s_mov_b32 s101, 0
	v_lshl_add_u64 v[216:217], v[252:253], 0, s[100:101]
	global_store_dwordx4 v[216:217], v[60:63], off
	global_store_dwordx4 v[216:217], v[56:59], off offset:64
	global_store_dwordx4 v[216:217], v[48:51], off offset:512
	global_store_dwordx4 v[216:217], v[40:43], off offset:576
	s_mov_b32 s100, 0x90000
	s_mov_b32 s101, 0
	v_lshl_add_u64 v[218:219], v[252:253], 0, s[100:101]
	global_store_dwordx4 v[218:219], v[52:55], off
	global_store_dwordx4 v[218:219], v[44:47], off offset:64
	global_store_dwordx4 v[218:219], v[32:35], off offset:512
	global_store_dwordx4 v[218:219], v[24:27], off offset:576
	s_waitcnt vmcnt(16)
	v_pk_fma_f32 v[36:37], v[36:37], 0.5, v[220:221] op_sel_hi:[1,0,1]
	v_pk_fma_f32 v[38:39], v[38:39], 0.5, v[222:223] op_sel_hi:[1,0,1]
	v_pk_fma_f32 v[28:29], v[28:29], 0.5, v[224:225] op_sel_hi:[1,0,1]
	v_pk_fma_f32 v[30:31], v[30:31], 0.5, v[226:227] op_sel_hi:[1,0,1]
	v_pk_fma_f32 v[16:17], v[16:17], 0.5, v[228:229] op_sel_hi:[1,0,1]
	v_pk_fma_f32 v[18:19], v[18:19], 0.5, v[230:231] op_sel_hi:[1,0,1]
	v_pk_fma_f32 v[8:9], v[8:9], 0.5, v[232:233] op_sel_hi:[1,0,1]
	v_pk_fma_f32 v[10:11], v[10:11], 0.5, v[234:235] op_sel_hi:[1,0,1]
	v_pk_fma_f32 v[20:21], v[20:21], 0.5, v[236:237] op_sel_hi:[1,0,1]
	v_pk_fma_f32 v[22:23], v[22:23], 0.5, v[238:239] op_sel_hi:[1,0,1]
	v_pk_fma_f32 v[12:13], v[12:13], 0.5, v[240:241] op_sel_hi:[1,0,1]
	v_pk_fma_f32 v[14:15], v[14:15], 0.5, v[242:243] op_sel_hi:[1,0,1]
	v_pk_fma_f32 v[4:5], v[4:5], 0.5, v[244:245] op_sel_hi:[1,0,1]
	v_pk_fma_f32 v[6:7], v[6:7], 0.5, v[246:247] op_sel_hi:[1,0,1]
	v_pk_fma_f32 v[0:1], v[0:1], 0.5, v[248:249] op_sel_hi:[1,0,1]
	v_pk_fma_f32 v[2:3], v[2:3], 0.5, v[250:251] op_sel_hi:[1,0,1]
	s_mov_b32 s100, 0xa0000
	s_mov_b32 s101, 0
	v_lshl_add_u64 v[216:217], v[252:253], 0, s[100:101]
	global_store_dwordx4 v[216:217], v[36:39], off
	global_store_dwordx4 v[216:217], v[28:31], off offset:64
	global_store_dwordx4 v[216:217], v[16:19], off offset:512
	global_store_dwordx4 v[216:217], v[8:11], off offset:576
	s_mov_b32 s100, 0xb0000
	s_mov_b32 s101, 0
	v_lshl_add_u64 v[218:219], v[252:253], 0, s[100:101]
	global_store_dwordx4 v[218:219], v[20:23], off
	global_store_dwordx4 v[218:219], v[12:15], off offset:64
	global_store_dwordx4 v[218:219], v[4:7], off offset:512
	global_store_dwordx4 v[218:219], v[0:3], off offset:576
	s_and_b64 vcc, exec, s[14:15]
	s_mov_b32 s75, s73
	s_mov_b32 s30, s74
	s_mov_b64 s[54:55], s[18:19]
	s_mov_b64 s[52:53], s[16:17]
	s_cbranch_vccz .LBB0_1943
	s_waitcnt vmcnt(0)
	s_cmpk_gt_u32 s8, 0xff
	s_cbranch_scc1 .LBB0_1958
	s_barrier

;     DI bool next(int i, Unit& u) const {
;         const long L = (long)i * G + c; if (L >= nwg) return false;
;         int wgid = (int)L; { const int q = nwg / NXCD, r = nwg % NXCD, xcd = wgid % NXCD, off = wgid / NXCD; wgid = (xcd < r ? xcd * (q + 1) : r * (q + 1) + (xcd - r) * q) + off; }
;         const int nig = WGM * nN, gid = wgid / nig, fm = gid * WGM, gsz = (nM - fm) < WGM ? (nM - fm) : WGM;
;         u.pm = fm + ((wgid % nig) % gsz); u.pn = (wgid % nig) / gsz; return true;
;     }
;     DI void operator()(const AccT& acc, const Unit& u, int wr, int wc, int fr, int fq) const {
;     ...
;             float* base = H + ((size_t)u.pm * 256 + ai * 128 + wr * 64 + fr) * 1024 + u.pn * 256 + wc * 32 + 4 * fq;
; #pragma unroll
;             for (int m = 0; m < 4; ++m)
; #pragma unroll
;                 for (int bj = 0; bj < 2; ++bj)
; #pragma unroll
;                     for (int n = 0; n < 2; ++n) h[m][bj][n] = *(const f32x4*)(base + (size_t)m * 16 * 1024 + bj * 128 + n * 16);
.LBB0_3001:
	s_mov_b32 s98, s28
	s_ashr_i32 s99, s28, 31
	s_lshl_b64 s[98:99], s[98:99], 20
	s_lshl_b32 s100, s71, 8
	s_ashr_i32 s101, s100, 31
	v_lshl_add_u64 v[252:253], v[134:135], 0, s[98:99]
	v_lshl_add_u64 v[252:253], s[100:101], 2, v[252:253]
	v_lshl_add_u64 v[252:253], v[252:253], 0, s[8:9]
	v_lshl_add_u64 v[252:253], v[252:253], 0, v[132:133]
	global_load_dwordx4 v[220:223], v[252:253], off
	global_load_dwordx4 v[224:227], v[252:253], off offset:64
	global_load_dwordx4 v[228:231], v[252:253], off offset:512
	global_load_dwordx4 v[232:235], v[252:253], off offset:576
	s_mov_b32 s100, 0x10000
	s_mov_b32 s101, 0
	v_lshl_add_u64 v[252:253], v[252:253], 0, s[100:101]
	global_load_dwordx4 v[236:239], v[252:253], off
	global_load_dwordx4 v[240:243], v[252:253], off offset:64
	global_load_dwordx4 v[244:247], v[252:253], off offset:512
	global_load_dwordx4 v[248:251], v[252:253], off offset:576
	s_mov_b32 s100, 0xffff0000
	s_mov_b32 s101, -1
	v_lshl_add_u64 v[252:253], v[252:253], 0, s[100:101]
	s_add_i32 s70, s70, 1
	s_mul_i32 s4, s70, s45
	s_mul_hi_u32 s5, s70, s44
	s_add_i32 s5, s5, s4
	s_mul_i32 s4, s70, s44
	s_add_u32 s24, s4, s2
	s_addc_u32 s25, s5, s3
	v_cmp_gt_i64_e64 s[4:5], s[24:25], v[142:143]
	s_and_b64 vcc, exec, s[4:5]
	s_cbranch_vccnz .LBB0_3007
	s_ashr_i32 s16, s24, 31
	s_lshr_b32 s16, s16, 29
	s_add_i32 s18, s24, s16
	s_and_b32 s16, s18, -8
	s_sub_i32 s19, s24, s16
	s_cmp_gt_i32 s19, 3
	s_mov_b64 s[16:17], -1
	s_cbranch_scc0 .LBB0_3004
	s_mul_i32 s16, s19, 0xa1
	s_add_i32 s26, s16, 4
	s_mov_b64 s[16:17], 0

; #define PG8_STAGE(bufoff, gbase, voff) do { _Pragma("unroll") for (int _i = 0; _i < 2; ++_i) \
;         __builtin_amdgcn_global_load_lds((const unsigned*)((const char*)(gbase) + (voff)[_i]), (LAS unsigned*)(lds + (bufoff) + ldsw + _i * 8192), 16, 0, 0); } while (0)
; #define PG8_LDA(dst, b, h) do { _Pragma("unroll") for (int m = 0; m < 4; ++m) _Pragma("unroll") for (int k = 0; k < 2; ++k) dst[m][k] = *(const LAS bf16x8*)(lds + PG8_SA(b, h) + aoff + m * 2048 + k * 1024); } while (0)
; #define PG8_LDB(dst, b, h) do { _Pragma("unroll") for (int n = 0; n < 2; ++n) _Pragma("unroll") for (int k = 0; k < 2; ++k) dst[n][k] = *(const LAS bf16x8*)(lds + PG8_SB(b, h) + boff + n * 2048 + k * 1024); } while (0)
; #define PG8_MMA(ai, bj, At, Bt) do { __builtin_amdgcn_s_setprio(1); _Pragma("unroll") for (int m = 0; m < 4; ++m) _Pragma("unroll") for (int n = 0; n < 2; ++n) _Pragma("unroll") for (int k = 0; k < 2; ++k) \
;         acc[ai][bj][m][n] = __builtin_amdgcn_mfma_f32_16x16x32_bf16(Bt[n][k], At[m][k], acc[ai][bj][m][n], 0, 0, 0); __builtin_amdgcn_s_setprio(0); } while (0)
; #define PG8_WAIT_L(n) asm volatile("s_waitcnt lgkmcnt(" #n ")" ::: "memory")
; #define PG8_BAR __builtin_amdgcn_s_barrier()
; #define PG8_SCHED __builtin_amdgcn_sched_barrier(0)
; template <class Epi>
; DI void gemm_phase(int wv, LAS unsigned char* lds, const Gemm g, const StaticOrder& S, const Epi& E) {
;     ...
;         for (int t = 0; t < nt; t += 2) {
;             const bool last = (t == nt - 2);
;             const char* a1 = cA + (size_t)(t + 1) * kstep;
;             const char* a2 = last ? nA : cA + (size_t)(t + 2) * kstep; const char* b2 = last ? nB : cB + (size_t)(t + 2) * kstep;
;             const char* a3 = a2 + kstep; const char* b3 = b2 + kstep;
;             PG8_LDB(B0, 0, 0); PG8_SCHED; PG8_LDA(At, 0, 0); PG8_STAGE(PG8_SA(1, 1), a1 + hstep, voffA);
;             PG8_WAIT_L(8); PG8_BAR; PG8_WAIT_L(0); PG8_MMA(0, 0, At, B0); PG8_BAR; PG8_SCHED;
;             PG8_LDB(B1, 0, 1); PG8_STAGE(PG8_SB(0, 0), b2, voffB);
;             PG8_BAR; PG8_WAIT_L(0); PG8_MMA(0, 1, At, B1); PG8_BAR;
;             PG8_LDA(At, 0, 1); PG8_STAGE(PG8_SA(0, 0), a2, voffA);
;             PG8_BAR; PG8_WAIT_L(0); PG8_MMA(1, 0, At, B0); PG8_BAR; PG8_SCHED;
.LBB0_3008:
	ds_read_b128 v[150:153], v147
	ds_read_b128 v[154:157], v147 offset:1024
	ds_read_b128 v[158:161], v147 offset:2048
	ds_read_b128 v[162:165], v147 offset:3072
	s_add_u32 s36, s30, 0x100
	s_addc_u32 s37, s31, 0
	s_cmp_eq_u32 s75, 12
	s_cselect_b32 s49, s19, s37
	s_cselect_b32 s48, s29, s36
	s_cselect_b32 s47, s17, s74
	s_cselect_b32 s46, s72, s73
	v_lshl_add_u64 v[144:145], s[30:31], 0, v[136:137]
	s_add_i32 m0, s55, 0xc000
	ds_read_b128 v[166:169], v148
	ds_read_b128 v[170:173], v148 offset:1024
	ds_read_b128 v[174:177], v148 offset:2048
	ds_read_b128 v[178:181], v148 offset:3072
	ds_read_b128 v[182:185], v148 offset:4096
	ds_read_b128 v[186:189], v148 offset:5120
	ds_read_b128 v[190:193], v148 offset:6144
	ds_read_b128 v[194:197], v148 offset:7168
	global_load_lds_dwordx4 v[144:145], off
	v_lshl_add_u64 v[144:145], s[30:31], 0, v[138:139]
	s_add_i32 m0, s55, 0xe000
	s_nop 0
	global_load_lds_dwordx4 v[144:145], off
	s_waitcnt lgkmcnt(8)
	s_barrier
	s_waitcnt lgkmcnt(0)
	s_setprio 1
	s_waitcnt lgkmcnt(0)
	v_mfma_f32_16x16x32_bf16 v[124:127], v[150:153], v[166:169], v[124:127]
	v_mfma_f32_16x16x32_bf16 v[120:123], v[158:161], v[166:169], v[120:123]
	v_mfma_f32_16x16x32_bf16 v[116:119], v[150:153], v[174:177], v[116:119]
	v_mfma_f32_16x16x32_bf16 v[112:115], v[158:161], v[174:177], v[112:115]
	v_mfma_f32_16x16x32_bf16 v[104:107], v[150:153], v[182:185], v[104:107]
	v_mfma_f32_16x16x32_bf16 v[96:99], v[158:161], v[182:185], v[96:99]
	v_mfma_f32_16x16x32_bf16 v[88:91], v[150:153], v[190:193], v[88:91]
	v_mfma_f32_16x16x32_bf16 v[80:83], v[158:161], v[190:193], v[80:83]
	v_mfma_f32_16x16x32_bf16 v[124:127], v[154:157], v[170:173], v[124:127]
	v_mfma_f32_16x16x32_bf16 v[120:123], v[162:165], v[170:173], v[120:123]
	v_mfma_f32_16x16x32_bf16 v[116:119], v[154:157], v[178:181], v[116:119]
	v_mfma_f32_16x16x32_bf16 v[112:115], v[162:165], v[178:181], v[112:115]
	v_mfma_f32_16x16x32_bf16 v[104:107], v[154:157], v[186:189], v[104:107]
	v_mfma_f32_16x16x32_bf16 v[96:99], v[162:165], v[186:189], v[96:99]
	v_mfma_f32_16x16x32_bf16 v[88:91], v[154:157], v[194:197], v[88:91]
	v_mfma_f32_16x16x32_bf16 v[80:83], v[162:165], v[194:197], v[80:83]
	s_setprio 0
	s_barrier
	s_add_i32 s30, s62, s54
	v_lshl_add_u64 v[144:145], s[46:47], 0, v[128:129]
	s_mov_b32 m0, s30
	ds_read_b128 v[198:201], v149
	ds_read_b128 v[202:205], v149 offset:1024
	ds_read_b128 v[206:209], v149 offset:2048
	ds_read_b128 v[210:213], v149 offset:3072
	global_load_lds_dwordx4 v[144:145], off
	v_lshl_add_u64 v[214:215], s[46:47], 0, v[130:131]
	s_add_i32 m0, s30, 0x2000
	s_nop 0
	global_load_lds_dwordx4 v[214:215], off
	s_barrier
	s_waitcnt lgkmcnt(0)
	s_setprio 1
	s_waitcnt lgkmcnt(0)
	v_mfma_f32_16x16x32_bf16 v[108:111], v[198:201], v[166:169], v[108:111]
	v_mfma_f32_16x16x32_bf16 v[100:103], v[206:209], v[166:169], v[100:103]
	v_mfma_f32_16x16x32_bf16 v[92:95], v[198:201], v[174:177], v[92:95]
	v_mfma_f32_16x16x32_bf16 v[84:87], v[206:209], v[174:177], v[84:87]
	v_mfma_f32_16x16x32_bf16 v[76:79], v[198:201], v[182:185], v[76:79]
	v_mfma_f32_16x16x32_bf16 v[72:75], v[206:209], v[182:185], v[72:75]
	v_mfma_f32_16x16x32_bf16 v[68:71], v[198:201], v[190:193], v[68:71]
	v_mfma_f32_16x16x32_bf16 v[64:67], v[206:209], v[190:193], v[64:67]
	v_mfma_f32_16x16x32_bf16 v[108:111], v[202:205], v[170:173], v[108:111]
	v_mfma_f32_16x16x32_bf16 v[100:103], v[210:213], v[170:173], v[100:103]
	v_mfma_f32_16x16x32_bf16 v[92:95], v[202:205], v[178:181], v[92:95]
	v_mfma_f32_16x16x32_bf16 v[84:87], v[210:213], v[178:181], v[84:87]
	v_mfma_f32_16x16x32_bf16 v[76:79], v[202:205], v[186:189], v[76:79]
	v_mfma_f32_16x16x32_bf16 v[72:75], v[210:213], v[186:189], v[72:75]
	v_mfma_f32_16x16x32_bf16 v[68:71], v[202:205], v[194:197], v[68:71]
	v_mfma_f32_16x16x32_bf16 v[64:67], v[210:213], v[194:197], v[64:67]
	s_setprio 0
	s_mov_b32 m0, s55
	v_lshl_add_u64 v[216:217], s[48:49], 0, v[128:129]
	s_barrier
	ds_read_b128 v[166:169], v148 offset:16384
	ds_read_b128 v[170:173], v148 offset:17408
	ds_read_b128 v[174:177], v148 offset:18432
	ds_read_b128 v[178:181], v148 offset:19456
	ds_read_b128 v[182:185], v148 offset:20480
	ds_read_b128 v[186:189], v148 offset:21504
	ds_read_b128 v[190:193], v148 offset:22528
	ds_read_b128 v[194:197], v148 offset:23552
	global_load_lds_dwordx4 v[216:217], off
	v_lshl_add_u64 v[218:219], s[48:49], 0, v[130:131]
	s_mov_b32 m0, s56
	s_nop 0
	global_load_lds_dwordx4 v[218:219], off
	s_barrier
	s_waitcnt lgkmcnt(0)
	s_setprio 1
	s_waitcnt lgkmcnt(0)
	v_mfma_f32_16x16x32_bf16 v[60:63], v[150:153], v[166:169], v[60:63]
	v_mfma_f32_16x16x32_bf16 v[56:59], v[158:161], v[166:169], v[56:59]
	v_mfma_f32_16x16x32_bf16 v[52:55], v[150:153], v[174:177], v[52:55]
	v_mfma_f32_16x16x32_bf16 v[44:47], v[158:161], v[174:177], v[44:47]
	v_mfma_f32_16x16x32_bf16 v[36:39], v[150:153], v[182:185], v[36:39]
	v_mfma_f32_16x16x32_bf16 v[28:31], v[158:161], v[182:185], v[28:31]
	v_mfma_f32_16x16x32_bf16 v[20:23], v[150:153], v[190:193], v[20:23]
	v_mfma_f32_16x16x32_bf16 v[12:15], v[158:161], v[190:193], v[12:15]
	v_mfma_f32_16x16x32_bf16 v[60:63], v[154:157], v[170:173], v[60:63]
	v_mfma_f32_16x16x32_bf16 v[56:59], v[162:165], v[170:173], v[56:59]
	v_mfma_f32_16x16x32_bf16 v[52:55], v[154:157], v[178:181], v[52:55]
	v_mfma_f32_16x16x32_bf16 v[44:47], v[162:165], v[178:181], v[44:47]
	v_mfma_f32_16x16x32_bf16 v[36:39], v[154:157], v[186:189], v[36:39]
	v_mfma_f32_16x16x32_bf16 v[28:31], v[162:165], v[186:189], v[28:31]
	v_mfma_f32_16x16x32_bf16 v[20:23], v[154:157], v[194:197], v[20:23]
	v_mfma_f32_16x16x32_bf16 v[12:15], v[162:165], v[194:197], v[12:15]
	s_setprio 0
	s_barrier
; #define PG8_STAGE(bufoff, gbase, voff) do { _Pragma("unroll") for (int _i = 0; _i < 2; ++_i) \
;         __builtin_amdgcn_global_load_lds((const unsigned*)((const char*)(gbase) + (voff)[_i]), (LAS unsigned*)(lds + (bufoff) + ldsw + _i * 8192), 16, 0, 0); } while (0)
; #define PG8_LDA(dst, b, h) do { _Pragma("unroll") for (int m = 0; m < 4; ++m) _Pragma("unroll") for (int k = 0; k < 2; ++k) dst[m][k] = *(const LAS bf16x8*)(lds + PG8_SA(b, h) + aoff + m * 2048 + k * 1024); } while (0)
; #define PG8_LDB(dst, b, h) do { _Pragma("unroll") for (int n = 0; n < 2; ++n) _Pragma("unroll") for (int k = 0; k < 2; ++k) dst[n][k] = *(const LAS bf16x8*)(lds + PG8_SB(b, h) + boff + n * 2048 + k * 1024); } while (0)
; #define PG8_MMA(ai, bj, At, Bt) do { __builtin_amdgcn_s_setprio(1); _Pragma("unroll") for (int m = 0; m < 4; ++m) _Pragma("unroll") for (int n = 0; n < 2; ++n) _Pragma("unroll") for (int k = 0; k < 2; ++k) \
;         acc[ai][bj][m][n] = __builtin_amdgcn_mfma_f32_16x16x32_bf16(Bt[n][k], At[m][k], acc[ai][bj][m][n], 0, 0, 0); __builtin_amdgcn_s_setprio(0); } while (0)
; #define PG8_WAIT_V(n) asm volatile("s_waitcnt vmcnt(" #n ")" ::: "memory")
; #define PG8_WAIT_L(n) asm volatile("s_waitcnt lgkmcnt(" #n ")" ::: "memory")
; #define PG8_BAR __builtin_amdgcn_s_barrier()
; #define PG8_SCHED __builtin_amdgcn_sched_barrier(0)
; template <class Epi>
; DI void gemm_phase(int wv, LAS unsigned char* lds, const Gemm g, const StaticOrder& S, const Epi& E) {
;     ...
;             PG8_STAGE(PG8_SB(0, 1), b2 + hstep, voffB);
;             PG8_WAIT_V(6); PG8_BAR; PG8_MMA(1, 1, At, B1); PG8_BAR;
;             PG8_LDB(B0, 1, 0); PG8_SCHED; PG8_LDA(At, 1, 0); PG8_STAGE(PG8_SA(0, 1), a2 + hstep, voffA);
;             PG8_WAIT_L(8); PG8_BAR; PG8_WAIT_L(0); PG8_MMA(0, 0, At, B0); PG8_BAR; PG8_SCHED;
;             PG8_LDB(B1, 1, 1); PG8_STAGE(PG8_SB(1, 0), b3, voffB);
;             PG8_BAR; PG8_WAIT_L(0); PG8_MMA(0, 1, At, B1); PG8_BAR;
;             PG8_LDA(At, 1, 1); PG8_STAGE(PG8_SA(1, 0), a3, voffA);
;             PG8_BAR; PG8_WAIT_L(0); PG8_MMA(1, 0, At, B0); PG8_BAR; PG8_SCHED;
	s_add_u32 s30, s46, 0x40000
	s_addc_u32 s31, s47, 0
	s_add_i32 s76, s63, s54
	v_lshl_add_u64 v[150:151], s[30:31], 0, v[128:129]
	s_mov_b32 m0, s76
	s_nop 0
	global_load_lds_dwordx4 v[150:151], off
	v_lshl_add_u64 v[150:151], s[30:31], 0, v[130:131]
	s_add_i32 m0, s76, 0x2000
	s_nop 0
	global_load_lds_dwordx4 v[150:151], off
	s_waitcnt vmcnt(6)
	s_barrier
	s_setprio 1
	v_mfma_f32_16x16x32_bf16 v[48:51], v[198:201], v[166:169], v[48:51]
	v_mfma_f32_16x16x32_bf16 v[40:43], v[206:209], v[166:169], v[40:43]
	v_mfma_f32_16x16x32_bf16 v[32:35], v[198:201], v[174:177], v[32:35]
	v_mfma_f32_16x16x32_bf16 v[24:27], v[206:209], v[174:177], v[24:27]
	v_mfma_f32_16x16x32_bf16 v[16:19], v[198:201], v[182:185], v[16:19]
	v_mfma_f32_16x16x32_bf16 v[8:11], v[206:209], v[182:185], v[8:11]
	v_mfma_f32_16x16x32_bf16 v[4:7], v[198:201], v[190:193], v[4:7]
	v_mfma_f32_16x16x32_bf16 v[0:3], v[206:209], v[190:193], v[0:3]
	v_mfma_f32_16x16x32_bf16 v[48:51], v[202:205], v[170:173], v[48:51]
	v_mfma_f32_16x16x32_bf16 v[40:43], v[210:213], v[170:173], v[40:43]
	v_mfma_f32_16x16x32_bf16 v[32:35], v[202:205], v[178:181], v[32:35]
	v_mfma_f32_16x16x32_bf16 v[24:27], v[210:213], v[178:181], v[24:27]
	v_mfma_f32_16x16x32_bf16 v[16:19], v[202:205], v[186:189], v[16:19]
	v_mfma_f32_16x16x32_bf16 v[8:11], v[210:213], v[186:189], v[8:11]
	v_mfma_f32_16x16x32_bf16 v[4:7], v[202:205], v[194:197], v[4:7]
	v_mfma_f32_16x16x32_bf16 v[0:3], v[210:213], v[194:197], v[0:3]
	s_setprio 0
	s_add_i32 s76, 0, 0x18000
	v_add_u32_e32 v162, s76, v146
	s_barrier
	ds_read_b128 v[150:153], v162
	ds_read_b128 v[154:157], v162 offset:1024
	ds_read_b128 v[158:161], v162 offset:2048
	ds_read_b128 v[162:165], v162 offset:3072
	s_add_u32 s30, s48, 0x40000
	s_addc_u32 s31, s49, 0
	s_mov_b32 m0, s57
	v_lshl_add_u64 v[198:199], s[30:31], 0, v[128:129]
	ds_read_b128 v[166:169], v148 offset:32768
	ds_read_b128 v[170:173], v148 offset:33792
	ds_read_b128 v[174:177], v148 offset:34816
	ds_read_b128 v[178:181], v148 offset:35840
	ds_read_b128 v[182:185], v148 offset:36864
	ds_read_b128 v[186:189], v148 offset:37888
	ds_read_b128 v[190:193], v148 offset:38912
	ds_read_b128 v[194:197], v148 offset:39936
	global_load_lds_dwordx4 v[198:199], off
	v_lshl_add_u64 v[198:199], s[30:31], 0, v[130:131]
	s_mov_b32 m0, s58
	s_nop 0
	global_load_lds_dwordx4 v[198:199], off
	s_waitcnt lgkmcnt(8)
	s_barrier
	s_waitcnt lgkmcnt(0)
	s_setprio 1
	s_waitcnt lgkmcnt(0)
	v_mfma_f32_16x16x32_bf16 v[124:127], v[150:153], v[166:169], v[124:127]
	v_mfma_f32_16x16x32_bf16 v[120:123], v[158:161], v[166:169], v[120:123]
	v_mfma_f32_16x16x32_bf16 v[116:119], v[150:153], v[174:177], v[116:119]
	v_mfma_f32_16x16x32_bf16 v[112:115], v[158:161], v[174:177], v[112:115]
	v_mfma_f32_16x16x32_bf16 v[104:107], v[150:153], v[182:185], v[104:107]
	v_mfma_f32_16x16x32_bf16 v[96:99], v[158:161], v[182:185], v[96:99]
	v_mfma_f32_16x16x32_bf16 v[88:91], v[150:153], v[190:193], v[88:91]
	v_mfma_f32_16x16x32_bf16 v[80:83], v[158:161], v[190:193], v[80:83]
	v_mfma_f32_16x16x32_bf16 v[124:127], v[154:157], v[170:173], v[124:127]
	v_mfma_f32_16x16x32_bf16 v[120:123], v[162:165], v[170:173], v[120:123]
	v_mfma_f32_16x16x32_bf16 v[116:119], v[154:157], v[178:181], v[116:119]
	v_mfma_f32_16x16x32_bf16 v[112:115], v[162:165], v[178:181], v[112:115]
	v_mfma_f32_16x16x32_bf16 v[104:107], v[154:157], v[186:189], v[104:107]
	v_mfma_f32_16x16x32_bf16 v[96:99], v[162:165], v[186:189], v[96:99]
	v_mfma_f32_16x16x32_bf16 v[88:91], v[154:157], v[194:197], v[88:91]
	v_mfma_f32_16x16x32_bf16 v[80:83], v[162:165], v[194:197], v[80:83]
	s_setprio 0
	s_barrier
	s_add_i32 s48, 0, 0x1c000
	s_add_i32 s30, s76, s54
	v_add_u32_e32 v210, s48, v146
	v_lshl_add_u64 v[144:145], v[144:145], 0, s[10:11]
	s_mov_b32 m0, s30
	ds_read_b128 v[198:201], v210
	ds_read_b128 v[202:205], v210 offset:1024
	ds_read_b128 v[206:209], v210 offset:2048
	ds_read_b128 v[210:213], v210 offset:3072
	global_load_lds_dwordx4 v[144:145], off
	v_lshl_add_u64 v[144:145], v[214:215], 0, s[10:11]
	s_add_i32 m0, s30, 0x2000
	s_nop 0
	global_load_lds_dwordx4 v[144:145], off
	s_barrier
	s_waitcnt lgkmcnt(0)
	s_setprio 1
	s_waitcnt lgkmcnt(0)
	v_mfma_f32_16x16x32_bf16 v[108:111], v[198:201], v[166:169], v[108:111]
	v_mfma_f32_16x16x32_bf16 v[100:103], v[206:209], v[166:169], v[100:103]
	v_mfma_f32_16x16x32_bf16 v[92:95], v[198:201], v[174:177], v[92:95]
	v_mfma_f32_16x16x32_bf16 v[84:87], v[206:209], v[174:177], v[84:87]
	v_mfma_f32_16x16x32_bf16 v[76:79], v[198:201], v[182:185], v[76:79]
	v_mfma_f32_16x16x32_bf16 v[72:75], v[206:209], v[182:185], v[72:75]
	v_mfma_f32_16x16x32_bf16 v[68:71], v[198:201], v[190:193], v[68:71]
	v_mfma_f32_16x16x32_bf16 v[64:67], v[206:209], v[190:193], v[64:67]
	v_mfma_f32_16x16x32_bf16 v[108:111], v[202:205], v[170:173], v[108:111]
	v_mfma_f32_16x16x32_bf16 v[100:103], v[210:213], v[170:173], v[100:103]
	v_mfma_f32_16x16x32_bf16 v[92:95], v[202:205], v[178:181], v[92:95]
	v_mfma_f32_16x16x32_bf16 v[84:87], v[210:213], v[178:181], v[84:87]
	v_mfma_f32_16x16x32_bf16 v[76:79], v[202:205], v[186:189], v[76:79]
	v_mfma_f32_16x16x32_bf16 v[72:75], v[210:213], v[186:189], v[72:75]
	v_mfma_f32_16x16x32_bf16 v[68:71], v[202:205], v[194:197], v[68:71]
	v_mfma_f32_16x16x32_bf16 v[64:67], v[210:213], v[194:197], v[64:67]
	s_setprio 0
	s_mov_b32 m0, s60
	v_lshl_add_u64 v[144:145], v[216:217], 0, s[10:11]
	s_barrier
	ds_read_b128 v[166:169], v148 offset:49152
	ds_read_b128 v[170:173], v148 offset:50176
	ds_read_b128 v[174:177], v148 offset:51200
	ds_read_b128 v[178:181], v148 offset:52224
	ds_read_b128 v[182:185], v148 offset:53248
	ds_read_b128 v[186:189], v148 offset:54272
	ds_read_b128 v[190:193], v148 offset:55296
	ds_read_b128 v[194:197], v148 offset:56320
	global_load_lds_dwordx4 v[144:145], off
	v_lshl_add_u64 v[144:145], v[218:219], 0, s[10:11]
	s_mov_b32 m0, s61
	s_nop 0
	global_load_lds_dwordx4 v[144:145], off
	s_barrier
; #define PG8_STAGE(bufoff, gbase, voff) do { _Pragma("unroll") for (int _i = 0; _i < 2; ++_i) \
;         __builtin_amdgcn_global_load_lds((const unsigned*)((const char*)(gbase) + (voff)[_i]), (LAS unsigned*)(lds + (bufoff) + ldsw + _i * 8192), 16, 0, 0); } while (0)
; #define PG8_MMA(ai, bj, At, Bt) do { __builtin_amdgcn_s_setprio(1); _Pragma("unroll") for (int m = 0; m < 4; ++m) _Pragma("unroll") for (int n = 0; n < 2; ++n) _Pragma("unroll") for (int k = 0; k < 2; ++k) \
;         acc[ai][bj][m][n] = __builtin_amdgcn_mfma_f32_16x16x32_bf16(Bt[n][k], At[m][k], acc[ai][bj][m][n], 0, 0, 0); __builtin_amdgcn_s_setprio(0); } while (0)
; #define PG8_WAIT_V(n) asm volatile("s_waitcnt vmcnt(" #n ")" ::: "memory")
; #define PG8_WAIT_L(n) asm volatile("s_waitcnt lgkmcnt(" #n ")" ::: "memory")
; #define PG8_BAR __builtin_amdgcn_s_barrier()
; #define PG8_SCHED __builtin_amdgcn_sched_barrier(0)
; template <class Epi>
; DI void gemm_phase(int wv, LAS unsigned char* lds, const Gemm g, const StaticOrder& S, const Epi& E) {
;     ...
;             PG8_BAR; PG8_WAIT_L(0); PG8_MMA(1, 0, At, B0); PG8_BAR; PG8_SCHED;
;             PG8_STAGE(PG8_SB(1, 1), b3 + hstep, voffB);
;             PG8_WAIT_V(6); PG8_BAR; PG8_MMA(1, 1, At, B1); PG8_BAR;
;         }
;         E(acc, cur, wr, wc, fr, fq);
;     DI void operator()(const AccT& acc, const Unit& u, int wr, int wc, int fr, int fq) const {
; #pragma unroll
;         for (int ai = 0; ai < 2; ++ai) {
;             f32x4 h[4][2][2];
;             float* base = H + ((size_t)u.pm * 256 + ai * 128 + wr * 64 + fr) * 1024 + u.pn * 256 + wc * 32 + 4 * fq;
; #pragma unroll
;             for (int m = 0; m < 4; ++m)
; #pragma unroll
;                 for (int bj = 0; bj < 2; ++bj)
; #pragma unroll
;                     for (int n = 0; n < 2; ++n) h[m][bj][n] = *(const f32x4*)(base + (size_t)m * 16 * 1024 + bj * 128 + n * 16);
;             __builtin_amdgcn_sched_barrier(0);
; #pragma unroll
;             for (int m = 0; m < 4; ++m)
; #pragma unroll
;                 for (int bj = 0; bj < 2; ++bj)
; #pragma unroll
;                     for (int n = 0; n < 2; ++n) *(f32x4*)(base + (size_t)m * 16 * 1024 + bj * 128 + n * 16) = h[m][bj][n] + acc[ai][bj][m][n] * alpha;
;         }
;     }
	s_waitcnt lgkmcnt(0)
	s_setprio 1
	s_waitcnt lgkmcnt(0)
	v_mfma_f32_16x16x32_bf16 v[60:63], v[150:153], v[166:169], v[60:63]
	v_mfma_f32_16x16x32_bf16 v[56:59], v[158:161], v[166:169], v[56:59]
	v_mfma_f32_16x16x32_bf16 v[52:55], v[150:153], v[174:177], v[52:55]
	v_mfma_f32_16x16x32_bf16 v[44:47], v[158:161], v[174:177], v[44:47]
	v_mfma_f32_16x16x32_bf16 v[36:39], v[150:153], v[182:185], v[36:39]
	v_mfma_f32_16x16x32_bf16 v[28:31], v[158:161], v[182:185], v[28:31]
	v_mfma_f32_16x16x32_bf16 v[20:23], v[150:153], v[190:193], v[20:23]
	v_mfma_f32_16x16x32_bf16 v[12:15], v[158:161], v[190:193], v[12:15]
	v_mfma_f32_16x16x32_bf16 v[60:63], v[154:157], v[170:173], v[60:63]
	v_mfma_f32_16x16x32_bf16 v[56:59], v[162:165], v[170:173], v[56:59]
	v_mfma_f32_16x16x32_bf16 v[52:55], v[154:157], v[178:181], v[52:55]
	v_mfma_f32_16x16x32_bf16 v[44:47], v[162:165], v[178:181], v[44:47]
	v_mfma_f32_16x16x32_bf16 v[36:39], v[154:157], v[186:189], v[36:39]
	v_mfma_f32_16x16x32_bf16 v[28:31], v[162:165], v[186:189], v[28:31]
	v_mfma_f32_16x16x32_bf16 v[20:23], v[154:157], v[194:197], v[20:23]
	v_mfma_f32_16x16x32_bf16 v[12:15], v[162:165], v[194:197], v[12:15]
	s_setprio 0
	s_barrier
	s_add_u32 s30, s46, 0x40080
	s_addc_u32 s31, s47, 0
	s_add_i32 s46, s48, s54
	v_lshl_add_u64 v[144:145], s[30:31], 0, v[128:129]
	s_mov_b32 m0, s46
	s_nop 0
	global_load_lds_dwordx4 v[144:145], off
	v_lshl_add_u64 v[144:145], s[30:31], 0, v[130:131]
	s_add_i32 m0, s46, 0x2000
	s_nop 0
	global_load_lds_dwordx4 v[144:145], off
	s_waitcnt vmcnt(6)
	s_barrier
	s_setprio 1
	v_mfma_f32_16x16x32_bf16 v[48:51], v[198:201], v[166:169], v[48:51]
	v_mfma_f32_16x16x32_bf16 v[40:43], v[206:209], v[166:169], v[40:43]
	v_mfma_f32_16x16x32_bf16 v[32:35], v[198:201], v[174:177], v[32:35]
	v_mfma_f32_16x16x32_bf16 v[24:27], v[206:209], v[174:177], v[24:27]
	v_mfma_f32_16x16x32_bf16 v[16:19], v[198:201], v[182:185], v[16:19]
	v_mfma_f32_16x16x32_bf16 v[8:11], v[206:209], v[182:185], v[8:11]
	v_mfma_f32_16x16x32_bf16 v[4:7], v[198:201], v[190:193], v[4:7]
	v_mfma_f32_16x16x32_bf16 v[0:3], v[206:209], v[190:193], v[0:3]
	v_mfma_f32_16x16x32_bf16 v[48:51], v[202:205], v[170:173], v[48:51]
	v_mfma_f32_16x16x32_bf16 v[40:43], v[210:213], v[170:173], v[40:43]
	v_mfma_f32_16x16x32_bf16 v[32:35], v[202:205], v[178:181], v[32:35]
	v_mfma_f32_16x16x32_bf16 v[24:27], v[210:213], v[178:181], v[24:27]
	v_mfma_f32_16x16x32_bf16 v[16:19], v[202:205], v[186:189], v[16:19]
	v_mfma_f32_16x16x32_bf16 v[8:11], v[210:213], v[186:189], v[8:11]
	v_mfma_f32_16x16x32_bf16 v[4:7], v[202:205], v[194:197], v[4:7]
	v_mfma_f32_16x16x32_bf16 v[0:3], v[210:213], v[194:197], v[0:3]
	s_setprio 0
	s_add_i32 s75, s75, 2
	s_add_u32 s73, s73, 0x100
	s_addc_u32 s74, s74, 0
	s_cmp_gt_u32 s75, 13
	s_mov_b64 s[30:31], s[36:37]
	s_barrier
	s_cbranch_scc0 .LBB0_3008
	s_ashr_i32 s29, s28, 31
	s_lshl_b32 s30, s71, 8
	s_lshl_b64 s[28:29], s[28:29], 20
	s_ashr_i32 s31, s30, 31
	s_mov_b32 s100, 0x20000
	s_mov_b32 s101, 0
	v_lshl_add_u64 v[214:215], v[252:253], 0, s[100:101]
	global_load_dwordx4 v[150:153], v[214:215], off
	global_load_dwordx4 v[154:157], v[214:215], off offset:64
	global_load_dwordx4 v[158:161], v[214:215], off offset:512
	global_load_dwordx4 v[162:165], v[214:215], off offset:576
	s_mov_b32 s100, 0x30000
	s_mov_b32 s101, 0
	v_lshl_add_u64 v[216:217], v[252:253], 0, s[100:101]
	global_load_dwordx4 v[166:169], v[216:217], off
	global_load_dwordx4 v[170:173], v[216:217], off offset:64
	global_load_dwordx4 v[174:177], v[216:217], off offset:512
	global_load_dwordx4 v[178:181], v[216:217], off offset:576
	s_mov_b32 s100, 0x80000
	s_mov_b32 s101, 0
	v_lshl_add_u64 v[214:215], v[252:253], 0, s[100:101]
	global_load_dwordx4 v[182:185], v[214:215], off
	global_load_dwordx4 v[186:189], v[214:215], off offset:64
	global_load_dwordx4 v[190:193], v[214:215], off offset:512
	global_load_dwordx4 v[194:197], v[214:215], off offset:576
	s_mov_b32 s100, 0x90000
	s_mov_b32 s101, 0
	v_lshl_add_u64 v[216:217], v[252:253], 0, s[100:101]
	global_load_dwordx4 v[198:201], v[216:217], off
	global_load_dwordx4 v[202:205], v[216:217], off offset:64
	global_load_dwordx4 v[206:209], v[216:217], off offset:512
	global_load_dwordx4 v[210:213], v[216:217], off offset:576
	s_waitcnt vmcnt(16)
	v_pk_add_f32 v[124:125], v[124:125], v[220:221]
	v_pk_add_f32 v[126:127], v[126:127], v[222:223]
	v_pk_add_f32 v[120:121], v[120:121], v[224:225]
	v_pk_add_f32 v[122:123], v[122:123], v[226:227]
	v_pk_add_f32 v[108:109], v[108:109], v[228:229]
	v_pk_add_f32 v[110:111], v[110:111], v[230:231]
	v_pk_add_f32 v[100:101], v[100:101], v[232:233]
	v_pk_add_f32 v[102:103], v[102:103], v[234:235]
	v_pk_add_f32 v[116:117], v[116:117], v[236:237]
	v_pk_add_f32 v[118:119], v[118:119], v[238:239]
	v_pk_add_f32 v[112:113], v[112:113], v[240:241]
	v_pk_add_f32 v[114:115], v[114:115], v[242:243]
	v_pk_add_f32 v[92:93], v[92:93], v[244:245]
	v_pk_add_f32 v[94:95], v[94:95], v[246:247]
	v_pk_add_f32 v[84:85], v[84:85], v[248:249]
	v_pk_add_f32 v[86:87], v[86:87], v[250:251]
	s_mov_b32 s100, 0x0
	s_mov_b32 s101, 0
	v_lshl_add_u64 v[216:217], v[252:253], 0, s[100:101]
	global_store_dwordx4 v[216:217], v[124:127], off
	global_store_dwordx4 v[216:217], v[120:123], off offset:64
	global_store_dwordx4 v[216:217], v[108:111], off offset:512
	global_store_dwordx4 v[216:217], v[100:103], off offset:576
	s_mov_b32 s100, 0x10000
	s_mov_b32 s101, 0
	v_lshl_add_u64 v[218:219], v[252:253], 0, s[100:101]
	global_store_dwordx4 v[218:219], v[116:119], off
	global_store_dwordx4 v[218:219], v[112:115], off offset:64
	global_store_dwordx4 v[218:219], v[92:95], off offset:512
	global_store_dwordx4 v[218:219], v[84:87], off offset:576
	s_mov_b32 s100, 0xa0000
	s_mov_b32 s101, 0
	v_lshl_add_u64 v[214:215], v[252:253], 0, s[100:101]
	global_load_dwordx4 v[220:223], v[214:215], off
	global_load_dwordx4 v[224:227], v[214:215], off offset:64
	global_load_dwordx4 v[228:231], v[214:215], off offset:512
	global_load_dwordx4 v[232:235], v[214:215], off offset:576
	s_mov_b32 s100, 0xb0000
	s_mov_b32 s101, 0
	v_lshl_add_u64 v[216:217], v[252:253], 0, s[100:101]
	global_load_dwordx4 v[236:239], v[216:217], off
	global_load_dwordx4 v[240:243], v[216:217], off offset:64
	global_load_dwordx4 v[244:247], v[216:217], off offset:512
	global_load_dwordx4 v[248:251], v[216:217], off offset:576
	s_waitcnt vmcnt(24)
;     DI void operator()(const AccT& acc, const Unit& u, int wr, int wc, int fr, int fq) const {
; #pragma unroll
;         for (int ai = 0; ai < 2; ++ai) {
;             f32x4 h[4][2][2];
;             float* base = H + ((size_t)u.pm * 256 + ai * 128 + wr * 64 + fr) * 1024 + u.pn * 256 + wc * 32 + 4 * fq;
; #pragma unroll
;             for (int m = 0; m < 4; ++m)
; #pragma unroll
;                 for (int bj = 0; bj < 2; ++bj)
; #pragma unroll
;                     for (int n = 0; n < 2; ++n) h[m][bj][n] = *(const f32x4*)(base + (size_t)m * 16 * 1024 + bj * 128 + n * 16);
;             __builtin_amdgcn_sched_barrier(0);
; #pragma unroll
;             for (int m = 0; m < 4; ++m)
; #pragma unroll
;                 for (int bj = 0; bj < 2; ++bj)
; #pragma unroll
;                     for (int n = 0; n < 2; ++n) *(f32x4*)(base + (size_t)m * 16 * 1024 + bj * 128 + n * 16) = h[m][bj][n] + acc[ai][bj][m][n] * alpha;
;         }
;     }
	v_pk_add_f32 v[104:105], v[104:105], v[150:151]
	v_pk_add_f32 v[106:107], v[106:107], v[152:153]
	v_pk_add_f32 v[96:97], v[96:97], v[154:155]
	v_pk_add_f32 v[98:99], v[98:99], v[156:157]
	v_pk_add_f32 v[76:77], v[76:77], v[158:159]
	v_pk_add_f32 v[78:79], v[78:79], v[160:161]
	v_pk_add_f32 v[72:73], v[72:73], v[162:163]
	v_pk_add_f32 v[74:75], v[74:75], v[164:165]
	v_pk_add_f32 v[88:89], v[88:89], v[166:167]
	v_pk_add_f32 v[90:91], v[90:91], v[168:169]
	v_pk_add_f32 v[80:81], v[80:81], v[170:171]
	v_pk_add_f32 v[82:83], v[82:83], v[172:173]
	v_pk_add_f32 v[68:69], v[68:69], v[174:175]
	v_pk_add_f32 v[70:71], v[70:71], v[176:177]
	v_pk_add_f32 v[64:65], v[64:65], v[178:179]
	v_pk_add_f32 v[66:67], v[66:67], v[180:181]
	s_mov_b32 s100, 0x20000
	s_mov_b32 s101, 0
	v_lshl_add_u64 v[216:217], v[252:253], 0, s[100:101]
	global_store_dwordx4 v[216:217], v[104:107], off
	global_store_dwordx4 v[216:217], v[96:99], off offset:64
	global_store_dwordx4 v[216:217], v[76:79], off offset:512
	global_store_dwordx4 v[216:217], v[72:75], off offset:576
	s_mov_b32 s100, 0x30000
	s_mov_b32 s101, 0
	v_lshl_add_u64 v[218:219], v[252:253], 0, s[100:101]
	global_store_dwordx4 v[218:219], v[88:91], off
	global_store_dwordx4 v[218:219], v[80:83], off offset:64
	global_store_dwordx4 v[218:219], v[68:71], off offset:512
	global_store_dwordx4 v[218:219], v[64:67], off offset:576
	s_waitcnt vmcnt(24)
	v_pk_add_f32 v[60:61], v[60:61], v[182:183]
	v_pk_add_f32 v[62:63], v[62:63], v[184:185]
	v_pk_add_f32 v[56:57], v[56:57], v[186:187]
	v_pk_add_f32 v[58:59], v[58:59], v[188:189]
	v_pk_add_f32 v[48:49], v[48:49], v[190:191]
	v_pk_add_f32 v[50:51], v[50:51], v[192:193]
	v_pk_add_f32 v[40:41], v[40:41], v[194:195]
	v_pk_add_f32 v[42:43], v[42:43], v[196:197]
	v_pk_add_f32 v[52:53], v[52:53], v[198:199]
	v_pk_add_f32 v[54:55], v[54:55], v[200:201]
	v_pk_add_f32 v[44:45], v[44:45], v[202:203]
	v_pk_add_f32 v[46:47], v[46:47], v[204:205]
	v_pk_add_f32 v[32:33], v[32:33], v[206:207]
	v_pk_add_f32 v[34:35], v[34:35], v[208:209]
	v_pk_add_f32 v[24:25], v[24:25], v[210:211]
	v_pk_add_f32 v[26:27], v[26:27], v[212:213]
	s_mov_b32 s100, 0x80000
	s_mov_b32 s101, 0
	v_lshl_add_u64 v[216:217], v[252:253], 0, s[100:101]
	global_store_dwordx4 v[216:217], v[60:63], off
	global_store_dwordx4 v[216:217], v[56:59], off offset:64
	global_store_dwordx4 v[216:217], v[48:51], off offset:512
	global_store_dwordx4 v[216:217], v[40:43], off offset:576
	s_mov_b32 s100, 0x90000
	s_mov_b32 s101, 0
	v_lshl_add_u64 v[218:219], v[252:253], 0, s[100:101]
	global_store_dwordx4 v[218:219], v[52:55], off
	global_store_dwordx4 v[218:219], v[44:47], off offset:64
	global_store_dwordx4 v[218:219], v[32:35], off offset:512
	global_store_dwordx4 v[218:219], v[24:27], off offset:576
	s_waitcnt vmcnt(16)
	v_pk_add_f32 v[36:37], v[36:37], v[220:221]
	v_pk_add_f32 v[38:39], v[38:39], v[222:223]
	v_pk_add_f32 v[28:29], v[28:29], v[224:225]
	v_pk_add_f32 v[30:31], v[30:31], v[226:227]
	v_pk_add_f32 v[16:17], v[16:17], v[228:229]
	v_pk_add_f32 v[18:19], v[18:19], v[230:231]
	v_pk_add_f32 v[8:9], v[8:9], v[232:233]
	v_pk_add_f32 v[10:11], v[10:11], v[234:235]
	v_pk_add_f32 v[20:21], v[20:21], v[236:237]
	v_pk_add_f32 v[22:23], v[22:23], v[238:239]
	v_pk_add_f32 v[12:13], v[12:13], v[240:241]
	v_pk_add_f32 v[14:15], v[14:15], v[242:243]
	v_pk_add_f32 v[4:5], v[4:5], v[244:245]
	v_pk_add_f32 v[6:7], v[6:7], v[246:247]
	v_pk_add_f32 v[0:1], v[0:1], v[248:249]
	v_pk_add_f32 v[2:3], v[2:3], v[250:251]
	s_mov_b32 s100, 0xa0000
	s_mov_b32 s101, 0
	v_lshl_add_u64 v[216:217], v[252:253], 0, s[100:101]
	global_store_dwordx4 v[216:217], v[36:39], off
	global_store_dwordx4 v[216:217], v[28:31], off offset:64
	global_store_dwordx4 v[216:217], v[16:19], off offset:512
	global_store_dwordx4 v[216:217], v[8:11], off offset:576
	s_mov_b32 s100, 0xb0000
	s_mov_b32 s101, 0
	v_lshl_add_u64 v[218:219], v[252:253], 0, s[100:101]
	global_store_dwordx4 v[218:219], v[20:23], off
	global_store_dwordx4 v[218:219], v[12:15], off offset:64
	global_store_dwordx4 v[218:219], v[4:7], off offset:512
	global_store_dwordx4 v[218:219], v[0:3], off offset:576
	s_and_b64 vcc, exec, s[4:5]
	s_mov_b32 s71, s16
	s_mov_b32 s28, s18
	s_mov_b64 s[36:37], s[26:27]
	s_mov_b64 s[30:31], s[24:25]
	s_cbranch_vccz .LBB0_3001
	s_waitcnt vmcnt(0)
	s_cmpk_gt_u32 s41, 0xff
	s_cbranch_scc1 .LBB0_3012
	s_barrier

;     DI bool next(int i, Unit& u) const {
;         const long L = (long)i * G + c; if (L >= nwg) return false;
;         int wgid = (int)L; { const int q = nwg / NXCD, r = nwg % NXCD, xcd = wgid % NXCD, off = wgid / NXCD; wgid = (xcd < r ? xcd * (q + 1) : r * (q + 1) + (xcd - r) * q) + off; }
;         const int nig = WGM * nN, gid = wgid / nig, fm = gid * WGM, gsz = (nM - fm) < WGM ? (nM - fm) : WGM;
;         u.pm = fm + ((wgid % nig) % gsz); u.pn = (wgid % nig) / gsz; return true;
;     }
;     DI void operator()(const AccT& acc, const Unit& u, int wr, int wc, int fr, int fq) const {
;     ...
;             float* base = H + ((size_t)u.pm * 256 + ai * 128 + wr * 64 + fr) * 1024 + u.pn * 256 + wc * 32 + 4 * fq;
; #pragma unroll
;             for (int m = 0; m < 4; ++m)
; #pragma unroll
;                 for (int bj = 0; bj < 2; ++bj)
; #pragma unroll
;                     for (int n = 0; n < 2; ++n) h[m][bj][n] = *(const f32x4*)(base + (size_t)m * 16 * 1024 + bj * 128 + n * 16);
.LBB0_3202:
	s_mov_b32 s98, s16
	s_ashr_i32 s99, s16, 31
	s_lshl_b64 s[98:99], s[98:99], 20
	s_lshl_b32 s100, s59, 8
	s_ashr_i32 s101, s100, 31
	v_lshl_add_u64 v[252:253], v[134:135], 0, s[98:99]
	v_lshl_add_u64 v[252:253], s[100:101], 2, v[252:253]
	v_lshl_add_u64 v[252:253], v[252:253], 0, s[10:11]
	v_lshl_add_u64 v[252:253], v[252:253], 0, v[132:133]
	global_load_dwordx4 v[220:223], v[252:253], off
	global_load_dwordx4 v[224:227], v[252:253], off offset:64
	global_load_dwordx4 v[228:231], v[252:253], off offset:512
	global_load_dwordx4 v[232:235], v[252:253], off offset:576
	s_mov_b32 s100, 0x10000
	s_mov_b32 s101, 0
	v_lshl_add_u64 v[252:253], v[252:253], 0, s[100:101]
	global_load_dwordx4 v[236:239], v[252:253], off
	global_load_dwordx4 v[240:243], v[252:253], off offset:64
	global_load_dwordx4 v[244:247], v[252:253], off offset:512
	global_load_dwordx4 v[248:251], v[252:253], off offset:576
	s_mov_b32 s100, 0xffff0000
	s_mov_b32 s101, -1
	v_lshl_add_u64 v[252:253], v[252:253], 0, s[100:101]
	s_add_i32 s56, s56, 1
	s_mul_i32 s4, s56, s45
	s_mul_hi_u32 s5, s56, s44
	s_add_i32 s5, s5, s4
	s_mul_i32 s4, s56, s44
	s_add_u32 s8, s4, s2
	s_addc_u32 s9, s5, s3
	v_cmp_gt_i64_e64 s[4:5], s[8:9], v[142:143]
	v_cmp_lt_i64_e64 s[6:7], s[8:9], v[140:141]
	s_and_b64 vcc, exec, s[4:5]
	s_cbranch_vccnz .LBB0_3208
	s_ashr_i32 s9, s8, 31
	s_lshr_b32 s9, s9, 29
	s_add_i32 s17, s8, s9
	s_and_b32 s9, s17, -8
	s_sub_i32 s22, s8, s9
	s_cmp_gt_i32 s22, 3
	s_mov_b64 s[8:9], -1
	s_cbranch_scc0 .LBB0_3205
	s_mul_i32 s8, s22, 0xa1
	s_add_i32 s23, s8, 4
	s_mov_b64 s[8:9], 0

; #define PG8_STAGE(bufoff, gbase, voff) do { _Pragma("unroll") for (int _i = 0; _i < 2; ++_i) \
;         __builtin_amdgcn_global_load_lds((const unsigned*)((const char*)(gbase) + (voff)[_i]), (LAS unsigned*)(lds + (bufoff) + ldsw + _i * 8192), 16, 0, 0); } while (0)
; #define PG8_LDA(dst, b, h) do { _Pragma("unroll") for (int m = 0; m < 4; ++m) _Pragma("unroll") for (int k = 0; k < 2; ++k) dst[m][k] = *(const LAS bf16x8*)(lds + PG8_SA(b, h) + aoff + m * 2048 + k * 1024); } while (0)
; #define PG8_LDB(dst, b, h) do { _Pragma("unroll") for (int n = 0; n < 2; ++n) _Pragma("unroll") for (int k = 0; k < 2; ++k) dst[n][k] = *(const LAS bf16x8*)(lds + PG8_SB(b, h) + boff + n * 2048 + k * 1024); } while (0)
; #define PG8_MMA(ai, bj, At, Bt) do { __builtin_amdgcn_s_setprio(1); _Pragma("unroll") for (int m = 0; m < 4; ++m) _Pragma("unroll") for (int n = 0; n < 2; ++n) _Pragma("unroll") for (int k = 0; k < 2; ++k) \
;         acc[ai][bj][m][n] = __builtin_amdgcn_mfma_f32_16x16x32_bf16(Bt[n][k], At[m][k], acc[ai][bj][m][n], 0, 0, 0); __builtin_amdgcn_s_setprio(0); } while (0)
; #define PG8_WAIT_L(n) asm volatile("s_waitcnt lgkmcnt(" #n ")" ::: "memory")
; #define PG8_BAR __builtin_amdgcn_s_barrier()
; #define PG8_SCHED __builtin_amdgcn_sched_barrier(0)
; template <class Epi>
; DI void gemm_phase(int wv, LAS unsigned char* lds, const Gemm g, const StaticOrder& S, const Epi& E) {
;     ...
;         for (int t = 0; t < nt; t += 2) {
;             const bool last = (t == nt - 2);
;             const char* a1 = cA + (size_t)(t + 1) * kstep;
;             const char* a2 = last ? nA : cA + (size_t)(t + 2) * kstep; const char* b2 = last ? nB : cB + (size_t)(t + 2) * kstep;
;             const char* a3 = a2 + kstep; const char* b3 = b2 + kstep;
;             PG8_LDB(B0, 0, 0); PG8_SCHED; PG8_LDA(At, 0, 0); PG8_STAGE(PG8_SA(1, 1), a1 + hstep, voffA);
;             PG8_WAIT_L(8); PG8_BAR; PG8_WAIT_L(0); PG8_MMA(0, 0, At, B0); PG8_BAR; PG8_SCHED;
;             PG8_LDB(B1, 0, 1); PG8_STAGE(PG8_SB(0, 0), b2, voffB);
;             PG8_BAR; PG8_WAIT_L(0); PG8_MMA(0, 1, At, B1); PG8_BAR;
;             PG8_LDA(At, 0, 1); PG8_STAGE(PG8_SA(0, 0), a2, voffA);
;             PG8_BAR; PG8_WAIT_L(0); PG8_MMA(1, 0, At, B0); PG8_BAR; PG8_SCHED;
.LBB0_3213:
	ds_read_b128 v[150:153], v147
	ds_read_b128 v[154:157], v147 offset:1024
	ds_read_b128 v[158:161], v147 offset:2048
	ds_read_b128 v[162:165], v147 offset:3072
	s_add_u32 s20, s18, 0x100
	s_addc_u32 s21, s19, 0
	s_cmp_eq_u32 s61, 40
	s_cselect_b32 s25, s7, s21
	s_cselect_b32 s24, s6, s20
	s_cselect_b32 s23, s9, s60
	s_cselect_b32 s22, s8, s17
	v_lshl_add_u64 v[144:145], s[18:19], 0, v[136:137]
	s_add_i32 m0, s30, 0xc000
	ds_read_b128 v[166:169], v148
	ds_read_b128 v[170:173], v148 offset:1024
	ds_read_b128 v[174:177], v148 offset:2048
	ds_read_b128 v[178:181], v148 offset:3072
	ds_read_b128 v[182:185], v148 offset:4096
	ds_read_b128 v[186:189], v148 offset:5120
	ds_read_b128 v[190:193], v148 offset:6144
	ds_read_b128 v[194:197], v148 offset:7168
	global_load_lds_dwordx4 v[144:145], off
	v_lshl_add_u64 v[144:145], s[18:19], 0, v[138:139]
	s_add_i32 m0, s30, 0xe000
	s_nop 0
	global_load_lds_dwordx4 v[144:145], off
	s_waitcnt lgkmcnt(8)
	s_barrier
	s_waitcnt lgkmcnt(0)
	s_setprio 1
	s_waitcnt lgkmcnt(0)
	v_mfma_f32_16x16x32_bf16 v[124:127], v[150:153], v[166:169], v[124:127]
	v_mfma_f32_16x16x32_bf16 v[120:123], v[158:161], v[166:169], v[120:123]
	v_mfma_f32_16x16x32_bf16 v[116:119], v[150:153], v[174:177], v[116:119]
	v_mfma_f32_16x16x32_bf16 v[112:115], v[158:161], v[174:177], v[112:115]
	v_mfma_f32_16x16x32_bf16 v[104:107], v[150:153], v[182:185], v[104:107]
	v_mfma_f32_16x16x32_bf16 v[96:99], v[158:161], v[182:185], v[96:99]
	v_mfma_f32_16x16x32_bf16 v[88:91], v[150:153], v[190:193], v[88:91]
	v_mfma_f32_16x16x32_bf16 v[80:83], v[158:161], v[190:193], v[80:83]
	v_mfma_f32_16x16x32_bf16 v[124:127], v[154:157], v[170:173], v[124:127]
	v_mfma_f32_16x16x32_bf16 v[120:123], v[162:165], v[170:173], v[120:123]
	v_mfma_f32_16x16x32_bf16 v[116:119], v[154:157], v[178:181], v[116:119]
	v_mfma_f32_16x16x32_bf16 v[112:115], v[162:165], v[178:181], v[112:115]
	v_mfma_f32_16x16x32_bf16 v[104:107], v[154:157], v[186:189], v[104:107]
	v_mfma_f32_16x16x32_bf16 v[96:99], v[162:165], v[186:189], v[96:99]
	v_mfma_f32_16x16x32_bf16 v[88:91], v[154:157], v[194:197], v[88:91]
	v_mfma_f32_16x16x32_bf16 v[80:83], v[162:165], v[194:197], v[80:83]
	s_setprio 0
	s_barrier
	s_add_i32 s18, s48, s29
	v_lshl_add_u64 v[144:145], s[22:23], 0, v[128:129]
	s_mov_b32 m0, s18
	ds_read_b128 v[198:201], v149
	ds_read_b128 v[202:205], v149 offset:1024
	ds_read_b128 v[206:209], v149 offset:2048
	ds_read_b128 v[210:213], v149 offset:3072
	global_load_lds_dwordx4 v[144:145], off
	v_lshl_add_u64 v[214:215], s[22:23], 0, v[130:131]
	s_add_i32 m0, s18, 0x2000
	s_nop 0
	global_load_lds_dwordx4 v[214:215], off
	s_barrier
	s_waitcnt lgkmcnt(0)
	s_setprio 1
	s_waitcnt lgkmcnt(0)
	v_mfma_f32_16x16x32_bf16 v[108:111], v[198:201], v[166:169], v[108:111]
	v_mfma_f32_16x16x32_bf16 v[100:103], v[206:209], v[166:169], v[100:103]
	v_mfma_f32_16x16x32_bf16 v[92:95], v[198:201], v[174:177], v[92:95]
	v_mfma_f32_16x16x32_bf16 v[84:87], v[206:209], v[174:177], v[84:87]
	v_mfma_f32_16x16x32_bf16 v[76:79], v[198:201], v[182:185], v[76:79]
	v_mfma_f32_16x16x32_bf16 v[72:75], v[206:209], v[182:185], v[72:75]
	v_mfma_f32_16x16x32_bf16 v[68:71], v[198:201], v[190:193], v[68:71]
	v_mfma_f32_16x16x32_bf16 v[64:67], v[206:209], v[190:193], v[64:67]
	v_mfma_f32_16x16x32_bf16 v[108:111], v[202:205], v[170:173], v[108:111]
	v_mfma_f32_16x16x32_bf16 v[100:103], v[210:213], v[170:173], v[100:103]
	v_mfma_f32_16x16x32_bf16 v[92:95], v[202:205], v[178:181], v[92:95]
	v_mfma_f32_16x16x32_bf16 v[84:87], v[210:213], v[178:181], v[84:87]
	v_mfma_f32_16x16x32_bf16 v[76:79], v[202:205], v[186:189], v[76:79]
	v_mfma_f32_16x16x32_bf16 v[72:75], v[210:213], v[186:189], v[72:75]
	v_mfma_f32_16x16x32_bf16 v[68:71], v[202:205], v[194:197], v[68:71]
	v_mfma_f32_16x16x32_bf16 v[64:67], v[210:213], v[194:197], v[64:67]
	s_setprio 0
	s_mov_b32 m0, s30
	v_lshl_add_u64 v[216:217], s[24:25], 0, v[128:129]
	s_barrier
	ds_read_b128 v[166:169], v148 offset:16384
	ds_read_b128 v[170:173], v148 offset:17408
	ds_read_b128 v[174:177], v148 offset:18432
	ds_read_b128 v[178:181], v148 offset:19456
	ds_read_b128 v[182:185], v148 offset:20480
	ds_read_b128 v[186:189], v148 offset:21504
	ds_read_b128 v[190:193], v148 offset:22528
	ds_read_b128 v[194:197], v148 offset:23552
	global_load_lds_dwordx4 v[216:217], off
	v_lshl_add_u64 v[218:219], s[24:25], 0, v[130:131]
	s_mov_b32 m0, s31
	s_nop 0
	global_load_lds_dwordx4 v[218:219], off
	s_barrier
	s_waitcnt lgkmcnt(0)
	s_setprio 1
	s_waitcnt lgkmcnt(0)
	v_mfma_f32_16x16x32_bf16 v[60:63], v[150:153], v[166:169], v[60:63]
	v_mfma_f32_16x16x32_bf16 v[56:59], v[158:161], v[166:169], v[56:59]
	v_mfma_f32_16x16x32_bf16 v[52:55], v[150:153], v[174:177], v[52:55]
	v_mfma_f32_16x16x32_bf16 v[44:47], v[158:161], v[174:177], v[44:47]
	v_mfma_f32_16x16x32_bf16 v[36:39], v[150:153], v[182:185], v[36:39]
	v_mfma_f32_16x16x32_bf16 v[28:31], v[158:161], v[182:185], v[28:31]
	v_mfma_f32_16x16x32_bf16 v[20:23], v[150:153], v[190:193], v[20:23]
	v_mfma_f32_16x16x32_bf16 v[12:15], v[158:161], v[190:193], v[12:15]
	v_mfma_f32_16x16x32_bf16 v[60:63], v[154:157], v[170:173], v[60:63]
	v_mfma_f32_16x16x32_bf16 v[56:59], v[162:165], v[170:173], v[56:59]
	v_mfma_f32_16x16x32_bf16 v[52:55], v[154:157], v[178:181], v[52:55]
	v_mfma_f32_16x16x32_bf16 v[44:47], v[162:165], v[178:181], v[44:47]
	v_mfma_f32_16x16x32_bf16 v[36:39], v[154:157], v[186:189], v[36:39]
	v_mfma_f32_16x16x32_bf16 v[28:31], v[162:165], v[186:189], v[28:31]
	v_mfma_f32_16x16x32_bf16 v[20:23], v[154:157], v[194:197], v[20:23]
	v_mfma_f32_16x16x32_bf16 v[12:15], v[162:165], v[194:197], v[12:15]
	s_setprio 0
	s_barrier
; #define PG8_STAGE(bufoff, gbase, voff) do { _Pragma("unroll") for (int _i = 0; _i < 2; ++_i) \
;         __builtin_amdgcn_global_load_lds((const unsigned*)((const char*)(gbase) + (voff)[_i]), (LAS unsigned*)(lds + (bufoff) + ldsw + _i * 8192), 16, 0, 0); } while (0)
; #define PG8_LDA(dst, b, h) do { _Pragma("unroll") for (int m = 0; m < 4; ++m) _Pragma("unroll") for (int k = 0; k < 2; ++k) dst[m][k] = *(const LAS bf16x8*)(lds + PG8_SA(b, h) + aoff + m * 2048 + k * 1024); } while (0)
; #define PG8_LDB(dst, b, h) do { _Pragma("unroll") for (int n = 0; n < 2; ++n) _Pragma("unroll") for (int k = 0; k < 2; ++k) dst[n][k] = *(const LAS bf16x8*)(lds + PG8_SB(b, h) + boff + n * 2048 + k * 1024); } while (0)
; #define PG8_MMA(ai, bj, At, Bt) do { __builtin_amdgcn_s_setprio(1); _Pragma("unroll") for (int m = 0; m < 4; ++m) _Pragma("unroll") for (int n = 0; n < 2; ++n) _Pragma("unroll") for (int k = 0; k < 2; ++k) \
;         acc[ai][bj][m][n] = __builtin_amdgcn_mfma_f32_16x16x32_bf16(Bt[n][k], At[m][k], acc[ai][bj][m][n], 0, 0, 0); __builtin_amdgcn_s_setprio(0); } while (0)
; #define PG8_WAIT_V(n) asm volatile("s_waitcnt vmcnt(" #n ")" ::: "memory")
; #define PG8_WAIT_L(n) asm volatile("s_waitcnt lgkmcnt(" #n ")" ::: "memory")
; #define PG8_BAR __builtin_amdgcn_s_barrier()
; #define PG8_SCHED __builtin_amdgcn_sched_barrier(0)
; template <class Epi>
; DI void gemm_phase(int wv, LAS unsigned char* lds, const Gemm g, const StaticOrder& S, const Epi& E) {
;     ...
;             PG8_STAGE(PG8_SB(0, 1), b2 + hstep, voffB);
;             PG8_WAIT_V(6); PG8_BAR; PG8_MMA(1, 1, At, B1); PG8_BAR;
;             PG8_LDB(B0, 1, 0); PG8_SCHED; PG8_LDA(At, 1, 0); PG8_STAGE(PG8_SA(0, 1), a2 + hstep, voffA);
;             PG8_WAIT_L(8); PG8_BAR; PG8_WAIT_L(0); PG8_MMA(0, 0, At, B0); PG8_BAR; PG8_SCHED;
;             PG8_LDB(B1, 1, 1); PG8_STAGE(PG8_SB(1, 0), b3, voffB);
;             PG8_BAR; PG8_WAIT_L(0); PG8_MMA(0, 1, At, B1); PG8_BAR;
;             PG8_LDA(At, 1, 1); PG8_STAGE(PG8_SA(1, 0), a3, voffA);
;             PG8_BAR; PG8_WAIT_L(0); PG8_MMA(1, 0, At, B0); PG8_BAR; PG8_SCHED;
	s_add_u32 s18, s22, 0xb0000
	s_addc_u32 s19, s23, 0
	s_add_i32 s62, s49, s29
	v_lshl_add_u64 v[150:151], s[18:19], 0, v[128:129]
	s_mov_b32 m0, s62
	s_nop 0
	global_load_lds_dwordx4 v[150:151], off
	v_lshl_add_u64 v[150:151], s[18:19], 0, v[130:131]
	s_add_i32 m0, s62, 0x2000
	s_nop 0
	global_load_lds_dwordx4 v[150:151], off
	s_waitcnt vmcnt(6)
	s_barrier
	s_setprio 1
	v_mfma_f32_16x16x32_bf16 v[48:51], v[198:201], v[166:169], v[48:51]
	v_mfma_f32_16x16x32_bf16 v[40:43], v[206:209], v[166:169], v[40:43]
	v_mfma_f32_16x16x32_bf16 v[32:35], v[198:201], v[174:177], v[32:35]
	v_mfma_f32_16x16x32_bf16 v[24:27], v[206:209], v[174:177], v[24:27]
	v_mfma_f32_16x16x32_bf16 v[16:19], v[198:201], v[182:185], v[16:19]
	v_mfma_f32_16x16x32_bf16 v[8:11], v[206:209], v[182:185], v[8:11]
	v_mfma_f32_16x16x32_bf16 v[4:7], v[198:201], v[190:193], v[4:7]
	v_mfma_f32_16x16x32_bf16 v[0:3], v[206:209], v[190:193], v[0:3]
	v_mfma_f32_16x16x32_bf16 v[48:51], v[202:205], v[170:173], v[48:51]
	v_mfma_f32_16x16x32_bf16 v[40:43], v[210:213], v[170:173], v[40:43]
	v_mfma_f32_16x16x32_bf16 v[32:35], v[202:205], v[178:181], v[32:35]
	v_mfma_f32_16x16x32_bf16 v[24:27], v[210:213], v[178:181], v[24:27]
	v_mfma_f32_16x16x32_bf16 v[16:19], v[202:205], v[186:189], v[16:19]
	v_mfma_f32_16x16x32_bf16 v[8:11], v[210:213], v[186:189], v[8:11]
	v_mfma_f32_16x16x32_bf16 v[4:7], v[202:205], v[194:197], v[4:7]
	v_mfma_f32_16x16x32_bf16 v[0:3], v[210:213], v[194:197], v[0:3]
	s_setprio 0
	s_add_i32 s62, 0, 0x18000
	v_add_u32_e32 v162, s62, v146
	s_barrier
	ds_read_b128 v[150:153], v162
	ds_read_b128 v[154:157], v162 offset:1024
	ds_read_b128 v[158:161], v162 offset:2048
	ds_read_b128 v[162:165], v162 offset:3072
	s_add_u32 s18, s24, 0xb0000
	s_addc_u32 s19, s25, 0
	s_mov_b32 m0, s36
	v_lshl_add_u64 v[198:199], s[18:19], 0, v[128:129]
	ds_read_b128 v[166:169], v148 offset:32768
	ds_read_b128 v[170:173], v148 offset:33792
	ds_read_b128 v[174:177], v148 offset:34816
	ds_read_b128 v[178:181], v148 offset:35840
	ds_read_b128 v[182:185], v148 offset:36864
	ds_read_b128 v[186:189], v148 offset:37888
	ds_read_b128 v[190:193], v148 offset:38912
	ds_read_b128 v[194:197], v148 offset:39936
	global_load_lds_dwordx4 v[198:199], off
	v_lshl_add_u64 v[198:199], s[18:19], 0, v[130:131]
	s_mov_b32 m0, s37
	s_nop 0
	global_load_lds_dwordx4 v[198:199], off
	s_waitcnt lgkmcnt(8)
	s_barrier
	s_waitcnt lgkmcnt(0)
	s_setprio 1
	s_waitcnt lgkmcnt(0)
	v_mfma_f32_16x16x32_bf16 v[124:127], v[150:153], v[166:169], v[124:127]
	v_mfma_f32_16x16x32_bf16 v[120:123], v[158:161], v[166:169], v[120:123]
	v_mfma_f32_16x16x32_bf16 v[116:119], v[150:153], v[174:177], v[116:119]
	v_mfma_f32_16x16x32_bf16 v[112:115], v[158:161], v[174:177], v[112:115]
	v_mfma_f32_16x16x32_bf16 v[104:107], v[150:153], v[182:185], v[104:107]
	v_mfma_f32_16x16x32_bf16 v[96:99], v[158:161], v[182:185], v[96:99]
	v_mfma_f32_16x16x32_bf16 v[88:91], v[150:153], v[190:193], v[88:91]
	v_mfma_f32_16x16x32_bf16 v[80:83], v[158:161], v[190:193], v[80:83]
	v_mfma_f32_16x16x32_bf16 v[124:127], v[154:157], v[170:173], v[124:127]
	v_mfma_f32_16x16x32_bf16 v[120:123], v[162:165], v[170:173], v[120:123]
	v_mfma_f32_16x16x32_bf16 v[116:119], v[154:157], v[178:181], v[116:119]
	v_mfma_f32_16x16x32_bf16 v[112:115], v[162:165], v[178:181], v[112:115]
	v_mfma_f32_16x16x32_bf16 v[104:107], v[154:157], v[186:189], v[104:107]
	v_mfma_f32_16x16x32_bf16 v[96:99], v[162:165], v[186:189], v[96:99]
	v_mfma_f32_16x16x32_bf16 v[88:91], v[154:157], v[194:197], v[88:91]
	v_mfma_f32_16x16x32_bf16 v[80:83], v[162:165], v[194:197], v[80:83]
	s_setprio 0
	s_barrier
	s_add_i32 s24, 0, 0x1c000
	s_add_i32 s18, s62, s29
	v_add_u32_e32 v210, s24, v146
	v_lshl_add_u64 v[144:145], v[144:145], 0, s[12:13]
	s_mov_b32 m0, s18
	ds_read_b128 v[198:201], v210
	ds_read_b128 v[202:205], v210 offset:1024
	ds_read_b128 v[206:209], v210 offset:2048
	ds_read_b128 v[210:213], v210 offset:3072
	global_load_lds_dwordx4 v[144:145], off
	v_lshl_add_u64 v[144:145], v[214:215], 0, s[12:13]
	s_add_i32 m0, s18, 0x2000
	s_nop 0
	global_load_lds_dwordx4 v[144:145], off
	s_barrier
	s_waitcnt lgkmcnt(0)
	s_setprio 1
	s_waitcnt lgkmcnt(0)
	v_mfma_f32_16x16x32_bf16 v[108:111], v[198:201], v[166:169], v[108:111]
	v_mfma_f32_16x16x32_bf16 v[100:103], v[206:209], v[166:169], v[100:103]
	v_mfma_f32_16x16x32_bf16 v[92:95], v[198:201], v[174:177], v[92:95]
	v_mfma_f32_16x16x32_bf16 v[84:87], v[206:209], v[174:177], v[84:87]
	v_mfma_f32_16x16x32_bf16 v[76:79], v[198:201], v[182:185], v[76:79]
	v_mfma_f32_16x16x32_bf16 v[72:75], v[206:209], v[182:185], v[72:75]
	v_mfma_f32_16x16x32_bf16 v[68:71], v[198:201], v[190:193], v[68:71]
	v_mfma_f32_16x16x32_bf16 v[64:67], v[206:209], v[190:193], v[64:67]
	v_mfma_f32_16x16x32_bf16 v[108:111], v[202:205], v[170:173], v[108:111]
	v_mfma_f32_16x16x32_bf16 v[100:103], v[210:213], v[170:173], v[100:103]
	v_mfma_f32_16x16x32_bf16 v[92:95], v[202:205], v[178:181], v[92:95]
	v_mfma_f32_16x16x32_bf16 v[84:87], v[210:213], v[178:181], v[84:87]
	v_mfma_f32_16x16x32_bf16 v[76:79], v[202:205], v[186:189], v[76:79]
	v_mfma_f32_16x16x32_bf16 v[72:75], v[210:213], v[186:189], v[72:75]
	v_mfma_f32_16x16x32_bf16 v[68:71], v[202:205], v[194:197], v[68:71]
	v_mfma_f32_16x16x32_bf16 v[64:67], v[210:213], v[194:197], v[64:67]
	s_setprio 0
	s_mov_b32 m0, s46
	v_lshl_add_u64 v[144:145], v[216:217], 0, s[12:13]
	s_barrier
	ds_read_b128 v[166:169], v148 offset:49152
	ds_read_b128 v[170:173], v148 offset:50176
	ds_read_b128 v[174:177], v148 offset:51200
	ds_read_b128 v[178:181], v148 offset:52224
	ds_read_b128 v[182:185], v148 offset:53248
	ds_read_b128 v[186:189], v148 offset:54272
	ds_read_b128 v[190:193], v148 offset:55296
	ds_read_b128 v[194:197], v148 offset:56320
	global_load_lds_dwordx4 v[144:145], off
	v_lshl_add_u64 v[144:145], v[218:219], 0, s[12:13]
	s_mov_b32 m0, s47
	s_nop 0
	global_load_lds_dwordx4 v[144:145], off
	s_barrier
; #define PG8_STAGE(bufoff, gbase, voff) do { _Pragma("unroll") for (int _i = 0; _i < 2; ++_i) \
;         __builtin_amdgcn_global_load_lds((const unsigned*)((const char*)(gbase) + (voff)[_i]), (LAS unsigned*)(lds + (bufoff) + ldsw + _i * 8192), 16, 0, 0); } while (0)
; #define PG8_MMA(ai, bj, At, Bt) do { __builtin_amdgcn_s_setprio(1); _Pragma("unroll") for (int m = 0; m < 4; ++m) _Pragma("unroll") for (int n = 0; n < 2; ++n) _Pragma("unroll") for (int k = 0; k < 2; ++k) \
;         acc[ai][bj][m][n] = __builtin_amdgcn_mfma_f32_16x16x32_bf16(Bt[n][k], At[m][k], acc[ai][bj][m][n], 0, 0, 0); __builtin_amdgcn_s_setprio(0); } while (0)
; #define PG8_WAIT_V(n) asm volatile("s_waitcnt vmcnt(" #n ")" ::: "memory")
; #define PG8_WAIT_L(n) asm volatile("s_waitcnt lgkmcnt(" #n ")" ::: "memory")
; #define PG8_BAR __builtin_amdgcn_s_barrier()
; #define PG8_SCHED __builtin_amdgcn_sched_barrier(0)
; template <class Epi>
; DI void gemm_phase(int wv, LAS unsigned char* lds, const Gemm g, const StaticOrder& S, const Epi& E) {
;     ...
;             PG8_BAR; PG8_WAIT_L(0); PG8_MMA(1, 0, At, B0); PG8_BAR; PG8_SCHED;
;             PG8_STAGE(PG8_SB(1, 1), b3 + hstep, voffB);
;             PG8_WAIT_V(6); PG8_BAR; PG8_MMA(1, 1, At, B1); PG8_BAR;
;         }
;         E(acc, cur, wr, wc, fr, fq);
;     DI void operator()(const AccT& acc, const Unit& u, int wr, int wc, int fr, int fq) const {
; #pragma unroll
;         for (int ai = 0; ai < 2; ++ai) {
;             f32x4 h[4][2][2];
;             float* base = H + ((size_t)u.pm * 256 + ai * 128 + wr * 64 + fr) * 1024 + u.pn * 256 + wc * 32 + 4 * fq;
; #pragma unroll
;             for (int m = 0; m < 4; ++m)
; #pragma unroll
;                 for (int bj = 0; bj < 2; ++bj)
; #pragma unroll
;                     for (int n = 0; n < 2; ++n) h[m][bj][n] = *(const f32x4*)(base + (size_t)m * 16 * 1024 + bj * 128 + n * 16);
;             __builtin_amdgcn_sched_barrier(0);
; #pragma unroll
;             for (int m = 0; m < 4; ++m)
; #pragma unroll
;                 for (int bj = 0; bj < 2; ++bj)
; #pragma unroll
;                     for (int n = 0; n < 2; ++n) *(f32x4*)(base + (size_t)m * 16 * 1024 + bj * 128 + n * 16) = h[m][bj][n] + acc[ai][bj][m][n] * alpha;
;         }
;     }
	s_waitcnt lgkmcnt(0)
	s_setprio 1
	s_waitcnt lgkmcnt(0)
	v_mfma_f32_16x16x32_bf16 v[60:63], v[150:153], v[166:169], v[60:63]
	v_mfma_f32_16x16x32_bf16 v[56:59], v[158:161], v[166:169], v[56:59]
	v_mfma_f32_16x16x32_bf16 v[52:55], v[150:153], v[174:177], v[52:55]
	v_mfma_f32_16x16x32_bf16 v[44:47], v[158:161], v[174:177], v[44:47]
	v_mfma_f32_16x16x32_bf16 v[36:39], v[150:153], v[182:185], v[36:39]
	v_mfma_f32_16x16x32_bf16 v[28:31], v[158:161], v[182:185], v[28:31]
	v_mfma_f32_16x16x32_bf16 v[20:23], v[150:153], v[190:193], v[20:23]
	v_mfma_f32_16x16x32_bf16 v[12:15], v[158:161], v[190:193], v[12:15]
	v_mfma_f32_16x16x32_bf16 v[60:63], v[154:157], v[170:173], v[60:63]
	v_mfma_f32_16x16x32_bf16 v[56:59], v[162:165], v[170:173], v[56:59]
	v_mfma_f32_16x16x32_bf16 v[52:55], v[154:157], v[178:181], v[52:55]
	v_mfma_f32_16x16x32_bf16 v[44:47], v[162:165], v[178:181], v[44:47]
	v_mfma_f32_16x16x32_bf16 v[36:39], v[154:157], v[186:189], v[36:39]
	v_mfma_f32_16x16x32_bf16 v[28:31], v[162:165], v[186:189], v[28:31]
	v_mfma_f32_16x16x32_bf16 v[20:23], v[154:157], v[194:197], v[20:23]
	v_mfma_f32_16x16x32_bf16 v[12:15], v[162:165], v[194:197], v[12:15]
	s_setprio 0
	s_barrier
	s_add_u32 s18, s22, 0xb0080
	s_addc_u32 s19, s23, 0
	s_add_i32 s22, s24, s29
	v_lshl_add_u64 v[144:145], s[18:19], 0, v[128:129]
	s_mov_b32 m0, s22
	s_nop 0
	global_load_lds_dwordx4 v[144:145], off
	v_lshl_add_u64 v[144:145], s[18:19], 0, v[130:131]
	s_add_i32 m0, s22, 0x2000
	s_nop 0
	global_load_lds_dwordx4 v[144:145], off
	s_waitcnt vmcnt(6)
	s_barrier
	s_setprio 1
	v_mfma_f32_16x16x32_bf16 v[48:51], v[198:201], v[166:169], v[48:51]
	v_mfma_f32_16x16x32_bf16 v[40:43], v[206:209], v[166:169], v[40:43]
	v_mfma_f32_16x16x32_bf16 v[32:35], v[198:201], v[174:177], v[32:35]
	v_mfma_f32_16x16x32_bf16 v[24:27], v[206:209], v[174:177], v[24:27]
	v_mfma_f32_16x16x32_bf16 v[16:19], v[198:201], v[182:185], v[16:19]
	v_mfma_f32_16x16x32_bf16 v[8:11], v[206:209], v[182:185], v[8:11]
	v_mfma_f32_16x16x32_bf16 v[4:7], v[198:201], v[190:193], v[4:7]
	v_mfma_f32_16x16x32_bf16 v[0:3], v[206:209], v[190:193], v[0:3]
	v_mfma_f32_16x16x32_bf16 v[48:51], v[202:205], v[170:173], v[48:51]
	v_mfma_f32_16x16x32_bf16 v[40:43], v[210:213], v[170:173], v[40:43]
	v_mfma_f32_16x16x32_bf16 v[32:35], v[202:205], v[178:181], v[32:35]
	v_mfma_f32_16x16x32_bf16 v[24:27], v[210:213], v[178:181], v[24:27]
	v_mfma_f32_16x16x32_bf16 v[16:19], v[202:205], v[186:189], v[16:19]
	v_mfma_f32_16x16x32_bf16 v[8:11], v[210:213], v[186:189], v[8:11]
	v_mfma_f32_16x16x32_bf16 v[4:7], v[202:205], v[194:197], v[4:7]
	v_mfma_f32_16x16x32_bf16 v[0:3], v[210:213], v[194:197], v[0:3]
	s_setprio 0
	s_add_i32 s61, s61, 2
	s_add_u32 s17, s17, 0x100
	s_addc_u32 s60, s60, 0
	s_cmp_gt_u32 s61, 41
	s_mov_b64 s[18:19], s[20:21]
	s_barrier
	s_cbranch_scc0 .LBB0_3213
	s_ashr_i32 s17, s16, 31
	s_lshl_b32 s18, s59, 8
	s_lshl_b64 s[16:17], s[16:17], 20
	s_ashr_i32 s19, s18, 31
	s_mov_b32 s100, 0x20000
	s_mov_b32 s101, 0
	v_lshl_add_u64 v[214:215], v[252:253], 0, s[100:101]
	global_load_dwordx4 v[150:153], v[214:215], off
	global_load_dwordx4 v[154:157], v[214:215], off offset:64
	global_load_dwordx4 v[158:161], v[214:215], off offset:512
	global_load_dwordx4 v[162:165], v[214:215], off offset:576
	s_mov_b32 s100, 0x30000
	s_mov_b32 s101, 0
	v_lshl_add_u64 v[216:217], v[252:253], 0, s[100:101]
	global_load_dwordx4 v[166:169], v[216:217], off
	global_load_dwordx4 v[170:173], v[216:217], off offset:64
	global_load_dwordx4 v[174:177], v[216:217], off offset:512
	global_load_dwordx4 v[178:181], v[216:217], off offset:576
	s_mov_b32 s100, 0x80000
	s_mov_b32 s101, 0
	v_lshl_add_u64 v[214:215], v[252:253], 0, s[100:101]
	global_load_dwordx4 v[182:185], v[214:215], off
	global_load_dwordx4 v[186:189], v[214:215], off offset:64
	global_load_dwordx4 v[190:193], v[214:215], off offset:512
	global_load_dwordx4 v[194:197], v[214:215], off offset:576
	s_mov_b32 s100, 0x90000
	s_mov_b32 s101, 0
	v_lshl_add_u64 v[216:217], v[252:253], 0, s[100:101]
	global_load_dwordx4 v[198:201], v[216:217], off
	global_load_dwordx4 v[202:205], v[216:217], off offset:64
	global_load_dwordx4 v[206:209], v[216:217], off offset:512
	global_load_dwordx4 v[210:213], v[216:217], off offset:576
	s_waitcnt vmcnt(16)
	v_pk_fma_f32 v[124:125], v[124:125], 0.5, v[220:221] op_sel_hi:[1,0,1]
	v_pk_fma_f32 v[126:127], v[126:127], 0.5, v[222:223] op_sel_hi:[1,0,1]
	v_pk_fma_f32 v[120:121], v[120:121], 0.5, v[224:225] op_sel_hi:[1,0,1]
	v_pk_fma_f32 v[122:123], v[122:123], 0.5, v[226:227] op_sel_hi:[1,0,1]
	v_pk_fma_f32 v[108:109], v[108:109], 0.5, v[228:229] op_sel_hi:[1,0,1]
	v_pk_fma_f32 v[110:111], v[110:111], 0.5, v[230:231] op_sel_hi:[1,0,1]
	v_pk_fma_f32 v[100:101], v[100:101], 0.5, v[232:233] op_sel_hi:[1,0,1]
	v_pk_fma_f32 v[102:103], v[102:103], 0.5, v[234:235] op_sel_hi:[1,0,1]
	v_pk_fma_f32 v[116:117], v[116:117], 0.5, v[236:237] op_sel_hi:[1,0,1]
	v_pk_fma_f32 v[118:119], v[118:119], 0.5, v[238:239] op_sel_hi:[1,0,1]
	v_pk_fma_f32 v[112:113], v[112:113], 0.5, v[240:241] op_sel_hi:[1,0,1]
	v_pk_fma_f32 v[114:115], v[114:115], 0.5, v[242:243] op_sel_hi:[1,0,1]
	v_pk_fma_f32 v[92:93], v[92:93], 0.5, v[244:245] op_sel_hi:[1,0,1]
	v_pk_fma_f32 v[94:95], v[94:95], 0.5, v[246:247] op_sel_hi:[1,0,1]
	v_pk_fma_f32 v[84:85], v[84:85], 0.5, v[248:249] op_sel_hi:[1,0,1]
	v_pk_fma_f32 v[86:87], v[86:87], 0.5, v[250:251] op_sel_hi:[1,0,1]
	s_mov_b32 s100, 0x0
	s_mov_b32 s101, 0
	v_lshl_add_u64 v[216:217], v[252:253], 0, s[100:101]
	global_store_dwordx4 v[216:217], v[124:127], off
	global_store_dwordx4 v[216:217], v[120:123], off offset:64
	global_store_dwordx4 v[216:217], v[108:111], off offset:512
	global_store_dwordx4 v[216:217], v[100:103], off offset:576
	s_mov_b32 s100, 0x10000
	s_mov_b32 s101, 0
	v_lshl_add_u64 v[218:219], v[252:253], 0, s[100:101]
	global_store_dwordx4 v[218:219], v[116:119], off
	global_store_dwordx4 v[218:219], v[112:115], off offset:64
	global_store_dwordx4 v[218:219], v[92:95], off offset:512
	global_store_dwordx4 v[218:219], v[84:87], off offset:576
	s_mov_b32 s100, 0xa0000
	s_mov_b32 s101, 0
	v_lshl_add_u64 v[214:215], v[252:253], 0, s[100:101]
	global_load_dwordx4 v[220:223], v[214:215], off
	global_load_dwordx4 v[224:227], v[214:215], off offset:64
	global_load_dwordx4 v[228:231], v[214:215], off offset:512
	global_load_dwordx4 v[232:235], v[214:215], off offset:576
	s_mov_b32 s100, 0xb0000
	s_mov_b32 s101, 0
	v_lshl_add_u64 v[216:217], v[252:253], 0, s[100:101]
	global_load_dwordx4 v[236:239], v[216:217], off
	global_load_dwordx4 v[240:243], v[216:217], off offset:64
	global_load_dwordx4 v[244:247], v[216:217], off offset:512
	global_load_dwordx4 v[248:251], v[216:217], off offset:576
	s_waitcnt vmcnt(24)
;     DI void operator()(const AccT& acc, const Unit& u, int wr, int wc, int fr, int fq) const {
; #pragma unroll
;         for (int ai = 0; ai < 2; ++ai) {
;             f32x4 h[4][2][2];
;             float* base = H + ((size_t)u.pm * 256 + ai * 128 + wr * 64 + fr) * 1024 + u.pn * 256 + wc * 32 + 4 * fq;
; #pragma unroll
;             for (int m = 0; m < 4; ++m)
; #pragma unroll
;                 for (int bj = 0; bj < 2; ++bj)
; #pragma unroll
;                     for (int n = 0; n < 2; ++n) h[m][bj][n] = *(const f32x4*)(base + (size_t)m * 16 * 1024 + bj * 128 + n * 16);
;             __builtin_amdgcn_sched_barrier(0);
; #pragma unroll
;             for (int m = 0; m < 4; ++m)
; #pragma unroll
;                 for (int bj = 0; bj < 2; ++bj)
; #pragma unroll
;                     for (int n = 0; n < 2; ++n) *(f32x4*)(base + (size_t)m * 16 * 1024 + bj * 128 + n * 16) = h[m][bj][n] + acc[ai][bj][m][n] * alpha;
;         }
;     }
	v_pk_fma_f32 v[104:105], v[104:105], 0.5, v[150:151] op_sel_hi:[1,0,1]
	v_pk_fma_f32 v[106:107], v[106:107], 0.5, v[152:153] op_sel_hi:[1,0,1]
	v_pk_fma_f32 v[96:97], v[96:97], 0.5, v[154:155] op_sel_hi:[1,0,1]
	v_pk_fma_f32 v[98:99], v[98:99], 0.5, v[156:157] op_sel_hi:[1,0,1]
	v_pk_fma_f32 v[76:77], v[76:77], 0.5, v[158:159] op_sel_hi:[1,0,1]
	v_pk_fma_f32 v[78:79], v[78:79], 0.5, v[160:161] op_sel_hi:[1,0,1]
	v_pk_fma_f32 v[72:73], v[72:73], 0.5, v[162:163] op_sel_hi:[1,0,1]
	v_pk_fma_f32 v[74:75], v[74:75], 0.5, v[164:165] op_sel_hi:[1,0,1]
	v_pk_fma_f32 v[88:89], v[88:89], 0.5, v[166:167] op_sel_hi:[1,0,1]
	v_pk_fma_f32 v[90:91], v[90:91], 0.5, v[168:169] op_sel_hi:[1,0,1]
	v_pk_fma_f32 v[80:81], v[80:81], 0.5, v[170:171] op_sel_hi:[1,0,1]
	v_pk_fma_f32 v[82:83], v[82:83], 0.5, v[172:173] op_sel_hi:[1,0,1]
	v_pk_fma_f32 v[68:69], v[68:69], 0.5, v[174:175] op_sel_hi:[1,0,1]
	v_pk_fma_f32 v[70:71], v[70:71], 0.5, v[176:177] op_sel_hi:[1,0,1]
	v_pk_fma_f32 v[64:65], v[64:65], 0.5, v[178:179] op_sel_hi:[1,0,1]
	v_pk_fma_f32 v[66:67], v[66:67], 0.5, v[180:181] op_sel_hi:[1,0,1]
	s_mov_b32 s100, 0x20000
	s_mov_b32 s101, 0
	v_lshl_add_u64 v[216:217], v[252:253], 0, s[100:101]
	global_store_dwordx4 v[216:217], v[104:107], off
	global_store_dwordx4 v[216:217], v[96:99], off offset:64
	global_store_dwordx4 v[216:217], v[76:79], off offset:512
	global_store_dwordx4 v[216:217], v[72:75], off offset:576
	s_mov_b32 s100, 0x30000
	s_mov_b32 s101, 0
	v_lshl_add_u64 v[218:219], v[252:253], 0, s[100:101]
	global_store_dwordx4 v[218:219], v[88:91], off
	global_store_dwordx4 v[218:219], v[80:83], off offset:64
	global_store_dwordx4 v[218:219], v[68:71], off offset:512
	global_store_dwordx4 v[218:219], v[64:67], off offset:576
	s_waitcnt vmcnt(24)
	v_pk_fma_f32 v[60:61], v[60:61], 0.5, v[182:183] op_sel_hi:[1,0,1]
	v_pk_fma_f32 v[62:63], v[62:63], 0.5, v[184:185] op_sel_hi:[1,0,1]
	v_pk_fma_f32 v[56:57], v[56:57], 0.5, v[186:187] op_sel_hi:[1,0,1]
	v_pk_fma_f32 v[58:59], v[58:59], 0.5, v[188:189] op_sel_hi:[1,0,1]
	v_pk_fma_f32 v[48:49], v[48:49], 0.5, v[190:191] op_sel_hi:[1,0,1]
	v_pk_fma_f32 v[50:51], v[50:51], 0.5, v[192:193] op_sel_hi:[1,0,1]
	v_pk_fma_f32 v[40:41], v[40:41], 0.5, v[194:195] op_sel_hi:[1,0,1]
	v_pk_fma_f32 v[42:43], v[42:43], 0.5, v[196:197] op_sel_hi:[1,0,1]
	v_pk_fma_f32 v[52:53], v[52:53], 0.5, v[198:199] op_sel_hi:[1,0,1]
	v_pk_fma_f32 v[54:55], v[54:55], 0.5, v[200:201] op_sel_hi:[1,0,1]
	v_pk_fma_f32 v[44:45], v[44:45], 0.5, v[202:203] op_sel_hi:[1,0,1]
	v_pk_fma_f32 v[46:47], v[46:47], 0.5, v[204:205] op_sel_hi:[1,0,1]
	v_pk_fma_f32 v[32:33], v[32:33], 0.5, v[206:207] op_sel_hi:[1,0,1]
	v_pk_fma_f32 v[34:35], v[34:35], 0.5, v[208:209] op_sel_hi:[1,0,1]
	v_pk_fma_f32 v[24:25], v[24:25], 0.5, v[210:211] op_sel_hi:[1,0,1]
	v_pk_fma_f32 v[26:27], v[26:27], 0.5, v[212:213] op_sel_hi:[1,0,1]
	s_mov_b32 s100, 0x80000
	s_mov_b32 s101, 0
	v_lshl_add_u64 v[216:217], v[252:253], 0, s[100:101]
	global_store_dwordx4 v[216:217], v[60:63], off
	global_store_dwordx4 v[216:217], v[56:59], off offset:64
	global_store_dwordx4 v[216:217], v[48:51], off offset:512
	global_store_dwordx4 v[216:217], v[40:43], off offset:576
	s_mov_b32 s100, 0x90000
	s_mov_b32 s101, 0
	v_lshl_add_u64 v[218:219], v[252:253], 0, s[100:101]
	global_store_dwordx4 v[218:219], v[52:55], off
	global_store_dwordx4 v[218:219], v[44:47], off offset:64
	global_store_dwordx4 v[218:219], v[32:35], off offset:512
	global_store_dwordx4 v[218:219], v[24:27], off offset:576
	s_waitcnt vmcnt(16)
	v_pk_fma_f32 v[36:37], v[36:37], 0.5, v[220:221] op_sel_hi:[1,0,1]
	v_pk_fma_f32 v[38:39], v[38:39], 0.5, v[222:223] op_sel_hi:[1,0,1]
	v_pk_fma_f32 v[28:29], v[28:29], 0.5, v[224:225] op_sel_hi:[1,0,1]
	v_pk_fma_f32 v[30:31], v[30:31], 0.5, v[226:227] op_sel_hi:[1,0,1]
	v_pk_fma_f32 v[16:17], v[16:17], 0.5, v[228:229] op_sel_hi:[1,0,1]
	v_pk_fma_f32 v[18:19], v[18:19], 0.5, v[230:231] op_sel_hi:[1,0,1]
	v_pk_fma_f32 v[8:9], v[8:9], 0.5, v[232:233] op_sel_hi:[1,0,1]
	v_pk_fma_f32 v[10:11], v[10:11], 0.5, v[234:235] op_sel_hi:[1,0,1]
	v_pk_fma_f32 v[20:21], v[20:21], 0.5, v[236:237] op_sel_hi:[1,0,1]
	v_pk_fma_f32 v[22:23], v[22:23], 0.5, v[238:239] op_sel_hi:[1,0,1]
	v_pk_fma_f32 v[12:13], v[12:13], 0.5, v[240:241] op_sel_hi:[1,0,1]
	v_pk_fma_f32 v[14:15], v[14:15], 0.5, v[242:243] op_sel_hi:[1,0,1]
	v_pk_fma_f32 v[4:5], v[4:5], 0.5, v[244:245] op_sel_hi:[1,0,1]
	v_pk_fma_f32 v[6:7], v[6:7], 0.5, v[246:247] op_sel_hi:[1,0,1]
	v_pk_fma_f32 v[0:1], v[0:1], 0.5, v[248:249] op_sel_hi:[1,0,1]
	v_pk_fma_f32 v[2:3], v[2:3], 0.5, v[250:251] op_sel_hi:[1,0,1]
	s_mov_b32 s100, 0xa0000
	s_mov_b32 s101, 0
	v_lshl_add_u64 v[216:217], v[252:253], 0, s[100:101]
	global_store_dwordx4 v[216:217], v[36:39], off
	global_store_dwordx4 v[216:217], v[28:31], off offset:64
	global_store_dwordx4 v[216:217], v[16:19], off offset:512
	global_store_dwordx4 v[216:217], v[8:11], off offset:576
	s_mov_b32 s100, 0xb0000
	s_mov_b32 s101, 0
	v_lshl_add_u64 v[218:219], v[252:253], 0, s[100:101]
	global_store_dwordx4 v[218:219], v[20:23], off
	global_store_dwordx4 v[218:219], v[12:15], off offset:64
	global_store_dwordx4 v[218:219], v[4:7], off offset:512
	global_store_dwordx4 v[218:219], v[0:3], off offset:576
	s_and_b64 vcc, exec, s[4:5]
	s_mov_b32 s59, s57
	s_mov_b32 s16, s58
	s_mov_b64 s[20:21], s[8:9]
	s_mov_b64 s[18:19], s[6:7]
	s_cbranch_vccz .LBB0_3202
	s_waitcnt vmcnt(0)
	s_cmpk_gt_u32 s26, 0xff
	s_cbranch_scc1 .LBB0_3217
	s_barrier
